# GEMM epilogues (out, gdn-in, diff-in) store 16 B per lane via lane exchange; attention item epilogue loads batched; elem parameter rows fetched per part in one round trip
# speedup vs baseline: 1.0386x; 1.0214x over previous
.LBB0_84:
	s_add_i32 s54, s96, 0xffff8000
	s_lshr_b32 s54, s54, 4
	s_add_i32 s54, s54, 4
	s_ashr_i32 s55, s96, 13
	s_cmp_lt_i32 s96, 0x8000
	s_cselect_b32 s66, s55, s54
	s_and_b64 vcc, exec, s[88:89]
	v_lshlrev_b32_e32 v80, 2, v52
	v_lshlrev_b32_e32 v79, 2, v54
	v_lshlrev_b32_e32 v78, 2, v56
	s_cbranch_vccz .LBB0_90
	s_ashr_i32 s58, s66, 31
	s_add_u32 s54, s83, s66
	s_addc_u32 s55, s75, s58
	s_mulk_i32 s55, 0x3000
	s_mul_hi_u32 s59, s54, 0x3000
	s_add_i32 s59, s59, s55
	s_mulk_i32 s54, 0x3000
	s_add_u32 s54, s68, s54
	s_addc_u32 s55, s74, s59
	s_add_u32 s54, s54, 0x2000
	s_addc_u32 s55, s55, 0
	global_load_dwordx4 v[100:103], v[62:63], off
	global_load_dwordx4 v[104:107], v172, s[54:55]
	global_load_dwordx4 v[108:111], v[62:63], off offset:1024
	global_load_dwordx4 v[112:115], v80, s[54:55]
	global_load_dwordx4 v[116:119], v[62:63], off offset:2048
	global_load_dwordx4 v[120:123], v79, s[54:55]
	global_load_dwordx4 v[124:127], v[62:63], off offset:3072
	global_load_dwordx4 v[128:131], v78, s[54:55]
	v_and_b32_e32 v49, 0xffff0000, v38
	v_and_b32_e32 v51, 0xffff0000, v36
	v_lshlrev_b32_e32 v48, 16, v38
	v_lshlrev_b32_e32 v50, 16, v36
	v_lshlrev_b32_e32 v85, 16, v34
	v_and_b32_e32 v87, 0xffff0000, v34
	v_and_b32_e32 v86, 0xffff0000, v32
	v_lshlrev_b32_e32 v89, 16, v35
	v_and_b32_e32 v91, 0xffff0000, v35
	v_mul_f32_e32 v34, v49, v49
	v_mul_f32_e32 v35, v51, v51
	v_lshlrev_b32_e32 v38, 16, v39
	v_lshlrev_b32_e32 v82, 16, v37
	v_lshlrev_b32_e32 v84, 16, v32
	v_lshlrev_b32_e32 v88, 16, v33
	v_and_b32_e32 v90, 0xffff0000, v33
	v_pk_mul_f32 v[32:33], v[86:87], v[86:87]
	v_fmac_f32_e32 v34, v48, v48
	v_fmac_f32_e32 v35, v50, v50
	v_and_b32_e32 v39, 0xffff0000, v39
	v_and_b32_e32 v83, 0xffff0000, v37
	v_pk_fma_f32 v[32:33], v[84:85], v[84:85], v[32:33]
	v_fmac_f32_e32 v34, v38, v38
	v_fmac_f32_e32 v35, v82, v82
	v_pk_fma_f32 v[32:33], v[88:89], v[88:89], v[32:33]
	v_fmac_f32_e32 v34, v39, v39
	v_fmac_f32_e32 v35, v83, v83
	v_pk_fma_f32 v[32:33], v[90:91], v[90:91], v[32:33]
	v_add_f32_e32 v34, v34, v35
	v_add_f32_e32 v32, v34, v32
	v_add_f32_e32 v32, v32, v33
	v_lshl_add_u64 v[94:95], s[48:49], 0, v[66:67]
	s_nop 0
	v_add_f32_dpp v32, v32, v32 row_ror:8 row_mask:0xf bank_mask:0xf bound_ctrl:1
	s_nop 1
	v_add_f32_dpp v32, v32, v32 row_ror:4 row_mask:0xf bank_mask:0xf bound_ctrl:1
	s_nop 1
	v_add_f32_dpp v32, v32, v32 row_ror:2 row_mask:0xf bank_mask:0xf bound_ctrl:1
	s_nop 1
	v_add_f32_dpp v32, v32, v32 row_ror:1 row_mask:0xf bank_mask:0xf bound_ctrl:1
	ds_bpermute_b32 v33, v55, v32
	s_waitcnt lgkmcnt(0)
	v_add_f32_e32 v32, v32, v33
	ds_bpermute_b32 v33, v57, v32
	s_waitcnt lgkmcnt(0)
	v_add_f32_e32 v32, v32, v33
	v_fmamk_f32 v32, v32, 0x3a800000, v216
	v_rsq_f32_e32 v92, v32
	s_nop 0
	v_pk_mul_f32 v[32:33], v[38:39], v[92:93] op_sel_hi:[1, 0]
	v_pk_mul_f32 v[34:35], v[48:49], v[92:93] op_sel_hi:[1, 0]
	v_mov_b32_e32 v48, v88
	v_mov_b32_e32 v49, v90
	v_pk_mul_f32 v[48:49], v[48:49], v[92:93] op_sel_hi:[1, 0]
	v_mov_b32_e32 v90, v89
	s_waitcnt vmcnt(0)
	v_pk_mul_f32 v[36:37], v[100:101], v[34:35]
	v_pk_mul_f32 v[32:33], v[102:103], v[32:33]
	v_pk_fma_f32 v[34:35], v[106:107], v[32:33], v[30:31]
	v_pk_fma_f32 v[32:33], v[104:105], v[36:37], v[28:29]
	global_store_dwordx4 v[94:95], v[32:35], off
	v_pk_mul_f32 v[44:45], v[82:83], v[92:93] op_sel_hi:[1, 0]
	v_pk_mul_f32 v[46:47], v[50:51], v[92:93] op_sel_hi:[1, 0]
	v_mov_b32_e32 v50, v84
	v_mov_b32_e32 v51, v86
	v_pk_mul_f32 v[50:51], v[50:51], v[92:93] op_sel_hi:[1, 0]
	v_mov_b32_e32 v86, v85
	v_pk_mul_f32 v[84:85], v[86:87], v[92:93] op_sel_hi:[1, 0]
	v_pk_mul_f32 v[82:83], v[90:91], v[92:93] op_sel_hi:[1, 0]
	v_pk_mul_f32 v[36:37], v[108:109], v[46:47]
	v_pk_mul_f32 v[38:39], v[110:111], v[44:45]
	v_pk_fma_f32 v[36:37], v[112:113], v[36:37], v[24:25]
	v_pk_fma_f32 v[38:39], v[114:115], v[38:39], v[26:27]
	global_store_dwordx4 v[94:95], v[36:39], off offset:1024
	v_pk_mul_f32 v[40:41], v[116:117], v[50:51]
	v_pk_mul_f32 v[42:43], v[118:119], v[48:49]
	v_pk_fma_f32 v[40:41], v[120:121], v[40:41], v[20:21]
	v_pk_fma_f32 v[42:43], v[122:123], v[42:43], v[22:23]
	global_store_dwordx4 v[94:95], v[40:43], off offset:2048
	s_mov_b32 s54, s96
	s_ashr_i32 s55, s96, 31
	v_pk_mul_f32 v[44:45], v[84:85], v[124:125]
	v_pk_mul_f32 v[46:47], v[82:83], v[126:127]
	v_pk_fma_f32 v[48:49], v[128:129], v[44:45], v[16:17]
	v_pk_fma_f32 v[50:51], v[130:131], v[46:47], v[18:19]
	global_store_dwordx4 v[94:95], v[48:51], off offset:3072
	v_mov_b64_e32 v[44:45], v[48:49]
	v_mov_b64_e32 v[46:47], v[50:51]
	s_cbranch_execnz .LBB0_87

.LBB0_87:
	s_add_u32 s59, s66, s82
	s_addc_u32 s58, s58, 0
	s_mulk_i32 s58, 0x3000
	s_mul_hi_u32 s62, s59, 0x3000
	s_add_i32 s58, s62, s58
	s_mulk_i32 s59, 0x3000
	s_add_u32 s62, s68, s59
	s_addc_u32 s63, s74, s58
	s_add_u32 s96, s62, 0x1000
	s_addc_u32 s97, s63, 0
	global_load_dwordx4 v[132:135], v[60:61], off
	global_load_dwordx4 v[136:139], v172, s[96:97]
	global_load_dwordx4 v[140:143], v172, s[62:63]
	global_load_dwordx4 v[144:147], v[60:61], off offset:1024
	global_load_dwordx4 v[148:151], v80, s[96:97]
	global_load_dwordx4 v[152:155], v172, s[62:63] offset:1024
	global_load_dwordx4 v[156:159], v[60:61], off offset:2048
	global_load_dwordx4 v[160:163], v79, s[96:97]
	global_load_dwordx4 v[164:167], v172, s[62:63] offset:2048
	global_load_dwordx4 v[168:171], v[60:61], off offset:3072
	global_load_dwordx4 v[96:99], v78, s[96:97]
	global_load_dwordx4 v[100:103], v172, s[62:63] offset:3072
	v_mul_f32_e32 v81, v33, v33
	v_mul_f32_e32 v84, v37, v37
	v_pk_mul_f32 v[28:29], v[50:51], v[50:51]
	v_pk_mul_f32 v[48:49], v[48:49], v[48:49]
	v_pk_mul_f32 v[50:51], v[40:41], v[40:41]
	v_pk_mul_f32 v[30:31], v[42:43], v[42:43]
	v_fmac_f32_e32 v81, v32, v32
	v_fmac_f32_e32 v84, v36, v36
	v_mov_b32_e32 v82, v48
	v_mov_b32_e32 v83, v50
	v_mov_b32_e32 v50, v49
	v_mov_b32_e32 v48, v28
	v_mov_b32_e32 v49, v30
	v_mov_b32_e32 v30, v29
	v_fmac_f32_e32 v81, v34, v34
	v_fmac_f32_e32 v84, v38, v38
	v_pk_add_f32 v[28:29], v[82:83], v[50:51]
	v_fmac_f32_e32 v81, v35, v35
	v_fmac_f32_e32 v84, v39, v39
	v_pk_add_f32 v[28:29], v[48:49], v[28:29]
	v_add_f32_e32 v48, v81, v84
	v_pk_add_f32 v[28:29], v[30:31], v[28:29]
	s_lshl_b64 s[58:59], s[54:55], 11
	v_add_f32_e32 v29, v29, v48
	v_add_f32_e32 v28, v28, v29
	v_lshl_add_u64 v[50:51], v[64:65], 0, s[58:59]
	s_andn2_b64 vcc, exec, s[64:65]
	v_add_f32_dpp v28, v28, v28 row_ror:8 row_mask:0xf bank_mask:0xf bound_ctrl:1
	s_waitcnt vmcnt(0)
	v_pk_add_f32 v[20:21], v[136:137], 1.0 op_sel_hi:[1, 0]
	v_add_f32_dpp v28, v28, v28 row_ror:4 row_mask:0xf bank_mask:0xf bound_ctrl:1
	s_nop 1
	v_add_f32_dpp v28, v28, v28 row_ror:2 row_mask:0xf bank_mask:0xf bound_ctrl:1
	s_nop 1
	v_add_f32_dpp v28, v28, v28 row_ror:1 row_mask:0xf bank_mask:0xf bound_ctrl:1
	ds_bpermute_b32 v29, v55, v28
	s_waitcnt lgkmcnt(0)
	v_add_f32_e32 v28, v28, v29
	ds_bpermute_b32 v29, v57, v28
	s_waitcnt lgkmcnt(0)
	v_add_f32_e32 v28, v28, v29
	v_fmamk_f32 v28, v28, 0x3a800000, v216
	v_rsq_f32_e32 v48, v28
	s_nop 0
	v_pk_mul_f32 v[28:29], v[34:35], v[48:49] op_sel_hi:[1, 0]
	v_pk_mul_f32 v[30:31], v[32:33], v[48:49] op_sel_hi:[1, 0]
	v_pk_mul_f32 v[32:33], v[36:37], v[48:49] op_sel_hi:[1, 0]
	v_pk_mul_f32 v[30:31], v[132:133], v[30:31]
	v_pk_mul_f32 v[16:17], v[134:135], v[28:29]
	v_pk_add_f32 v[18:19], v[138:139], 1.0 op_sel_hi:[1, 0]
	v_pk_mul_f32 v[34:35], v[38:39], v[48:49] op_sel_hi:[1, 0]
	v_pk_fma_f32 v[16:17], v[18:19], v[16:17], v[142:143]
	v_pk_fma_f32 v[18:19], v[20:21], v[30:31], v[140:141]
	v_cvt_pk_bf16_f32 v21, v16, v17
	v_cvt_pk_bf16_f32 v20, v18, v19
	global_store_dwordx2 v[50:51], v[20:21], off
	s_nop 0
	v_pk_mul_f32 v[36:37], v[40:41], v[48:49] op_sel_hi:[1, 0]
	v_pk_mul_f32 v[38:39], v[42:43], v[48:49] op_sel_hi:[1, 0]
	v_pk_mul_f32 v[40:41], v[44:45], v[48:49] op_sel_hi:[1, 0]
	v_pk_mul_f32 v[42:43], v[46:47], v[48:49] op_sel_hi:[1, 0]
	v_pk_mul_f32 v[34:35], v[146:147], v[34:35]
	v_pk_mul_f32 v[20:21], v[144:145], v[32:33]
	v_pk_add_f32 v[26:27], v[150:151], 1.0 op_sel_hi:[1, 0]
	v_pk_add_f32 v[22:23], v[148:149], 1.0 op_sel_hi:[1, 0]
	v_pk_fma_f32 v[22:23], v[22:23], v[20:21], v[152:153]
	v_pk_fma_f32 v[20:21], v[26:27], v[34:35], v[154:155]
	v_cvt_pk_bf16_f32 v24, v22, v23
	v_cvt_pk_bf16_f32 v25, v20, v21
	global_store_dwordx2 v[50:51], v[24:25], off offset:512
	s_nop 0
	v_pk_mul_f32 v[26:27], v[158:159], v[38:39]
	v_pk_mul_f32 v[24:25], v[156:157], v[36:37]
	v_pk_add_f32 v[30:31], v[162:163], 1.0 op_sel_hi:[1, 0]
	v_pk_add_f32 v[28:29], v[160:161], 1.0 op_sel_hi:[1, 0]
	v_pk_fma_f32 v[26:27], v[30:31], v[26:27], v[166:167]
	v_pk_fma_f32 v[24:25], v[28:29], v[24:25], v[164:165]
	v_cvt_pk_bf16_f32 v29, v26, v27
	v_cvt_pk_bf16_f32 v28, v24, v25
	global_store_dwordx2 v[50:51], v[28:29], off offset:1024
	s_nop 0
	v_pk_mul_f32 v[42:43], v[42:43], v[170:171]
	v_pk_mul_f32 v[28:29], v[40:41], v[168:169]
	v_pk_add_f32 v[34:35], v[98:99], 1.0 op_sel_hi:[1, 0]
	v_pk_add_f32 v[30:31], v[96:97], 1.0 op_sel_hi:[1, 0]
	v_pk_fma_f32 v[30:31], v[30:31], v[28:29], v[100:101]
	v_pk_fma_f32 v[28:29], v[34:35], v[42:43], v[102:103]
	v_cvt_pk_bf16_f32 v32, v30, v31
	v_cvt_pk_bf16_f32 v33, v28, v29
	global_store_dwordx2 v[50:51], v[32:33], off offset:1536
	s_cbranch_vccnz .LBB0_75
	ds_read_b128 v[32:35], v53
	ds_read_b128 v[36:39], v53 offset:1024
	ds_read_b128 v[40:43], v53 offset:2048
	s_waitcnt lgkmcnt(2)
	v_mul_f32_e32 v33, v19, v33
	s_waitcnt lgkmcnt(1)
	v_mul_f32_e32 v37, v23, v37
	v_fmac_f32_e32 v33, v18, v32
	v_fmac_f32_e32 v37, v22, v36
	v_fmac_f32_e32 v33, v16, v34
	v_fmac_f32_e32 v33, v17, v35
	v_fmac_f32_e32 v37, v20, v38
	v_add_f32_e32 v32, 0, v33
	v_fmac_f32_e32 v37, v21, v39
	v_add_f32_e32 v36, v32, v37
	ds_read_b128 v[32:35], v53 offset:3072
	s_waitcnt lgkmcnt(1)
	v_mul_f32_e32 v37, v25, v41
	v_fmac_f32_e32 v37, v24, v40
	v_fmac_f32_e32 v37, v26, v42
	v_fmac_f32_e32 v37, v27, v43
	s_waitcnt lgkmcnt(0)
	v_mul_f32_e32 v33, v31, v33
	v_fmac_f32_e32 v33, v30, v32
	v_fmac_f32_e32 v33, v28, v34
	v_add_f32_e32 v36, v36, v37
	v_fmac_f32_e32 v33, v29, v35
	v_add_f32_e32 v32, v36, v33
	s_nop 1
	v_add_f32_dpp v32, v32, v32 row_ror:8 row_mask:0xf bank_mask:0xf bound_ctrl:1
	s_nop 1
	v_add_f32_dpp v36, v32, v32 row_ror:4 row_mask:0xf bank_mask:0xf bound_ctrl:1
	ds_read_b128 v[32:35], v53 offset:4096
	s_nop 0
	v_add_f32_dpp v36, v36, v36 row_ror:2 row_mask:0xf bank_mask:0xf bound_ctrl:1
	s_nop 1
	v_add_f32_dpp v36, v36, v36 row_ror:1 row_mask:0xf bank_mask:0xf bound_ctrl:1
	v_cndmask_b32_e64 v40, 0, v36, s[8:9]
	ds_read_b128 v[36:39], v53 offset:5120
	s_waitcnt lgkmcnt(1)
	v_mul_f32_e32 v33, v19, v33
	v_fmac_f32_e32 v33, v18, v32
	v_fmac_f32_e32 v33, v16, v34
	v_fmac_f32_e32 v33, v17, v35
	v_add_f32_e32 v41, 0, v33
	s_waitcnt lgkmcnt(0)
	v_mul_f32_e32 v37, v23, v37
	ds_read_b128 v[32:35], v53 offset:6144
	v_fmac_f32_e32 v37, v22, v36
	v_fmac_f32_e32 v37, v20, v38
	v_fmac_f32_e32 v37, v21, v39
	v_add_f32_e32 v41, v41, v37
	ds_read_b128 v[36:39], v53 offset:7168
	s_waitcnt lgkmcnt(1)
	v_mul_f32_e32 v33, v25, v33
	v_fmac_f32_e32 v33, v24, v32
	v_fmac_f32_e32 v33, v26, v34
	v_fmac_f32_e32 v33, v27, v35
	v_add_f32_e32 v32, v41, v33
	s_waitcnt lgkmcnt(0)
	v_mul_f32_e32 v33, v31, v37
	v_fmac_f32_e32 v33, v30, v36
	v_fmac_f32_e32 v33, v28, v38
	v_fmac_f32_e32 v33, v29, v39
	v_add_f32_e32 v32, v32, v33
	s_nop 1
	v_add_f32_dpp v32, v32, v32 row_ror:8 row_mask:0xf bank_mask:0xf bound_ctrl:1
	s_nop 1
	v_add_f32_dpp v36, v32, v32 row_ror:4 row_mask:0xf bank_mask:0xf bound_ctrl:1
	ds_read_b128 v[32:35], v53 offset:8192
	s_nop 0
	v_add_f32_dpp v36, v36, v36 row_ror:2 row_mask:0xf bank_mask:0xf bound_ctrl:1
	s_nop 1
	v_add_f32_dpp v36, v36, v36 row_ror:1 row_mask:0xf bank_mask:0xf bound_ctrl:1
	v_cndmask_b32_e64 v40, v40, v36, s[10:11]
	ds_read_b128 v[36:39], v53 offset:9216
	s_waitcnt lgkmcnt(1)
	v_mul_f32_e32 v33, v19, v33
	v_fmac_f32_e32 v33, v18, v32
	v_fmac_f32_e32 v33, v16, v34
	v_fmac_f32_e32 v33, v17, v35
	v_add_f32_e32 v41, 0, v33
	s_waitcnt lgkmcnt(0)
	v_mul_f32_e32 v37, v23, v37
	ds_read_b128 v[32:35], v53 offset:10240
	v_fmac_f32_e32 v37, v22, v36
	v_fmac_f32_e32 v37, v20, v38
	v_fmac_f32_e32 v37, v21, v39
	v_add_f32_e32 v41, v41, v37
	ds_read_b128 v[36:39], v53 offset:11264
	s_waitcnt lgkmcnt(1)
	v_mul_f32_e32 v33, v25, v33
	v_fmac_f32_e32 v33, v24, v32
	v_fmac_f32_e32 v33, v26, v34
	v_fmac_f32_e32 v33, v27, v35
	v_add_f32_e32 v32, v41, v33
	s_waitcnt lgkmcnt(0)
	v_mul_f32_e32 v33, v31, v37
	v_fmac_f32_e32 v33, v30, v36
	v_fmac_f32_e32 v33, v28, v38
	v_fmac_f32_e32 v33, v29, v39
	v_add_f32_e32 v32, v32, v33
	s_nop 1
	v_add_f32_dpp v32, v32, v32 row_ror:8 row_mask:0xf bank_mask:0xf bound_ctrl:1
	s_nop 1
	v_add_f32_dpp v36, v32, v32 row_ror:4 row_mask:0xf bank_mask:0xf bound_ctrl:1
	ds_read_b128 v[32:35], v53 offset:12288
	s_nop 0
	v_add_f32_dpp v36, v36, v36 row_ror:2 row_mask:0xf bank_mask:0xf bound_ctrl:1
	s_nop 1
	v_add_f32_dpp v36, v36, v36 row_ror:1 row_mask:0xf bank_mask:0xf bound_ctrl:1
	v_cndmask_b32_e64 v40, v40, v36, s[12:13]
	ds_read_b128 v[36:39], v53 offset:13312
	s_waitcnt lgkmcnt(1)
	v_mul_f32_e32 v33, v19, v33
	v_fmac_f32_e32 v33, v18, v32
	v_fmac_f32_e32 v33, v16, v34
	v_fmac_f32_e32 v33, v17, v35
	v_add_f32_e32 v41, 0, v33
	s_waitcnt lgkmcnt(0)
	v_mul_f32_e32 v37, v23, v37
	ds_read_b128 v[32:35], v53 offset:14336
	v_fmac_f32_e32 v37, v22, v36
	v_fmac_f32_e32 v37, v20, v38
	v_fmac_f32_e32 v37, v21, v39
	v_add_f32_e32 v41, v41, v37
	ds_read_b128 v[36:39], v53 offset:15360
	s_waitcnt lgkmcnt(1)
	v_mul_f32_e32 v33, v25, v33
	v_fmac_f32_e32 v33, v24, v32
	v_fmac_f32_e32 v33, v26, v34
	v_fmac_f32_e32 v33, v27, v35
	v_add_f32_e32 v32, v41, v33
	s_waitcnt lgkmcnt(0)
	v_mul_f32_e32 v33, v31, v37
	v_fmac_f32_e32 v33, v30, v36
	v_fmac_f32_e32 v33, v28, v38
	v_fmac_f32_e32 v33, v29, v39
	v_add_f32_e32 v32, v32, v33
	s_nop 1
	v_add_f32_dpp v32, v32, v32 row_ror:8 row_mask:0xf bank_mask:0xf bound_ctrl:1
	s_nop 1
	v_add_f32_dpp v36, v32, v32 row_ror:4 row_mask:0xf bank_mask:0xf bound_ctrl:1
	ds_read_b128 v[32:35], v53 offset:16384
	s_nop 0
	v_add_f32_dpp v36, v36, v36 row_ror:2 row_mask:0xf bank_mask:0xf bound_ctrl:1
	s_nop 1
	v_add_f32_dpp v36, v36, v36 row_ror:1 row_mask:0xf bank_mask:0xf bound_ctrl:1
	v_cndmask_b32_e64 v40, v40, v36, s[14:15]
	ds_read_b128 v[36:39], v53 offset:17408
	s_waitcnt lgkmcnt(1)
	v_mul_f32_e32 v33, v19, v33
	v_fmac_f32_e32 v33, v18, v32
	v_fmac_f32_e32 v33, v16, v34
	v_fmac_f32_e32 v33, v17, v35
	v_add_f32_e32 v41, 0, v33
	s_waitcnt lgkmcnt(0)
	v_mul_f32_e32 v37, v23, v37
	ds_read_b128 v[32:35], v53 offset:18432
	v_fmac_f32_e32 v37, v22, v36
	v_fmac_f32_e32 v37, v20, v38
	v_fmac_f32_e32 v37, v21, v39
	v_add_f32_e32 v41, v41, v37
	ds_read_b128 v[36:39], v53 offset:19456
	s_waitcnt lgkmcnt(1)
	v_mul_f32_e32 v33, v25, v33
	v_fmac_f32_e32 v33, v24, v32
	v_fmac_f32_e32 v33, v26, v34
	v_fmac_f32_e32 v33, v27, v35
	v_add_f32_e32 v32, v41, v33
	s_waitcnt lgkmcnt(0)
	v_mul_f32_e32 v33, v31, v37
	v_fmac_f32_e32 v33, v30, v36
	v_fmac_f32_e32 v33, v28, v38
	v_fmac_f32_e32 v33, v29, v39
	v_add_f32_e32 v32, v32, v33
	s_nop 1
	v_add_f32_dpp v32, v32, v32 row_ror:8 row_mask:0xf bank_mask:0xf bound_ctrl:1
	s_nop 1
	v_add_f32_dpp v36, v32, v32 row_ror:4 row_mask:0xf bank_mask:0xf bound_ctrl:1
	ds_read_b128 v[32:35], v53 offset:20480
	s_nop 0
	v_add_f32_dpp v36, v36, v36 row_ror:2 row_mask:0xf bank_mask:0xf bound_ctrl:1
	s_nop 1
	v_add_f32_dpp v36, v36, v36 row_ror:1 row_mask:0xf bank_mask:0xf bound_ctrl:1
	v_cndmask_b32_e64 v40, v40, v36, s[16:17]
	ds_read_b128 v[36:39], v53 offset:21504
	s_waitcnt lgkmcnt(1)
	v_mul_f32_e32 v33, v19, v33
	v_fmac_f32_e32 v33, v18, v32
	v_fmac_f32_e32 v33, v16, v34
	v_fmac_f32_e32 v33, v17, v35
	v_add_f32_e32 v41, 0, v33
	s_waitcnt lgkmcnt(0)
	v_mul_f32_e32 v37, v23, v37
	ds_read_b128 v[32:35], v53 offset:22528
	v_fmac_f32_e32 v37, v22, v36
	v_fmac_f32_e32 v37, v20, v38
	v_fmac_f32_e32 v37, v21, v39
	v_add_f32_e32 v41, v41, v37
	ds_read_b128 v[36:39], v53 offset:23552
	s_waitcnt lgkmcnt(1)
	v_mul_f32_e32 v33, v25, v33
	v_fmac_f32_e32 v33, v24, v32
	v_fmac_f32_e32 v33, v26, v34
	v_fmac_f32_e32 v33, v27, v35
	v_add_f32_e32 v32, v41, v33
	s_waitcnt lgkmcnt(0)
	v_mul_f32_e32 v33, v31, v37
	v_fmac_f32_e32 v33, v30, v36
	v_fmac_f32_e32 v33, v28, v38
	v_fmac_f32_e32 v33, v29, v39
	v_add_f32_e32 v32, v32, v33
	s_nop 1
	v_add_f32_dpp v32, v32, v32 row_ror:8 row_mask:0xf bank_mask:0xf bound_ctrl:1
	s_nop 1
	v_add_f32_dpp v36, v32, v32 row_ror:4 row_mask:0xf bank_mask:0xf bound_ctrl:1
	ds_read_b128 v[32:35], v53 offset:24576
	s_nop 0
	v_add_f32_dpp v36, v36, v36 row_ror:2 row_mask:0xf bank_mask:0xf bound_ctrl:1
	s_nop 1
	v_add_f32_dpp v36, v36, v36 row_ror:1 row_mask:0xf bank_mask:0xf bound_ctrl:1
	v_cndmask_b32_e64 v40, v40, v36, s[18:19]
	ds_read_b128 v[36:39], v53 offset:25600
	s_waitcnt lgkmcnt(1)
	v_mul_f32_e32 v33, v19, v33
	v_fmac_f32_e32 v33, v18, v32
	v_fmac_f32_e32 v33, v16, v34
	v_fmac_f32_e32 v33, v17, v35
	v_add_f32_e32 v41, 0, v33
	s_waitcnt lgkmcnt(0)
	v_mul_f32_e32 v37, v23, v37
	ds_read_b128 v[32:35], v53 offset:26624
	v_fmac_f32_e32 v37, v22, v36
	v_fmac_f32_e32 v37, v20, v38
	v_fmac_f32_e32 v37, v21, v39
	v_add_f32_e32 v41, v41, v37
	ds_read_b128 v[36:39], v53 offset:27648
	s_waitcnt lgkmcnt(1)
	v_mul_f32_e32 v33, v25, v33
	v_fmac_f32_e32 v33, v24, v32
	v_fmac_f32_e32 v33, v26, v34
	v_fmac_f32_e32 v33, v27, v35
	v_add_f32_e32 v32, v41, v33
	s_waitcnt lgkmcnt(0)
	v_mul_f32_e32 v33, v31, v37
	v_fmac_f32_e32 v33, v30, v36
	v_fmac_f32_e32 v33, v28, v38
	v_fmac_f32_e32 v33, v29, v39
	v_add_f32_e32 v32, v32, v33
	s_nop 1
	v_add_f32_dpp v32, v32, v32 row_ror:8 row_mask:0xf bank_mask:0xf bound_ctrl:1
	s_nop 1
	v_add_f32_dpp v36, v32, v32 row_ror:4 row_mask:0xf bank_mask:0xf bound_ctrl:1
	ds_read_b128 v[32:35], v53 offset:28672
	s_nop 0
	v_add_f32_dpp v36, v36, v36 row_ror:2 row_mask:0xf bank_mask:0xf bound_ctrl:1
	s_nop 1
	v_add_f32_dpp v36, v36, v36 row_ror:1 row_mask:0xf bank_mask:0xf bound_ctrl:1
	v_cndmask_b32_e64 v40, v40, v36, s[20:21]
	ds_read_b128 v[36:39], v53 offset:29696
	s_waitcnt lgkmcnt(1)
	v_mul_f32_e32 v33, v19, v33
	v_fmac_f32_e32 v33, v18, v32
	v_fmac_f32_e32 v33, v16, v34
	v_fmac_f32_e32 v33, v17, v35
	v_add_f32_e32 v41, 0, v33
	s_waitcnt lgkmcnt(0)
	v_mul_f32_e32 v37, v23, v37
	ds_read_b128 v[32:35], v53 offset:30720
	v_fmac_f32_e32 v37, v22, v36
	v_fmac_f32_e32 v37, v20, v38
	v_fmac_f32_e32 v37, v21, v39
	v_add_f32_e32 v41, v41, v37
	ds_read_b128 v[36:39], v53 offset:31744
	s_waitcnt lgkmcnt(1)
	v_mul_f32_e32 v33, v25, v33
	v_fmac_f32_e32 v33, v24, v32
	v_fmac_f32_e32 v33, v26, v34
	v_fmac_f32_e32 v33, v27, v35
	v_add_f32_e32 v32, v41, v33
	s_waitcnt lgkmcnt(0)
	v_mul_f32_e32 v33, v31, v37
	v_fmac_f32_e32 v33, v30, v36
	v_fmac_f32_e32 v33, v28, v38
	v_fmac_f32_e32 v33, v29, v39
	v_add_f32_e32 v32, v32, v33
	s_nop 1
	v_add_f32_dpp v32, v32, v32 row_ror:8 row_mask:0xf bank_mask:0xf bound_ctrl:1
	s_nop 1
	v_add_f32_dpp v36, v32, v32 row_ror:4 row_mask:0xf bank_mask:0xf bound_ctrl:1
	ds_read_b128 v[32:35], v53 offset:32768
	s_nop 0
	v_add_f32_dpp v36, v36, v36 row_ror:2 row_mask:0xf bank_mask:0xf bound_ctrl:1
	s_nop 1
	v_add_f32_dpp v36, v36, v36 row_ror:1 row_mask:0xf bank_mask:0xf bound_ctrl:1
	v_cndmask_b32_e64 v40, v40, v36, s[22:23]
	ds_read_b128 v[36:39], v53 offset:33792
	s_waitcnt lgkmcnt(1)
	v_mul_f32_e32 v33, v19, v33
	v_fmac_f32_e32 v33, v18, v32
	v_fmac_f32_e32 v33, v16, v34
	v_fmac_f32_e32 v33, v17, v35
	v_add_f32_e32 v41, 0, v33
	s_waitcnt lgkmcnt(0)
	v_mul_f32_e32 v37, v23, v37
	ds_read_b128 v[32:35], v53 offset:34816
	v_fmac_f32_e32 v37, v22, v36
	v_fmac_f32_e32 v37, v20, v38
	v_fmac_f32_e32 v37, v21, v39
	v_add_f32_e32 v41, v41, v37
	ds_read_b128 v[36:39], v53 offset:35840
	s_waitcnt lgkmcnt(1)
	v_mul_f32_e32 v33, v25, v33
	v_fmac_f32_e32 v33, v24, v32
	v_fmac_f32_e32 v33, v26, v34
	v_fmac_f32_e32 v33, v27, v35
	v_add_f32_e32 v32, v41, v33
	s_waitcnt lgkmcnt(0)
	v_mul_f32_e32 v33, v31, v37
	v_fmac_f32_e32 v33, v30, v36
	v_fmac_f32_e32 v33, v28, v38
	v_fmac_f32_e32 v33, v29, v39
	v_add_f32_e32 v32, v32, v33
	s_nop 1
	v_add_f32_dpp v32, v32, v32 row_ror:8 row_mask:0xf bank_mask:0xf bound_ctrl:1
	s_nop 1
	v_add_f32_dpp v36, v32, v32 row_ror:4 row_mask:0xf bank_mask:0xf bound_ctrl:1
	ds_read_b128 v[32:35], v53 offset:36864
	s_nop 0
	v_add_f32_dpp v36, v36, v36 row_ror:2 row_mask:0xf bank_mask:0xf bound_ctrl:1
	s_nop 1
	v_add_f32_dpp v36, v36, v36 row_ror:1 row_mask:0xf bank_mask:0xf bound_ctrl:1
	v_cndmask_b32_e64 v40, v40, v36, s[24:25]
	ds_read_b128 v[36:39], v53 offset:37888
	s_waitcnt lgkmcnt(1)
	v_mul_f32_e32 v33, v19, v33
	v_fmac_f32_e32 v33, v18, v32
	v_fmac_f32_e32 v33, v16, v34
	v_fmac_f32_e32 v33, v17, v35
	v_add_f32_e32 v41, 0, v33
	s_waitcnt lgkmcnt(0)
	v_mul_f32_e32 v37, v23, v37
	ds_read_b128 v[32:35], v53 offset:38912
	v_fmac_f32_e32 v37, v22, v36
	v_fmac_f32_e32 v37, v20, v38
	v_fmac_f32_e32 v37, v21, v39
	v_add_f32_e32 v41, v41, v37
	ds_read_b128 v[36:39], v53 offset:39936
	s_waitcnt lgkmcnt(1)
	v_mul_f32_e32 v33, v25, v33
	v_fmac_f32_e32 v33, v24, v32
	v_fmac_f32_e32 v33, v26, v34
	v_fmac_f32_e32 v33, v27, v35
	v_add_f32_e32 v32, v41, v33
	s_waitcnt lgkmcnt(0)
	v_mul_f32_e32 v33, v31, v37
	v_fmac_f32_e32 v33, v30, v36
	v_fmac_f32_e32 v33, v28, v38
	v_fmac_f32_e32 v33, v29, v39
	v_add_f32_e32 v32, v32, v33
	s_nop 1
	v_add_f32_dpp v32, v32, v32 row_ror:8 row_mask:0xf bank_mask:0xf bound_ctrl:1
	s_nop 1
	v_add_f32_dpp v36, v32, v32 row_ror:4 row_mask:0xf bank_mask:0xf bound_ctrl:1
	ds_read_b128 v[32:35], v53 offset:40960
	s_nop 0
	v_add_f32_dpp v36, v36, v36 row_ror:2 row_mask:0xf bank_mask:0xf bound_ctrl:1
	s_nop 1
	v_add_f32_dpp v36, v36, v36 row_ror:1 row_mask:0xf bank_mask:0xf bound_ctrl:1
	v_cndmask_b32_e64 v40, v40, v36, s[26:27]
	ds_read_b128 v[36:39], v53 offset:41984
	s_waitcnt lgkmcnt(1)
	v_mul_f32_e32 v33, v19, v33
	v_fmac_f32_e32 v33, v18, v32
	v_fmac_f32_e32 v33, v16, v34
	v_fmac_f32_e32 v33, v17, v35
	v_add_f32_e32 v41, 0, v33
	s_waitcnt lgkmcnt(0)
	v_mul_f32_e32 v37, v23, v37
	ds_read_b128 v[32:35], v53 offset:43008
	v_fmac_f32_e32 v37, v22, v36
	v_fmac_f32_e32 v37, v20, v38
	v_fmac_f32_e32 v37, v21, v39
	v_add_f32_e32 v41, v41, v37
	ds_read_b128 v[36:39], v53 offset:44032
	s_waitcnt lgkmcnt(1)
	v_mul_f32_e32 v33, v25, v33
	v_fmac_f32_e32 v33, v24, v32
	v_fmac_f32_e32 v33, v26, v34
	v_fmac_f32_e32 v33, v27, v35
	v_add_f32_e32 v32, v41, v33
	s_waitcnt lgkmcnt(0)
	v_mul_f32_e32 v33, v31, v37
	v_fmac_f32_e32 v33, v30, v36
	v_fmac_f32_e32 v33, v28, v38
	v_fmac_f32_e32 v33, v29, v39
	v_add_f32_e32 v32, v32, v33
	s_nop 1
	v_add_f32_dpp v32, v32, v32 row_ror:8 row_mask:0xf bank_mask:0xf bound_ctrl:1
	s_nop 1
	v_add_f32_dpp v36, v32, v32 row_ror:4 row_mask:0xf bank_mask:0xf bound_ctrl:1
	ds_read_b128 v[32:35], v53 offset:45056
	s_nop 0
	v_add_f32_dpp v36, v36, v36 row_ror:2 row_mask:0xf bank_mask:0xf bound_ctrl:1
	s_nop 1
	v_add_f32_dpp v36, v36, v36 row_ror:1 row_mask:0xf bank_mask:0xf bound_ctrl:1
	v_cndmask_b32_e64 v40, v40, v36, s[28:29]
	ds_read_b128 v[36:39], v53 offset:46080
	s_waitcnt lgkmcnt(1)
	v_mul_f32_e32 v33, v19, v33
	v_fmac_f32_e32 v33, v18, v32
	v_fmac_f32_e32 v33, v16, v34
	v_fmac_f32_e32 v33, v17, v35
	v_add_f32_e32 v41, 0, v33
	s_waitcnt lgkmcnt(0)
	v_mul_f32_e32 v37, v23, v37
	ds_read_b128 v[32:35], v53 offset:47104
	v_fmac_f32_e32 v37, v22, v36
	v_fmac_f32_e32 v37, v20, v38
	v_fmac_f32_e32 v37, v21, v39
	v_add_f32_e32 v41, v41, v37
	ds_read_b128 v[36:39], v53 offset:48128
	s_waitcnt lgkmcnt(1)
	v_mul_f32_e32 v33, v25, v33
	v_fmac_f32_e32 v33, v24, v32
	v_fmac_f32_e32 v33, v26, v34
	v_fmac_f32_e32 v33, v27, v35
	v_add_f32_e32 v32, v41, v33
	s_waitcnt lgkmcnt(0)
	v_mul_f32_e32 v33, v31, v37
	v_fmac_f32_e32 v33, v30, v36
	v_fmac_f32_e32 v33, v28, v38
	v_fmac_f32_e32 v33, v29, v39
	v_add_f32_e32 v32, v32, v33
	s_nop 1
	v_add_f32_dpp v32, v32, v32 row_ror:8 row_mask:0xf bank_mask:0xf bound_ctrl:1
	s_nop 1
	v_add_f32_dpp v36, v32, v32 row_ror:4 row_mask:0xf bank_mask:0xf bound_ctrl:1
	ds_read_b128 v[32:35], v53 offset:49152
	s_nop 0
	v_add_f32_dpp v36, v36, v36 row_ror:2 row_mask:0xf bank_mask:0xf bound_ctrl:1
	s_nop 1
	v_add_f32_dpp v36, v36, v36 row_ror:1 row_mask:0xf bank_mask:0xf bound_ctrl:1
	v_cndmask_b32_e64 v40, v40, v36, s[30:31]
	ds_read_b128 v[36:39], v53 offset:50176
	s_waitcnt lgkmcnt(1)
	v_mul_f32_e32 v33, v19, v33
	v_fmac_f32_e32 v33, v18, v32
	v_fmac_f32_e32 v33, v16, v34
	v_fmac_f32_e32 v33, v17, v35
	v_add_f32_e32 v41, 0, v33
	s_waitcnt lgkmcnt(0)
	v_mul_f32_e32 v37, v23, v37
	ds_read_b128 v[32:35], v53 offset:51200
	v_fmac_f32_e32 v37, v22, v36
	v_fmac_f32_e32 v37, v20, v38
	v_fmac_f32_e32 v37, v21, v39
	v_add_f32_e32 v41, v41, v37
	ds_read_b128 v[36:39], v53 offset:52224
	s_waitcnt lgkmcnt(1)
	v_mul_f32_e32 v33, v25, v33
	v_fmac_f32_e32 v33, v24, v32
	v_fmac_f32_e32 v33, v26, v34
	v_fmac_f32_e32 v33, v27, v35
	v_add_f32_e32 v32, v41, v33
	s_waitcnt lgkmcnt(0)
	v_mul_f32_e32 v33, v31, v37
	v_fmac_f32_e32 v33, v30, v36
	v_fmac_f32_e32 v33, v28, v38
	v_fmac_f32_e32 v33, v29, v39
	v_add_f32_e32 v32, v32, v33
	s_nop 1
	v_add_f32_dpp v32, v32, v32 row_ror:8 row_mask:0xf bank_mask:0xf bound_ctrl:1
	s_nop 1
	v_add_f32_dpp v36, v32, v32 row_ror:4 row_mask:0xf bank_mask:0xf bound_ctrl:1
	ds_read_b128 v[32:35], v53 offset:53248
	s_nop 0
	v_add_f32_dpp v36, v36, v36 row_ror:2 row_mask:0xf bank_mask:0xf bound_ctrl:1
	s_nop 1
	v_add_f32_dpp v36, v36, v36 row_ror:1 row_mask:0xf bank_mask:0xf bound_ctrl:1
	v_cndmask_b32_e64 v40, v40, v36, s[34:35]
	ds_read_b128 v[36:39], v53 offset:54272
	s_waitcnt lgkmcnt(1)
	v_mul_f32_e32 v33, v19, v33
	v_fmac_f32_e32 v33, v18, v32
	v_fmac_f32_e32 v33, v16, v34
	v_fmac_f32_e32 v33, v17, v35
	v_add_f32_e32 v41, 0, v33
	s_waitcnt lgkmcnt(0)
	v_mul_f32_e32 v37, v23, v37
	ds_read_b128 v[32:35], v53 offset:55296
	v_fmac_f32_e32 v37, v22, v36
	v_fmac_f32_e32 v37, v20, v38
	v_fmac_f32_e32 v37, v21, v39
	v_add_f32_e32 v41, v41, v37
	ds_read_b128 v[36:39], v53 offset:56320
	s_waitcnt lgkmcnt(1)
	v_mul_f32_e32 v33, v25, v33
	v_fmac_f32_e32 v33, v24, v32
	v_fmac_f32_e32 v33, v26, v34
	v_fmac_f32_e32 v33, v27, v35
	v_add_f32_e32 v32, v41, v33
	s_waitcnt lgkmcnt(0)
	v_mul_f32_e32 v33, v31, v37
	v_fmac_f32_e32 v33, v30, v36
	v_fmac_f32_e32 v33, v28, v38
	v_fmac_f32_e32 v33, v29, v39
	v_add_f32_e32 v32, v32, v33
	s_nop 1
	v_add_f32_dpp v32, v32, v32 row_ror:8 row_mask:0xf bank_mask:0xf bound_ctrl:1
	s_nop 1
	v_add_f32_dpp v36, v32, v32 row_ror:4 row_mask:0xf bank_mask:0xf bound_ctrl:1
	ds_read_b128 v[32:35], v53 offset:57344
	s_nop 0
	v_add_f32_dpp v36, v36, v36 row_ror:2 row_mask:0xf bank_mask:0xf bound_ctrl:1
	s_nop 1
	v_add_f32_dpp v36, v36, v36 row_ror:1 row_mask:0xf bank_mask:0xf bound_ctrl:1
	v_cndmask_b32_e64 v40, v40, v36, s[36:37]
	ds_read_b128 v[36:39], v53 offset:58368
	s_waitcnt lgkmcnt(1)
	v_mul_f32_e32 v33, v19, v33
	v_fmac_f32_e32 v33, v18, v32
	v_fmac_f32_e32 v33, v16, v34
	v_fmac_f32_e32 v33, v17, v35
	v_add_f32_e32 v41, 0, v33
	s_waitcnt lgkmcnt(0)
	v_mul_f32_e32 v37, v23, v37
	ds_read_b128 v[32:35], v53 offset:59392
	v_fmac_f32_e32 v37, v22, v36
	v_fmac_f32_e32 v37, v20, v38
	v_fmac_f32_e32 v37, v21, v39
	v_add_f32_e32 v41, v41, v37
	ds_read_b128 v[36:39], v53 offset:60416
	s_waitcnt lgkmcnt(1)
	v_mul_f32_e32 v33, v25, v33
	v_fmac_f32_e32 v33, v24, v32
	v_fmac_f32_e32 v33, v26, v34
	v_fmac_f32_e32 v33, v27, v35
	v_add_f32_e32 v32, v41, v33
	s_waitcnt lgkmcnt(0)
	v_mul_f32_e32 v33, v31, v37
	v_fmac_f32_e32 v33, v30, v36
	v_fmac_f32_e32 v33, v28, v38
	v_fmac_f32_e32 v33, v29, v39
	v_add_f32_e32 v32, v32, v33
	s_nop 1
	v_add_f32_dpp v32, v32, v32 row_ror:8 row_mask:0xf bank_mask:0xf bound_ctrl:1
	s_nop 1
	v_add_f32_dpp v36, v32, v32 row_ror:4 row_mask:0xf bank_mask:0xf bound_ctrl:1
	ds_read_b128 v[32:35], v53 offset:61440
	s_nop 0
	v_add_f32_dpp v36, v36, v36 row_ror:2 row_mask:0xf bank_mask:0xf bound_ctrl:1
	s_nop 1
	v_add_f32_dpp v36, v36, v36 row_ror:1 row_mask:0xf bank_mask:0xf bound_ctrl:1
	v_cndmask_b32_e64 v40, v40, v36, s[38:39]
	ds_read_b128 v[36:39], v53 offset:62464
	s_waitcnt lgkmcnt(1)
	v_mul_f32_e32 v19, v19, v33
	v_fmac_f32_e32 v19, v18, v32
	v_fmac_f32_e32 v19, v16, v34
	v_fmac_f32_e32 v19, v17, v35
	v_add_f32_e32 v32, 0, v19
	s_waitcnt lgkmcnt(0)
	v_mul_f32_e32 v23, v23, v37
	ds_read_b128 v[16:19], v53 offset:63488
	v_fmac_f32_e32 v23, v22, v36
	v_fmac_f32_e32 v23, v20, v38
	v_fmac_f32_e32 v23, v21, v39
	v_add_f32_e32 v32, v32, v23
	ds_read_b128 v[20:23], v53 offset:64512
	s_waitcnt lgkmcnt(1)
	v_mul_f32_e32 v17, v25, v17
	v_fmac_f32_e32 v17, v24, v16
	v_fmac_f32_e32 v17, v26, v18
	v_fmac_f32_e32 v17, v27, v19
	v_add_f32_e32 v16, v32, v17
	s_waitcnt lgkmcnt(0)
	v_mul_f32_e32 v17, v31, v21
	v_fmac_f32_e32 v17, v30, v20
	v_fmac_f32_e32 v17, v28, v22
	v_fmac_f32_e32 v17, v29, v23
	v_add_f32_e32 v16, v16, v17
	s_nop 1
	v_add_f32_dpp v16, v16, v16 row_ror:8 row_mask:0xf bank_mask:0xf bound_ctrl:1
	s_nop 1
	v_add_f32_dpp v16, v16, v16 row_ror:4 row_mask:0xf bank_mask:0xf bound_ctrl:1
	s_nop 1
	v_add_f32_dpp v16, v16, v16 row_ror:2 row_mask:0xf bank_mask:0xf bound_ctrl:1
	s_nop 1
	v_add_f32_dpp v16, v16, v16 row_ror:1 row_mask:0xf bank_mask:0xf bound_ctrl:1
	v_cndmask_b32_e64 v16, v40, v16, s[40:41]
	ds_bpermute_b32 v17, v55, v16
	s_waitcnt lgkmcnt(0)
	v_add_f32_e32 v16, v16, v17
	ds_bpermute_b32 v17, v57, v16
	s_and_saveexec_b64 s[62:63], s[6:7]
	s_cbranch_execz .LBB0_74
	s_lshl_b64 s[54:55], s[54:55], 6
	s_waitcnt lgkmcnt(0)
	v_add_f32_e32 v18, v16, v17
	v_lshl_add_u64 v[16:17], v[58:59], 0, s[54:55]
	global_store_dword v[16:17], v18, off
	s_branch .LBB0_74

.LBB0_156:
	s_add_u32 s16, s14, 0xfffc0080
	s_addc_u32 s17, s15, -1
	s_add_i32 s39, 0, 0x10000
	v_add_u32_e32 v152, s39, v169
	ds_read_b128 v[128:131], v152
	ds_read_b128 v[132:135], v152 offset:1024
	ds_read_b128 v[148:151], v152 offset:2048
	ds_read_b128 v[152:155], v152 offset:3072
	s_cmp_eq_u32 s38, 12
	s_cselect_b32 s19, s11, s17
	s_cselect_b32 s18, s13, s16
	s_cselect_b32 s17, s20, s31
	s_cselect_b32 s16, s21, s29
	v_lshl_add_u64 v[204:205], s[14:15], 0, v[144:145]
	s_add_i32 m0, s48, 0xc000
	ds_read_b128 v[156:159], v182
	ds_read_b128 v[160:163], v182 offset:1024
	ds_read_b128 v[164:167], v182 offset:2048
	ds_read_b128 v[184:187], v182 offset:3072
	ds_read_b128 v[188:191], v182 offset:4096
	ds_read_b128 v[192:195], v182 offset:5120
	ds_read_b128 v[196:199], v182 offset:6144
	ds_read_b128 v[200:203], v182 offset:7168
	global_load_lds_dwordx4 v[204:205], off
	v_lshl_add_u64 v[204:205], s[14:15], 0, v[146:147]
	s_add_i32 m0, s48, 0xe000
	s_nop 0
	global_load_lds_dwordx4 v[204:205], off
	s_waitcnt lgkmcnt(8)
	s_barrier
	s_waitcnt lgkmcnt(0)
	s_setprio 1
	s_waitcnt lgkmcnt(0)
	v_mfma_f32_16x16x32_bf16 v[124:127], v[128:131], v[156:159], v[124:127]
	v_mfma_f32_16x16x32_bf16 v[120:123], v[148:151], v[156:159], v[120:123]
	v_mfma_f32_16x16x32_bf16 v[108:111], v[128:131], v[164:167], v[108:111]
	v_mfma_f32_16x16x32_bf16 v[104:107], v[148:151], v[164:167], v[104:107]
	v_mfma_f32_16x16x32_bf16 v[92:95], v[128:131], v[188:191], v[92:95]
	v_mfma_f32_16x16x32_bf16 v[88:91], v[148:151], v[188:191], v[88:91]
	v_mfma_f32_16x16x32_bf16 v[76:79], v[128:131], v[196:199], v[76:79]
	v_mfma_f32_16x16x32_bf16 v[72:75], v[148:151], v[196:199], v[72:75]
	v_mfma_f32_16x16x32_bf16 v[124:127], v[132:135], v[160:163], v[124:127]
	v_mfma_f32_16x16x32_bf16 v[120:123], v[152:155], v[160:163], v[120:123]
	v_mfma_f32_16x16x32_bf16 v[108:111], v[132:135], v[184:187], v[108:111]
	v_mfma_f32_16x16x32_bf16 v[104:107], v[152:155], v[184:187], v[104:107]
	v_mfma_f32_16x16x32_bf16 v[92:95], v[132:135], v[192:195], v[92:95]
	v_mfma_f32_16x16x32_bf16 v[88:91], v[152:155], v[192:195], v[88:91]
	v_mfma_f32_16x16x32_bf16 v[76:79], v[132:135], v[200:203], v[76:79]
	v_mfma_f32_16x16x32_bf16 v[72:75], v[152:155], v[200:203], v[72:75]
	s_setprio 0
	s_barrier
	s_add_i32 s74, 0, 0x14000
	s_add_i32 s39, s39, s47
	v_add_u32_e32 v172, s74, v169
	v_lshl_add_u64 v[212:213], s[16:17], 0, v[136:137]
	s_mov_b32 m0, s39
	ds_read_b128 v[204:207], v172
	ds_read_b128 v[208:211], v172 offset:1024
	ds_read_b128 v[230:233], v172 offset:2048
	ds_read_b128 v[234:237], v172 offset:3072
	global_load_lds_dwordx4 v[212:213], off
	v_lshl_add_u64 v[238:239], s[16:17], 0, v[138:139]
	s_add_i32 m0, s39, 0x2000
	s_nop 0
	global_load_lds_dwordx4 v[238:239], off
	s_barrier
	s_waitcnt lgkmcnt(0)
	s_setprio 1
	s_waitcnt lgkmcnt(0)
	v_mfma_f32_16x16x32_bf16 v[116:119], v[204:207], v[156:159], v[116:119]
	v_mfma_f32_16x16x32_bf16 v[112:115], v[230:233], v[156:159], v[112:115]
	v_mfma_f32_16x16x32_bf16 v[100:103], v[204:207], v[164:167], v[100:103]
	v_mfma_f32_16x16x32_bf16 v[96:99], v[230:233], v[164:167], v[96:99]
	v_mfma_f32_16x16x32_bf16 v[84:87], v[204:207], v[188:191], v[84:87]
	v_mfma_f32_16x16x32_bf16 v[80:83], v[230:233], v[188:191], v[80:83]
	v_mfma_f32_16x16x32_bf16 v[68:71], v[204:207], v[196:199], v[68:71]
	v_mfma_f32_16x16x32_bf16 v[64:67], v[230:233], v[196:199], v[64:67]
	v_mfma_f32_16x16x32_bf16 v[116:119], v[208:211], v[160:163], v[116:119]
	v_mfma_f32_16x16x32_bf16 v[112:115], v[234:237], v[160:163], v[112:115]
	v_mfma_f32_16x16x32_bf16 v[100:103], v[208:211], v[184:187], v[100:103]
	v_mfma_f32_16x16x32_bf16 v[96:99], v[234:237], v[184:187], v[96:99]
	v_mfma_f32_16x16x32_bf16 v[84:87], v[208:211], v[192:195], v[84:87]
	v_mfma_f32_16x16x32_bf16 v[80:83], v[234:237], v[192:195], v[80:83]
	v_mfma_f32_16x16x32_bf16 v[68:71], v[208:211], v[200:203], v[68:71]
	v_mfma_f32_16x16x32_bf16 v[64:67], v[234:237], v[200:203], v[64:67]
	s_setprio 0
	s_mov_b32 m0, s48
	v_lshl_add_u64 v[240:241], s[18:19], 0, v[136:137]
	s_barrier
	ds_read_b128 v[156:159], v182 offset:16384
	ds_read_b128 v[160:163], v182 offset:17408
	ds_read_b128 v[164:167], v182 offset:18432
	ds_read_b128 v[184:187], v182 offset:19456
	ds_read_b128 v[188:191], v182 offset:20480
	ds_read_b128 v[192:195], v182 offset:21504
	ds_read_b128 v[196:199], v182 offset:22528
	ds_read_b128 v[200:203], v182 offset:23552
	global_load_lds_dwordx4 v[240:241], off
	v_lshl_add_u64 v[242:243], s[18:19], 0, v[138:139]
	s_mov_b32 m0, s49
	s_nop 0
	global_load_lds_dwordx4 v[242:243], off
	s_barrier
	s_waitcnt lgkmcnt(0)
	s_setprio 1
	s_waitcnt lgkmcnt(0)
	v_mfma_f32_16x16x32_bf16 v[60:63], v[128:131], v[156:159], v[60:63]
	v_mfma_f32_16x16x32_bf16 v[56:59], v[148:151], v[156:159], v[56:59]
	v_mfma_f32_16x16x32_bf16 v[44:47], v[128:131], v[164:167], v[44:47]
	v_mfma_f32_16x16x32_bf16 v[40:43], v[148:151], v[164:167], v[40:43]
	v_mfma_f32_16x16x32_bf16 v[28:31], v[128:131], v[188:191], v[28:31]
	v_mfma_f32_16x16x32_bf16 v[24:27], v[148:151], v[188:191], v[24:27]
	v_mfma_f32_16x16x32_bf16 v[12:15], v[128:131], v[196:199], v[12:15]
	v_mfma_f32_16x16x32_bf16 v[8:11], v[148:151], v[196:199], v[8:11]
	v_mfma_f32_16x16x32_bf16 v[60:63], v[132:135], v[160:163], v[60:63]
	v_mfma_f32_16x16x32_bf16 v[56:59], v[152:155], v[160:163], v[56:59]
	v_mfma_f32_16x16x32_bf16 v[44:47], v[132:135], v[184:187], v[44:47]
	v_mfma_f32_16x16x32_bf16 v[40:43], v[152:155], v[184:187], v[40:43]
	v_mfma_f32_16x16x32_bf16 v[28:31], v[132:135], v[192:195], v[28:31]
	v_mfma_f32_16x16x32_bf16 v[24:27], v[152:155], v[192:195], v[24:27]
	v_mfma_f32_16x16x32_bf16 v[12:15], v[132:135], v[200:203], v[12:15]
	v_mfma_f32_16x16x32_bf16 v[8:11], v[152:155], v[200:203], v[8:11]
	s_setprio 0
	s_barrier
	s_add_u32 s58, s16, 0x40000
	s_addc_u32 s59, s17, 0
	s_add_i32 s39, s74, s47
	v_lshl_add_u64 v[128:129], s[58:59], 0, v[136:137]
	s_mov_b32 m0, s39
	s_nop 0
	global_load_lds_dwordx4 v[128:129], off
	v_lshl_add_u64 v[128:129], s[58:59], 0, v[138:139]
	s_add_i32 m0, s39, 0x2000
	s_nop 0
	global_load_lds_dwordx4 v[128:129], off
	s_waitcnt vmcnt(6)
	s_barrier
	s_setprio 1
	v_mfma_f32_16x16x32_bf16 v[52:55], v[204:207], v[156:159], v[52:55]
	v_mfma_f32_16x16x32_bf16 v[48:51], v[230:233], v[156:159], v[48:51]
	v_mfma_f32_16x16x32_bf16 v[36:39], v[204:207], v[164:167], v[36:39]
	v_mfma_f32_16x16x32_bf16 v[32:35], v[230:233], v[164:167], v[32:35]
	v_mfma_f32_16x16x32_bf16 v[20:23], v[204:207], v[188:191], v[20:23]
	v_mfma_f32_16x16x32_bf16 v[16:19], v[230:233], v[188:191], v[16:19]
	v_mfma_f32_16x16x32_bf16 v[4:7], v[204:207], v[196:199], v[4:7]
	v_mfma_f32_16x16x32_bf16 v[0:3], v[230:233], v[196:199], v[0:3]
	v_mfma_f32_16x16x32_bf16 v[52:55], v[208:211], v[160:163], v[52:55]
	v_mfma_f32_16x16x32_bf16 v[48:51], v[234:237], v[160:163], v[48:51]
	v_mfma_f32_16x16x32_bf16 v[36:39], v[208:211], v[184:187], v[36:39]
	v_mfma_f32_16x16x32_bf16 v[32:35], v[234:237], v[184:187], v[32:35]
	v_mfma_f32_16x16x32_bf16 v[20:23], v[208:211], v[192:195], v[20:23]
	v_mfma_f32_16x16x32_bf16 v[16:19], v[234:237], v[192:195], v[16:19]
	v_mfma_f32_16x16x32_bf16 v[4:7], v[208:211], v[200:203], v[4:7]
	v_mfma_f32_16x16x32_bf16 v[0:3], v[234:237], v[200:203], v[0:3]
	s_setprio 0
	s_add_i32 s39, 0, 0x18000
	v_add_u32_e32 v152, s39, v169
	s_barrier
	ds_read_b128 v[128:131], v152
	ds_read_b128 v[132:135], v152 offset:1024
	ds_read_b128 v[148:151], v152 offset:2048
	ds_read_b128 v[152:155], v152 offset:3072
	s_add_u32 s18, s18, 0x40000
	s_addc_u32 s19, s19, 0
	s_mov_b32 m0, s50
	v_lshl_add_u64 v[204:205], s[18:19], 0, v[136:137]
	ds_read_b128 v[156:159], v182 offset:32768
	ds_read_b128 v[160:163], v182 offset:33792
	ds_read_b128 v[164:167], v182 offset:34816
	ds_read_b128 v[184:187], v182 offset:35840
	ds_read_b128 v[188:191], v182 offset:36864
	ds_read_b128 v[192:195], v182 offset:37888
	ds_read_b128 v[196:199], v182 offset:38912
	ds_read_b128 v[200:203], v182 offset:39936
	global_load_lds_dwordx4 v[204:205], off
	v_lshl_add_u64 v[204:205], s[18:19], 0, v[138:139]
	s_mov_b32 m0, s51
	s_nop 0
	global_load_lds_dwordx4 v[204:205], off
	s_waitcnt lgkmcnt(8)
	s_barrier
	s_waitcnt lgkmcnt(0)
	s_setprio 1
	s_waitcnt lgkmcnt(0)
	v_mfma_f32_16x16x32_bf16 v[124:127], v[128:131], v[156:159], v[124:127]
	v_mfma_f32_16x16x32_bf16 v[120:123], v[148:151], v[156:159], v[120:123]
	v_mfma_f32_16x16x32_bf16 v[108:111], v[128:131], v[164:167], v[108:111]
	v_mfma_f32_16x16x32_bf16 v[104:107], v[148:151], v[164:167], v[104:107]
	v_mfma_f32_16x16x32_bf16 v[92:95], v[128:131], v[188:191], v[92:95]
	v_mfma_f32_16x16x32_bf16 v[88:91], v[148:151], v[188:191], v[88:91]
	v_mfma_f32_16x16x32_bf16 v[76:79], v[128:131], v[196:199], v[76:79]
	v_mfma_f32_16x16x32_bf16 v[72:75], v[148:151], v[196:199], v[72:75]
	v_mfma_f32_16x16x32_bf16 v[124:127], v[132:135], v[160:163], v[124:127]
	v_mfma_f32_16x16x32_bf16 v[120:123], v[152:155], v[160:163], v[120:123]
	v_mfma_f32_16x16x32_bf16 v[108:111], v[132:135], v[184:187], v[108:111]
	v_mfma_f32_16x16x32_bf16 v[104:107], v[152:155], v[184:187], v[104:107]
	v_mfma_f32_16x16x32_bf16 v[92:95], v[132:135], v[192:195], v[92:95]
	v_mfma_f32_16x16x32_bf16 v[88:91], v[152:155], v[192:195], v[88:91]
	v_mfma_f32_16x16x32_bf16 v[76:79], v[132:135], v[200:203], v[76:79]
	v_mfma_f32_16x16x32_bf16 v[72:75], v[152:155], v[200:203], v[72:75]
	s_setprio 0
	s_barrier
	s_add_i32 s18, 0, 0x1c000
	s_add_i32 s19, s39, s47
	v_add_u32_e32 v172, s18, v169
	v_lshl_add_u64 v[212:213], v[212:213], 0, s[78:79]
	s_mov_b32 m0, s19
	ds_read_b128 v[204:207], v172
	ds_read_b128 v[208:211], v172 offset:1024
	ds_read_b128 v[230:233], v172 offset:2048
	ds_read_b128 v[234:237], v172 offset:3072
	global_load_lds_dwordx4 v[212:213], off
	v_lshl_add_u64 v[212:213], v[238:239], 0, s[78:79]
	s_add_i32 m0, s19, 0x2000
	s_nop 0
	global_load_lds_dwordx4 v[212:213], off
	s_barrier
	s_waitcnt lgkmcnt(0)
	s_setprio 1
	s_waitcnt lgkmcnt(0)
	v_mfma_f32_16x16x32_bf16 v[116:119], v[204:207], v[156:159], v[116:119]
	v_mfma_f32_16x16x32_bf16 v[112:115], v[230:233], v[156:159], v[112:115]
	v_mfma_f32_16x16x32_bf16 v[100:103], v[204:207], v[164:167], v[100:103]
	v_mfma_f32_16x16x32_bf16 v[96:99], v[230:233], v[164:167], v[96:99]
	v_mfma_f32_16x16x32_bf16 v[84:87], v[204:207], v[188:191], v[84:87]
	v_mfma_f32_16x16x32_bf16 v[80:83], v[230:233], v[188:191], v[80:83]
	v_mfma_f32_16x16x32_bf16 v[68:71], v[204:207], v[196:199], v[68:71]
	v_mfma_f32_16x16x32_bf16 v[64:67], v[230:233], v[196:199], v[64:67]
	v_mfma_f32_16x16x32_bf16 v[116:119], v[208:211], v[160:163], v[116:119]
	v_mfma_f32_16x16x32_bf16 v[112:115], v[234:237], v[160:163], v[112:115]
	v_mfma_f32_16x16x32_bf16 v[100:103], v[208:211], v[184:187], v[100:103]
	v_mfma_f32_16x16x32_bf16 v[96:99], v[234:237], v[184:187], v[96:99]
	v_mfma_f32_16x16x32_bf16 v[84:87], v[208:211], v[192:195], v[84:87]
	v_mfma_f32_16x16x32_bf16 v[80:83], v[234:237], v[192:195], v[80:83]
	v_mfma_f32_16x16x32_bf16 v[68:71], v[208:211], v[200:203], v[68:71]
	v_mfma_f32_16x16x32_bf16 v[64:67], v[234:237], v[200:203], v[64:67]
	s_setprio 0
	s_mov_b32 m0, s88
	v_lshl_add_u64 v[212:213], v[240:241], 0, s[78:79]
	s_barrier
	ds_read_b128 v[156:159], v182 offset:49152
	ds_read_b128 v[160:163], v182 offset:50176
	ds_read_b128 v[164:167], v182 offset:51200
	ds_read_b128 v[184:187], v182 offset:52224
	ds_read_b128 v[188:191], v182 offset:53248
	ds_read_b128 v[192:195], v182 offset:54272
	ds_read_b128 v[196:199], v182 offset:55296
	ds_read_b128 v[200:203], v182 offset:56320
	global_load_lds_dwordx4 v[212:213], off
	v_lshl_add_u64 v[212:213], v[242:243], 0, s[78:79]
	s_mov_b32 m0, s89
	s_nop 0
	global_load_lds_dwordx4 v[212:213], off
	s_barrier
	s_waitcnt lgkmcnt(0)
	s_setprio 1
	s_waitcnt lgkmcnt(0)
	v_mfma_f32_16x16x32_bf16 v[60:63], v[128:131], v[156:159], v[60:63]
	v_mfma_f32_16x16x32_bf16 v[56:59], v[148:151], v[156:159], v[56:59]
	v_mfma_f32_16x16x32_bf16 v[44:47], v[128:131], v[164:167], v[44:47]
	v_mfma_f32_16x16x32_bf16 v[40:43], v[148:151], v[164:167], v[40:43]
	v_mfma_f32_16x16x32_bf16 v[28:31], v[128:131], v[188:191], v[28:31]
	v_mfma_f32_16x16x32_bf16 v[24:27], v[148:151], v[188:191], v[24:27]
	v_mfma_f32_16x16x32_bf16 v[12:15], v[128:131], v[196:199], v[12:15]
	v_mfma_f32_16x16x32_bf16 v[8:11], v[148:151], v[196:199], v[8:11]
	v_mfma_f32_16x16x32_bf16 v[60:63], v[132:135], v[160:163], v[60:63]
	v_mfma_f32_16x16x32_bf16 v[56:59], v[152:155], v[160:163], v[56:59]
	v_mfma_f32_16x16x32_bf16 v[44:47], v[132:135], v[184:187], v[44:47]
	v_mfma_f32_16x16x32_bf16 v[40:43], v[152:155], v[184:187], v[40:43]
	v_mfma_f32_16x16x32_bf16 v[28:31], v[132:135], v[192:195], v[28:31]
	v_mfma_f32_16x16x32_bf16 v[24:27], v[152:155], v[192:195], v[24:27]
	v_mfma_f32_16x16x32_bf16 v[12:15], v[132:135], v[200:203], v[12:15]
	v_mfma_f32_16x16x32_bf16 v[8:11], v[152:155], v[200:203], v[8:11]
	s_setprio 0
	s_barrier
	s_add_u32 s16, s16, 0x40080
	s_addc_u32 s17, s17, 0
	s_add_i32 s18, s18, s47
	v_lshl_add_u64 v[128:129], s[16:17], 0, v[136:137]
	s_mov_b32 m0, s18
	s_nop 0
	global_load_lds_dwordx4 v[128:129], off
	v_lshl_add_u64 v[128:129], s[16:17], 0, v[138:139]
	s_add_i32 m0, s18, 0x2000
	s_nop 0
	global_load_lds_dwordx4 v[128:129], off
	s_waitcnt vmcnt(6)
	s_barrier
	s_setprio 1
	v_mfma_f32_16x16x32_bf16 v[52:55], v[204:207], v[156:159], v[52:55]
	v_mfma_f32_16x16x32_bf16 v[48:51], v[230:233], v[156:159], v[48:51]
	v_mfma_f32_16x16x32_bf16 v[36:39], v[204:207], v[164:167], v[36:39]
	v_mfma_f32_16x16x32_bf16 v[32:35], v[230:233], v[164:167], v[32:35]
	v_mfma_f32_16x16x32_bf16 v[20:23], v[204:207], v[188:191], v[20:23]
	v_mfma_f32_16x16x32_bf16 v[16:19], v[230:233], v[188:191], v[16:19]
	v_mfma_f32_16x16x32_bf16 v[4:7], v[204:207], v[196:199], v[4:7]
	v_mfma_f32_16x16x32_bf16 v[0:3], v[230:233], v[196:199], v[0:3]
	v_mfma_f32_16x16x32_bf16 v[52:55], v[208:211], v[160:163], v[52:55]
	v_mfma_f32_16x16x32_bf16 v[48:51], v[234:237], v[160:163], v[48:51]
	v_mfma_f32_16x16x32_bf16 v[36:39], v[208:211], v[184:187], v[36:39]
	v_mfma_f32_16x16x32_bf16 v[32:35], v[234:237], v[184:187], v[32:35]
	v_mfma_f32_16x16x32_bf16 v[20:23], v[208:211], v[192:195], v[20:23]
	v_mfma_f32_16x16x32_bf16 v[16:19], v[234:237], v[192:195], v[16:19]
	v_mfma_f32_16x16x32_bf16 v[4:7], v[208:211], v[200:203], v[4:7]
	v_mfma_f32_16x16x32_bf16 v[0:3], v[234:237], v[200:203], v[0:3]
	s_setprio 0
	s_add_i32 s38, s38, 2
	s_add_u32 s14, s14, 0x100
	s_addc_u32 s15, s15, 0
	s_add_u32 s29, s29, 0x100
	s_addc_u32 s31, s31, 0
	s_cmp_gt_u32 s38, 13
	s_barrier
	s_cbranch_scc0 .LBB0_156
	v_and_b32_e32 v254, 4, v171
	v_mul_u32_u24_e32 v254, 14, v254
	v_mov_b32_e32 v255, 0
	s_lshl_b32 s15, s12, 8
	s_ashr_i32 s14, s10, 2
	s_add_i32 s15, s15, s87
	v_or_b32_e32 v150, s15, v168
	s_cmp_lt_i32 s14, 2
	s_cselect_b64 s[18:19], -1, 0
	s_cmp_gt_i32 s14, 1
	v_cmp_gt_i32_e32 vcc, s95, v150
	v_cmp_lt_i32_e64 s[16:17], s92, v150
	s_cbranch_scc1 .LBB0_159
	v_and_b32_e32 v128, 0x1fcf, v150
	v_cndmask_b32_e32 v128, v170, v128, vcc
	v_lshlrev_b32_e32 v172, 8, v128
	v_lshl_add_u64 v[128:129], v[142:143], 0, v[172:173]
	global_load_dwordx4 v[132:135], v[128:129], off
	s_nop 0
	global_load_dwordx4 v[128:131], v[128:129], off offset:128
	s_branch .LBB0_160

.LBB0_160:
	s_cmp_lt_u32 s10, 4
	v_lshl_or_b32 v148, s10, 8, v171
	s_waitcnt vmcnt(0)
	v_pk_mul_f32 v[152:153], v[120:121], v[128:129]
	s_cselect_b64 s[10:11], -1, 0
	s_cmp_eq_u32 s14, 3
	v_pk_mul_f32 v[158:159], v[122:123], v[130:131]
	v_pk_mul_f32 v[122:123], v[122:123], v[134:135]
	v_pk_mul_f32 v[120:121], v[120:121], v[132:133]
	v_pk_fma_f32 v[152:153], v[124:125], v[132:133], v[152:153] neg_lo:[0,0,1] neg_hi:[0,0,1]
	s_cselect_b64 s[12:13], -1, 0
	v_pk_fma_f32 v[158:159], v[126:127], v[134:135], v[158:159] neg_lo:[0,0,1] neg_hi:[0,0,1]
	v_pk_fma_f32 v[126:127], v[126:127], v[130:131], v[122:123]
	v_pk_fma_f32 v[124:125], v[124:125], v[128:129], v[120:121]
	v_pk_mul_f32 v[154:155], v[152:153], s[80:81] op_sel_hi:[1,0]
	v_ashrrev_i32_e32 v151, 31, v150
	v_pk_mul_f32 v[122:123], v[158:159], s[80:81] op_sel_hi:[1,0]
	v_pk_mul_f32 v[160:161], v[126:127], s[80:81] op_sel_hi:[1,0]
	v_pk_mul_f32 v[162:163], v[124:125], s[80:81] op_sel_hi:[1,0]
	s_or_b64 s[20:21], s[10:11], s[12:13]
	v_lshlrev_b64 v[156:157], 13, v[150:151]
	v_cndmask_b32_e64 v121, v153, v155, s[10:11]
	v_cndmask_b32_e64 v120, v152, v154, s[10:11]
	v_cndmask_b32_e64 v123, v159, v123, s[10:11]
	v_cndmask_b32_e64 v122, v158, v122, s[10:11]
	v_cndmask_b32_e64 v125, v125, v163, s[10:11]
	v_cndmask_b32_e64 v124, v124, v162, s[10:11]
	v_cndmask_b32_e64 v127, v127, v161, s[10:11]
	v_cndmask_b32_e64 v126, v126, v160, s[10:11]
	v_cndmask_b32_e64 v149, 0, 1, s[20:21]
	v_cvt_pk_bf16_f32 v160, v120, v121
	v_cvt_pk_bf16_f32 v161, v122, v123
	v_cvt_pk_bf16_f32 v162, v124, v125
	v_cvt_pk_bf16_f32 v163, v126, v127
	v_cmp_ne_u32_e64 s[12:13], 1, v149
	s_andn2_b64 vcc, exec, s[20:21]
	v_lshl_add_u64 v[158:159], s[22:23], 0, v[156:157]
	s_cbranch_vccnz .LBB0_162
	v_mov_b32_e32 v149, v173
	v_lshl_add_u64 v[152:153], v[148:149], 1, v[158:159]
	s_nop 1
	v_permlane16_swap_b32_e32 v160, v162
	v_permlane16_swap_b32_e32 v161, v163
	v_lshl_add_u64 v[244:245], v[152:153], 0, v[254:255]
	global_store_dwordx4 v[244:245], v[160:163], off

.LBB0_167:
	s_or_b64 exec, exec, s[14:15]
	v_and_b32_e32 v149, 0x5c, v148
	v_ashrrev_i32_e32 v153, 31, v152
	v_lshl_add_u64 v[164:165], v[152:153], 2, v[164:165]
	v_lshlrev_b32_e32 v172, 1, v149
	v_lshl_add_u64 v[166:167], v[166:167], 0, v[172:173]
	global_store_dwordx4 v[164:165], v[120:123], off
	global_store_dwordx4 v[164:165], v[124:127], off offset:128
	s_nop 1
	v_permlane16_swap_b32_e32 v160, v162
	v_permlane16_swap_b32_e32 v161, v163
	v_lshl_add_u64 v[244:245], v[166:167], 0, v[254:255]
	global_store_dwordx4 v[244:245], v[160:163], off
.LBB0_168:
	v_pk_mul_f32 v[120:121], v[114:115], v[130:131]
	v_pk_mul_f32 v[122:123], v[112:113], v[128:129]
	v_pk_mul_f32 v[114:115], v[114:115], v[134:135]
	v_pk_mul_f32 v[112:113], v[112:113], v[132:133]
	v_pk_fma_f32 v[120:121], v[118:119], v[134:135], v[120:121] neg_lo:[0,0,1] neg_hi:[0,0,1]
	v_pk_fma_f32 v[122:123], v[116:117], v[132:133], v[122:123] neg_lo:[0,0,1] neg_hi:[0,0,1]
	v_pk_fma_f32 v[118:119], v[118:119], v[130:131], v[114:115]
	v_pk_fma_f32 v[116:117], v[116:117], v[128:129], v[112:113]
	v_pk_mul_f32 v[112:113], v[122:123], s[80:81] op_sel_hi:[1,0]
	v_pk_mul_f32 v[114:115], v[120:121], s[80:81] op_sel_hi:[1,0]
	v_pk_mul_f32 v[124:125], v[116:117], s[80:81] op_sel_hi:[1,0]
	v_pk_mul_f32 v[126:127], v[118:119], s[80:81] op_sel_hi:[1,0]
	v_cndmask_b32_e64 v115, v121, v115, s[10:11]
	v_cndmask_b32_e64 v114, v120, v114, s[10:11]
	v_cndmask_b32_e64 v113, v123, v113, s[10:11]
	v_cndmask_b32_e64 v112, v122, v112, s[10:11]
	v_cndmask_b32_e64 v119, v119, v127, s[10:11]
	v_cndmask_b32_e64 v118, v118, v126, s[10:11]
	v_cndmask_b32_e64 v117, v117, v125, s[10:11]
	v_cndmask_b32_e64 v116, v116, v124, s[10:11]
	v_cvt_pk_bf16_f32 v120, v112, v113
	v_cvt_pk_bf16_f32 v121, v114, v115
	v_cvt_pk_bf16_f32 v122, v116, v117
	s_and_b64 vcc, exec, s[12:13]
	v_cvt_pk_bf16_f32 v123, v118, v119
	s_cbranch_vccnz .LBB0_170
	v_mov_b32_e32 v149, v173
	v_lshl_add_u64 v[124:125], v[148:149], 1, v[158:159]
	s_nop 1
	v_permlane16_swap_b32_e32 v120, v122
	v_permlane16_swap_b32_e32 v121, v123
	v_lshl_add_u64 v[244:245], v[124:125], 0, v[254:255]
	global_store_dwordx4 v[244:245], v[120:123], off offset:256

.LBB0_175:
	s_or_b64 exec, exec, s[16:17]
	v_ashrrev_i32_e32 v129, 31, v148
	v_subrev_co_u32_e32 v128, vcc, s29, v148
	v_and_b32_e32 v130, 0x5c, v148
	s_nop 0
	v_subbrev_co_u32_e32 v129, vcc, 0, v129, vcc
	v_lshl_add_u64 v[124:125], v[128:129], 2, v[124:125]
	v_lshlrev_b32_e32 v172, 1, v130
	v_lshl_add_u64 v[126:127], v[126:127], 0, v[172:173]
	global_store_dwordx4 v[124:125], v[112:115], off offset:512
	global_store_dwordx4 v[124:125], v[116:119], off offset:640
	s_nop 1
	v_permlane16_swap_b32_e32 v120, v122
	v_permlane16_swap_b32_e32 v121, v123
	v_lshl_add_u64 v[244:245], v[126:127], 0, v[254:255]
	global_store_dwordx4 v[244:245], v[120:123], off

.LBB0_179:
	s_waitcnt vmcnt(0)
	v_pk_mul_f32 v[122:123], v[106:107], v[114:115]
	v_pk_mul_f32 v[124:125], v[104:105], v[112:113]
	v_pk_mul_f32 v[106:107], v[106:107], v[118:119]
	v_pk_mul_f32 v[104:105], v[104:105], v[116:117]
	v_pk_fma_f32 v[122:123], v[110:111], v[118:119], v[122:123] neg_lo:[0,0,1] neg_hi:[0,0,1]
	v_pk_fma_f32 v[124:125], v[108:109], v[116:117], v[124:125] neg_lo:[0,0,1] neg_hi:[0,0,1]
	v_pk_fma_f32 v[110:111], v[110:111], v[114:115], v[106:107]
	v_pk_fma_f32 v[108:109], v[108:109], v[112:113], v[104:105]
	v_ashrrev_i32_e32 v127, 31, v126
	v_pk_mul_f32 v[106:107], v[122:123], s[80:81] op_sel_hi:[1,0]
	v_pk_mul_f32 v[104:105], v[124:125], s[80:81] op_sel_hi:[1,0]
	v_pk_mul_f32 v[128:129], v[110:111], s[80:81] op_sel_hi:[1,0]
	v_pk_mul_f32 v[130:131], v[108:109], s[80:81] op_sel_hi:[1,0]
	v_lshlrev_b64 v[120:121], 13, v[126:127]
	v_cndmask_b32_e64 v105, v125, v105, s[10:11]
	v_cndmask_b32_e64 v104, v124, v104, s[10:11]
	v_cndmask_b32_e64 v107, v123, v107, s[10:11]
	v_cndmask_b32_e64 v106, v122, v106, s[10:11]
	v_cndmask_b32_e64 v109, v109, v131, s[10:11]
	v_cndmask_b32_e64 v108, v108, v130, s[10:11]
	v_cndmask_b32_e64 v111, v111, v129, s[10:11]
	v_cndmask_b32_e64 v110, v110, v128, s[10:11]
	v_cvt_pk_bf16_f32 v128, v104, v105
	v_cvt_pk_bf16_f32 v129, v106, v107
	v_cvt_pk_bf16_f32 v130, v108, v109
	v_cvt_pk_bf16_f32 v131, v110, v111
	s_and_b64 vcc, exec, s[12:13]
	v_lshl_add_u64 v[124:125], s[22:23], 0, v[120:121]
	s_cbranch_vccnz .LBB0_181
	v_mov_b32_e32 v149, v173
	v_lshl_add_u64 v[120:121], v[148:149], 1, v[124:125]
	s_nop 1
	v_permlane16_swap_b32_e32 v128, v130
	v_permlane16_swap_b32_e32 v129, v131
	v_lshl_add_u64 v[244:245], v[120:121], 0, v[254:255]
	global_store_dwordx4 v[244:245], v[128:131], off

.LBB0_186:
	s_or_b64 exec, exec, s[20:21]
	v_and_b32_e32 v149, 0x5c, v148
	v_ashrrev_i32_e32 v153, 31, v152
	v_lshl_add_u64 v[126:127], v[152:153], 2, v[126:127]
	v_lshlrev_b32_e32 v172, 1, v149
	v_lshl_add_u64 v[132:133], v[132:133], 0, v[172:173]
	global_store_dwordx4 v[126:127], v[104:107], off
	global_store_dwordx4 v[126:127], v[108:111], off offset:128
	s_nop 1
	v_permlane16_swap_b32_e32 v128, v130
	v_permlane16_swap_b32_e32 v129, v131
	v_lshl_add_u64 v[244:245], v[132:133], 0, v[254:255]
	global_store_dwordx4 v[244:245], v[128:131], off
.LBB0_187:
	v_pk_mul_f32 v[104:105], v[98:99], v[114:115]
	v_pk_mul_f32 v[106:107], v[96:97], v[112:113]
	v_pk_mul_f32 v[98:99], v[98:99], v[118:119]
	v_pk_mul_f32 v[96:97], v[96:97], v[116:117]
	v_pk_fma_f32 v[104:105], v[102:103], v[118:119], v[104:105] neg_lo:[0,0,1] neg_hi:[0,0,1]
	v_pk_fma_f32 v[106:107], v[100:101], v[116:117], v[106:107] neg_lo:[0,0,1] neg_hi:[0,0,1]
	v_pk_fma_f32 v[102:103], v[102:103], v[114:115], v[98:99]
	v_pk_fma_f32 v[100:101], v[100:101], v[112:113], v[96:97]
	v_pk_mul_f32 v[96:97], v[106:107], s[80:81] op_sel_hi:[1,0]
	v_pk_mul_f32 v[98:99], v[104:105], s[80:81] op_sel_hi:[1,0]
	v_pk_mul_f32 v[108:109], v[100:101], s[80:81] op_sel_hi:[1,0]
	v_pk_mul_f32 v[110:111], v[102:103], s[80:81] op_sel_hi:[1,0]
	v_cndmask_b32_e64 v99, v105, v99, s[10:11]
	v_cndmask_b32_e64 v98, v104, v98, s[10:11]
	v_cndmask_b32_e64 v97, v107, v97, s[10:11]
	v_cndmask_b32_e64 v96, v106, v96, s[10:11]
	v_cndmask_b32_e64 v103, v103, v111, s[10:11]
	v_cndmask_b32_e64 v102, v102, v110, s[10:11]
	v_cndmask_b32_e64 v101, v101, v109, s[10:11]
	v_cndmask_b32_e64 v100, v100, v108, s[10:11]
	v_cvt_pk_bf16_f32 v104, v96, v97
	v_cvt_pk_bf16_f32 v105, v98, v99
	v_cvt_pk_bf16_f32 v106, v100, v101
	s_and_b64 vcc, exec, s[12:13]
	v_cvt_pk_bf16_f32 v107, v102, v103
	s_cbranch_vccnz .LBB0_189
	v_mov_b32_e32 v149, v173
	v_lshl_add_u64 v[108:109], v[148:149], 1, v[124:125]
	s_nop 1
	v_permlane16_swap_b32_e32 v104, v106
	v_permlane16_swap_b32_e32 v105, v107
	v_lshl_add_u64 v[244:245], v[108:109], 0, v[254:255]
	global_store_dwordx4 v[244:245], v[104:107], off offset:256

.LBB0_194:
	s_or_b64 exec, exec, s[18:19]
	v_ashrrev_i32_e32 v113, 31, v148
	v_subrev_co_u32_e32 v112, vcc, s29, v148
	v_and_b32_e32 v114, 0x5c, v148
	s_nop 0
	v_subbrev_co_u32_e32 v113, vcc, 0, v113, vcc
	v_lshl_add_u64 v[108:109], v[112:113], 2, v[108:109]
	v_lshlrev_b32_e32 v172, 1, v114
	v_lshl_add_u64 v[110:111], v[110:111], 0, v[172:173]
	global_store_dwordx4 v[108:109], v[96:99], off offset:512
	global_store_dwordx4 v[108:109], v[100:103], off offset:640
	s_nop 1
	v_permlane16_swap_b32_e32 v104, v106
	v_permlane16_swap_b32_e32 v105, v107
	v_lshl_add_u64 v[244:245], v[110:111], 0, v[254:255]
	global_store_dwordx4 v[244:245], v[104:107], off

.LBB0_198:
	s_waitcnt vmcnt(0)
	v_pk_mul_f32 v[106:107], v[90:91], v[98:99]
	v_pk_mul_f32 v[108:109], v[88:89], v[96:97]
	v_pk_mul_f32 v[90:91], v[90:91], v[102:103]
	v_pk_mul_f32 v[88:89], v[88:89], v[100:101]
	v_pk_fma_f32 v[106:107], v[94:95], v[102:103], v[106:107] neg_lo:[0,0,1] neg_hi:[0,0,1]
	v_pk_fma_f32 v[108:109], v[92:93], v[100:101], v[108:109] neg_lo:[0,0,1] neg_hi:[0,0,1]
	v_pk_fma_f32 v[94:95], v[94:95], v[98:99], v[90:91]
	v_pk_fma_f32 v[92:93], v[92:93], v[96:97], v[88:89]
	v_ashrrev_i32_e32 v111, 31, v110
	v_pk_mul_f32 v[90:91], v[106:107], s[80:81] op_sel_hi:[1,0]
	v_pk_mul_f32 v[88:89], v[108:109], s[80:81] op_sel_hi:[1,0]
	v_pk_mul_f32 v[112:113], v[94:95], s[80:81] op_sel_hi:[1,0]
	v_pk_mul_f32 v[114:115], v[92:93], s[80:81] op_sel_hi:[1,0]
	v_lshlrev_b64 v[104:105], 13, v[110:111]
	v_cndmask_b32_e64 v89, v109, v89, s[10:11]
	v_cndmask_b32_e64 v88, v108, v88, s[10:11]
	v_cndmask_b32_e64 v91, v107, v91, s[10:11]
	v_cndmask_b32_e64 v90, v106, v90, s[10:11]
	v_cndmask_b32_e64 v93, v93, v115, s[10:11]
	v_cndmask_b32_e64 v92, v92, v114, s[10:11]
	v_cndmask_b32_e64 v95, v95, v113, s[10:11]
	v_cndmask_b32_e64 v94, v94, v112, s[10:11]
	v_cvt_pk_bf16_f32 v112, v88, v89
	v_cvt_pk_bf16_f32 v113, v90, v91
	v_cvt_pk_bf16_f32 v114, v92, v93
	v_cvt_pk_bf16_f32 v115, v94, v95
	s_and_b64 vcc, exec, s[12:13]
	v_lshl_add_u64 v[108:109], s[22:23], 0, v[104:105]
	s_cbranch_vccnz .LBB0_200
	v_mov_b32_e32 v149, v173
	v_lshl_add_u64 v[104:105], v[148:149], 1, v[108:109]
	s_nop 1
	v_permlane16_swap_b32_e32 v112, v114
	v_permlane16_swap_b32_e32 v113, v115
	v_lshl_add_u64 v[244:245], v[104:105], 0, v[254:255]
	global_store_dwordx4 v[244:245], v[112:115], off

.LBB0_205:
	s_or_b64 exec, exec, s[20:21]
	v_and_b32_e32 v120, 0x5c, v148
	v_ashrrev_i32_e32 v153, 31, v152
	v_lshl_add_u64 v[110:111], v[152:153], 2, v[110:111]
	v_lshlrev_b32_e32 v172, 1, v120
	v_lshl_add_u64 v[116:117], v[116:117], 0, v[172:173]
	global_store_dwordx4 v[110:111], v[88:91], off
	global_store_dwordx4 v[110:111], v[92:95], off offset:128
	s_nop 1
	v_permlane16_swap_b32_e32 v112, v114
	v_permlane16_swap_b32_e32 v113, v115
	v_lshl_add_u64 v[244:245], v[116:117], 0, v[254:255]
	global_store_dwordx4 v[244:245], v[112:115], off
.LBB0_206:
	v_pk_mul_f32 v[88:89], v[82:83], v[98:99]
	v_pk_mul_f32 v[90:91], v[80:81], v[96:97]
	v_pk_mul_f32 v[82:83], v[82:83], v[102:103]
	v_pk_mul_f32 v[80:81], v[80:81], v[100:101]
	v_pk_fma_f32 v[88:89], v[86:87], v[102:103], v[88:89] neg_lo:[0,0,1] neg_hi:[0,0,1]
	v_pk_fma_f32 v[90:91], v[84:85], v[100:101], v[90:91] neg_lo:[0,0,1] neg_hi:[0,0,1]
	v_pk_fma_f32 v[86:87], v[86:87], v[98:99], v[82:83]
	v_pk_fma_f32 v[84:85], v[84:85], v[96:97], v[80:81]
	v_pk_mul_f32 v[80:81], v[90:91], s[80:81] op_sel_hi:[1,0]
	v_pk_mul_f32 v[82:83], v[88:89], s[80:81] op_sel_hi:[1,0]
	v_pk_mul_f32 v[92:93], v[84:85], s[80:81] op_sel_hi:[1,0]
	v_pk_mul_f32 v[94:95], v[86:87], s[80:81] op_sel_hi:[1,0]
	v_cndmask_b32_e64 v83, v89, v83, s[10:11]
	v_cndmask_b32_e64 v82, v88, v82, s[10:11]
	v_cndmask_b32_e64 v81, v91, v81, s[10:11]
	v_cndmask_b32_e64 v80, v90, v80, s[10:11]
	v_cndmask_b32_e64 v87, v87, v95, s[10:11]
	v_cndmask_b32_e64 v86, v86, v94, s[10:11]
	v_cndmask_b32_e64 v85, v85, v93, s[10:11]
	v_cndmask_b32_e64 v84, v84, v92, s[10:11]
	v_cvt_pk_bf16_f32 v88, v80, v81
	v_cvt_pk_bf16_f32 v89, v82, v83
	v_cvt_pk_bf16_f32 v90, v84, v85
	s_and_b64 vcc, exec, s[12:13]
	v_cvt_pk_bf16_f32 v91, v86, v87
	s_cbranch_vccnz .LBB0_208
	v_mov_b32_e32 v149, v173
	v_lshl_add_u64 v[92:93], v[148:149], 1, v[108:109]
	s_nop 1
	v_permlane16_swap_b32_e32 v88, v90
	v_permlane16_swap_b32_e32 v89, v91
	v_lshl_add_u64 v[244:245], v[92:93], 0, v[254:255]
	global_store_dwordx4 v[244:245], v[88:91], off offset:256

.LBB0_213:
	s_or_b64 exec, exec, s[18:19]
	v_ashrrev_i32_e32 v97, 31, v148
	v_subrev_co_u32_e32 v96, vcc, s29, v148
	v_and_b32_e32 v98, 0x5c, v148
	s_nop 0
	v_subbrev_co_u32_e32 v97, vcc, 0, v97, vcc
	v_lshl_add_u64 v[92:93], v[96:97], 2, v[92:93]
	v_lshlrev_b32_e32 v172, 1, v98
	v_lshl_add_u64 v[94:95], v[94:95], 0, v[172:173]
	global_store_dwordx4 v[92:93], v[80:83], off offset:512
	global_store_dwordx4 v[92:93], v[84:87], off offset:640
	s_nop 1
	v_permlane16_swap_b32_e32 v88, v90
	v_permlane16_swap_b32_e32 v89, v91
	v_lshl_add_u64 v[244:245], v[94:95], 0, v[254:255]
	global_store_dwordx4 v[244:245], v[88:91], off

.LBB0_217:
	s_waitcnt vmcnt(0)
	v_pk_mul_f32 v[90:91], v[74:75], v[82:83]
	v_pk_mul_f32 v[92:93], v[72:73], v[80:81]
	v_pk_mul_f32 v[74:75], v[74:75], v[86:87]
	v_pk_mul_f32 v[72:73], v[72:73], v[84:85]
	v_pk_fma_f32 v[90:91], v[78:79], v[86:87], v[90:91] neg_lo:[0,0,1] neg_hi:[0,0,1]
	v_pk_fma_f32 v[92:93], v[76:77], v[84:85], v[92:93] neg_lo:[0,0,1] neg_hi:[0,0,1]
	v_pk_fma_f32 v[78:79], v[78:79], v[82:83], v[74:75]
	v_pk_fma_f32 v[76:77], v[76:77], v[80:81], v[72:73]
	v_ashrrev_i32_e32 v95, 31, v94
	v_pk_mul_f32 v[74:75], v[90:91], s[80:81] op_sel_hi:[1,0]
	v_pk_mul_f32 v[72:73], v[92:93], s[80:81] op_sel_hi:[1,0]
	v_pk_mul_f32 v[96:97], v[78:79], s[80:81] op_sel_hi:[1,0]
	v_pk_mul_f32 v[98:99], v[76:77], s[80:81] op_sel_hi:[1,0]
	v_lshlrev_b64 v[88:89], 13, v[94:95]
	v_cndmask_b32_e64 v73, v93, v73, s[10:11]
	v_cndmask_b32_e64 v72, v92, v72, s[10:11]
	v_cndmask_b32_e64 v75, v91, v75, s[10:11]
	v_cndmask_b32_e64 v74, v90, v74, s[10:11]
	v_cndmask_b32_e64 v77, v77, v99, s[10:11]
	v_cndmask_b32_e64 v76, v76, v98, s[10:11]
	v_cndmask_b32_e64 v79, v79, v97, s[10:11]
	v_cndmask_b32_e64 v78, v78, v96, s[10:11]
	v_cvt_pk_bf16_f32 v96, v72, v73
	v_cvt_pk_bf16_f32 v97, v74, v75
	v_cvt_pk_bf16_f32 v98, v76, v77
	v_cvt_pk_bf16_f32 v99, v78, v79
	s_and_b64 vcc, exec, s[12:13]
	v_lshl_add_u64 v[92:93], s[22:23], 0, v[88:89]
	s_cbranch_vccnz .LBB0_219
	v_mov_b32_e32 v149, v173
	v_lshl_add_u64 v[88:89], v[148:149], 1, v[92:93]
	s_nop 1
	v_permlane16_swap_b32_e32 v96, v98
	v_permlane16_swap_b32_e32 v97, v99
	v_lshl_add_u64 v[244:245], v[88:89], 0, v[254:255]
	global_store_dwordx4 v[244:245], v[96:99], off

.LBB0_224:
	s_or_b64 exec, exec, s[20:21]
	v_and_b32_e32 v104, 0x5c, v148
	v_ashrrev_i32_e32 v153, 31, v152
	v_lshl_add_u64 v[94:95], v[152:153], 2, v[94:95]
	v_lshlrev_b32_e32 v172, 1, v104
	v_lshl_add_u64 v[100:101], v[100:101], 0, v[172:173]
	global_store_dwordx4 v[94:95], v[72:75], off
	global_store_dwordx4 v[94:95], v[76:79], off offset:128
	s_nop 1
	v_permlane16_swap_b32_e32 v96, v98
	v_permlane16_swap_b32_e32 v97, v99
	v_lshl_add_u64 v[244:245], v[100:101], 0, v[254:255]
	global_store_dwordx4 v[244:245], v[96:99], off
.LBB0_225:
	v_pk_mul_f32 v[72:73], v[66:67], v[82:83]
	v_pk_mul_f32 v[74:75], v[64:65], v[80:81]
	v_pk_mul_f32 v[66:67], v[66:67], v[86:87]
	v_pk_mul_f32 v[64:65], v[64:65], v[84:85]
	v_pk_fma_f32 v[72:73], v[70:71], v[86:87], v[72:73] neg_lo:[0,0,1] neg_hi:[0,0,1]
	v_pk_fma_f32 v[74:75], v[68:69], v[84:85], v[74:75] neg_lo:[0,0,1] neg_hi:[0,0,1]
	v_pk_fma_f32 v[70:71], v[70:71], v[82:83], v[66:67]
	v_pk_fma_f32 v[68:69], v[68:69], v[80:81], v[64:65]
	v_pk_mul_f32 v[64:65], v[74:75], s[80:81] op_sel_hi:[1,0]
	v_pk_mul_f32 v[66:67], v[72:73], s[80:81] op_sel_hi:[1,0]
	v_pk_mul_f32 v[76:77], v[68:69], s[80:81] op_sel_hi:[1,0]
	v_pk_mul_f32 v[78:79], v[70:71], s[80:81] op_sel_hi:[1,0]
	v_cndmask_b32_e64 v67, v73, v67, s[10:11]
	v_cndmask_b32_e64 v66, v72, v66, s[10:11]
	v_cndmask_b32_e64 v65, v75, v65, s[10:11]
	v_cndmask_b32_e64 v64, v74, v64, s[10:11]
	v_cndmask_b32_e64 v71, v71, v79, s[10:11]
	v_cndmask_b32_e64 v70, v70, v78, s[10:11]
	v_cndmask_b32_e64 v69, v69, v77, s[10:11]
	v_cndmask_b32_e64 v68, v68, v76, s[10:11]
	v_cvt_pk_bf16_f32 v72, v64, v65
	v_cvt_pk_bf16_f32 v73, v66, v67
	v_cvt_pk_bf16_f32 v74, v68, v69
	s_and_b64 vcc, exec, s[12:13]
	v_cvt_pk_bf16_f32 v75, v70, v71
	s_cbranch_vccnz .LBB0_227
	v_mov_b32_e32 v149, v173
	v_lshl_add_u64 v[76:77], v[148:149], 1, v[92:93]
	s_nop 1
	v_permlane16_swap_b32_e32 v72, v74
	v_permlane16_swap_b32_e32 v73, v75
	v_lshl_add_u64 v[244:245], v[76:77], 0, v[254:255]
	global_store_dwordx4 v[244:245], v[72:75], off offset:256

.LBB0_232:
	s_or_b64 exec, exec, s[18:19]
	v_ashrrev_i32_e32 v81, 31, v148
	v_subrev_co_u32_e32 v80, vcc, s29, v148
	v_and_b32_e32 v82, 0x5c, v148
	s_nop 0
	v_subbrev_co_u32_e32 v81, vcc, 0, v81, vcc
	v_lshl_add_u64 v[76:77], v[80:81], 2, v[76:77]
	v_lshlrev_b32_e32 v172, 1, v82
	v_lshl_add_u64 v[78:79], v[78:79], 0, v[172:173]
	global_store_dwordx4 v[76:77], v[64:67], off offset:512
	global_store_dwordx4 v[76:77], v[68:71], off offset:640
	s_nop 1
	v_permlane16_swap_b32_e32 v72, v74
	v_permlane16_swap_b32_e32 v73, v75
	v_lshl_add_u64 v[244:245], v[78:79], 0, v[254:255]
	global_store_dwordx4 v[244:245], v[72:75], off

.LBB0_236:
	s_waitcnt vmcnt(0)
	v_pk_mul_f32 v[74:75], v[58:59], v[66:67]
	v_pk_mul_f32 v[76:77], v[56:57], v[64:65]
	v_pk_mul_f32 v[58:59], v[58:59], v[70:71]
	v_pk_mul_f32 v[56:57], v[56:57], v[68:69]
	v_pk_fma_f32 v[74:75], v[62:63], v[70:71], v[74:75] neg_lo:[0,0,1] neg_hi:[0,0,1]
	v_pk_fma_f32 v[76:77], v[60:61], v[68:69], v[76:77] neg_lo:[0,0,1] neg_hi:[0,0,1]
	v_pk_fma_f32 v[62:63], v[62:63], v[66:67], v[58:59]
	v_pk_fma_f32 v[60:61], v[60:61], v[64:65], v[56:57]
	v_ashrrev_i32_e32 v79, 31, v78
	v_pk_mul_f32 v[58:59], v[74:75], s[80:81] op_sel_hi:[1,0]
	v_pk_mul_f32 v[56:57], v[76:77], s[80:81] op_sel_hi:[1,0]
	v_pk_mul_f32 v[80:81], v[62:63], s[80:81] op_sel_hi:[1,0]
	v_pk_mul_f32 v[82:83], v[60:61], s[80:81] op_sel_hi:[1,0]
	v_lshlrev_b64 v[72:73], 13, v[78:79]
	v_cndmask_b32_e64 v57, v77, v57, s[10:11]
	v_cndmask_b32_e64 v56, v76, v56, s[10:11]
	v_cndmask_b32_e64 v59, v75, v59, s[10:11]
	v_cndmask_b32_e64 v58, v74, v58, s[10:11]
	v_cndmask_b32_e64 v61, v61, v83, s[10:11]
	v_cndmask_b32_e64 v60, v60, v82, s[10:11]
	v_cndmask_b32_e64 v63, v63, v81, s[10:11]
	v_cndmask_b32_e64 v62, v62, v80, s[10:11]
	v_cvt_pk_bf16_f32 v80, v56, v57
	v_cvt_pk_bf16_f32 v81, v58, v59
	v_cvt_pk_bf16_f32 v82, v60, v61
	v_cvt_pk_bf16_f32 v83, v62, v63
	s_and_b64 vcc, exec, s[12:13]
	v_lshl_add_u64 v[76:77], s[22:23], 0, v[72:73]
	s_cbranch_vccnz .LBB0_238
	v_mov_b32_e32 v149, v173
	v_lshl_add_u64 v[72:73], v[148:149], 1, v[76:77]
	s_nop 1
	v_permlane16_swap_b32_e32 v80, v82
	v_permlane16_swap_b32_e32 v81, v83
	v_lshl_add_u64 v[244:245], v[72:73], 0, v[254:255]
	global_store_dwordx4 v[244:245], v[80:83], off

.LBB0_243:
	s_or_b64 exec, exec, s[20:21]
	v_and_b32_e32 v89, 0x5c, v148
	v_ashrrev_i32_e32 v153, 31, v152
	v_lshl_add_u64 v[78:79], v[152:153], 2, v[78:79]
	v_lshlrev_b32_e32 v172, 1, v89
	v_lshl_add_u64 v[84:85], v[84:85], 0, v[172:173]
	global_store_dwordx4 v[78:79], v[56:59], off
	global_store_dwordx4 v[78:79], v[60:63], off offset:128
	s_nop 1
	v_permlane16_swap_b32_e32 v80, v82
	v_permlane16_swap_b32_e32 v81, v83
	v_lshl_add_u64 v[244:245], v[84:85], 0, v[254:255]
	global_store_dwordx4 v[244:245], v[80:83], off
.LBB0_244:
	v_pk_mul_f32 v[56:57], v[50:51], v[66:67]
	v_pk_mul_f32 v[58:59], v[48:49], v[64:65]
	v_pk_mul_f32 v[50:51], v[50:51], v[70:71]
	v_pk_mul_f32 v[48:49], v[48:49], v[68:69]
	v_pk_fma_f32 v[56:57], v[54:55], v[70:71], v[56:57] neg_lo:[0,0,1] neg_hi:[0,0,1]
	v_pk_fma_f32 v[58:59], v[52:53], v[68:69], v[58:59] neg_lo:[0,0,1] neg_hi:[0,0,1]
	v_pk_fma_f32 v[54:55], v[54:55], v[66:67], v[50:51]
	v_pk_fma_f32 v[52:53], v[52:53], v[64:65], v[48:49]
	v_pk_mul_f32 v[48:49], v[58:59], s[80:81] op_sel_hi:[1,0]
	v_pk_mul_f32 v[50:51], v[56:57], s[80:81] op_sel_hi:[1,0]
	v_pk_mul_f32 v[60:61], v[52:53], s[80:81] op_sel_hi:[1,0]
	v_pk_mul_f32 v[62:63], v[54:55], s[80:81] op_sel_hi:[1,0]
	v_cndmask_b32_e64 v51, v57, v51, s[10:11]
	v_cndmask_b32_e64 v50, v56, v50, s[10:11]
	v_cndmask_b32_e64 v49, v59, v49, s[10:11]
	v_cndmask_b32_e64 v48, v58, v48, s[10:11]
	v_cndmask_b32_e64 v55, v55, v63, s[10:11]
	v_cndmask_b32_e64 v54, v54, v62, s[10:11]
	v_cndmask_b32_e64 v53, v53, v61, s[10:11]
	v_cndmask_b32_e64 v52, v52, v60, s[10:11]
	v_cvt_pk_bf16_f32 v56, v48, v49
	v_cvt_pk_bf16_f32 v57, v50, v51
	v_cvt_pk_bf16_f32 v58, v52, v53
	s_and_b64 vcc, exec, s[12:13]
	v_cvt_pk_bf16_f32 v59, v54, v55
	s_cbranch_vccnz .LBB0_246
	v_mov_b32_e32 v149, v173
	v_lshl_add_u64 v[60:61], v[148:149], 1, v[76:77]
	s_nop 1
	v_permlane16_swap_b32_e32 v56, v58
	v_permlane16_swap_b32_e32 v57, v59
	v_lshl_add_u64 v[244:245], v[60:61], 0, v[254:255]
	global_store_dwordx4 v[244:245], v[56:59], off offset:256

.LBB0_251:
	s_or_b64 exec, exec, s[18:19]
	v_ashrrev_i32_e32 v65, 31, v148
	v_subrev_co_u32_e32 v64, vcc, s29, v148
	v_and_b32_e32 v66, 0x5c, v148
	s_nop 0
	v_subbrev_co_u32_e32 v65, vcc, 0, v65, vcc
	v_lshl_add_u64 v[60:61], v[64:65], 2, v[60:61]
	v_lshlrev_b32_e32 v172, 1, v66
	v_lshl_add_u64 v[62:63], v[62:63], 0, v[172:173]
	global_store_dwordx4 v[60:61], v[48:51], off offset:512
	global_store_dwordx4 v[60:61], v[52:55], off offset:640
	s_nop 1
	v_permlane16_swap_b32_e32 v56, v58
	v_permlane16_swap_b32_e32 v57, v59
	v_lshl_add_u64 v[244:245], v[62:63], 0, v[254:255]
	global_store_dwordx4 v[244:245], v[56:59], off

.LBB0_255:
	s_waitcnt vmcnt(0)
	v_pk_mul_f32 v[58:59], v[42:43], v[50:51]
	v_pk_mul_f32 v[60:61], v[40:41], v[48:49]
	v_pk_mul_f32 v[42:43], v[42:43], v[54:55]
	v_pk_mul_f32 v[40:41], v[40:41], v[52:53]
	v_pk_fma_f32 v[58:59], v[46:47], v[54:55], v[58:59] neg_lo:[0,0,1] neg_hi:[0,0,1]
	v_pk_fma_f32 v[60:61], v[44:45], v[52:53], v[60:61] neg_lo:[0,0,1] neg_hi:[0,0,1]
	v_pk_fma_f32 v[46:47], v[46:47], v[50:51], v[42:43]
	v_pk_fma_f32 v[44:45], v[44:45], v[48:49], v[40:41]
	v_ashrrev_i32_e32 v63, 31, v62
	v_pk_mul_f32 v[42:43], v[58:59], s[80:81] op_sel_hi:[1,0]
	v_pk_mul_f32 v[40:41], v[60:61], s[80:81] op_sel_hi:[1,0]
	v_pk_mul_f32 v[64:65], v[46:47], s[80:81] op_sel_hi:[1,0]
	v_pk_mul_f32 v[66:67], v[44:45], s[80:81] op_sel_hi:[1,0]
	v_lshlrev_b64 v[56:57], 13, v[62:63]
	v_cndmask_b32_e64 v41, v61, v41, s[10:11]
	v_cndmask_b32_e64 v40, v60, v40, s[10:11]
	v_cndmask_b32_e64 v43, v59, v43, s[10:11]
	v_cndmask_b32_e64 v42, v58, v42, s[10:11]
	v_cndmask_b32_e64 v45, v45, v67, s[10:11]
	v_cndmask_b32_e64 v44, v44, v66, s[10:11]
	v_cndmask_b32_e64 v47, v47, v65, s[10:11]
	v_cndmask_b32_e64 v46, v46, v64, s[10:11]
	v_cvt_pk_bf16_f32 v64, v40, v41
	v_cvt_pk_bf16_f32 v65, v42, v43
	v_cvt_pk_bf16_f32 v66, v44, v45
	v_cvt_pk_bf16_f32 v67, v46, v47
	s_and_b64 vcc, exec, s[12:13]
	v_lshl_add_u64 v[60:61], s[22:23], 0, v[56:57]
	s_cbranch_vccnz .LBB0_257
	v_mov_b32_e32 v149, v173
	v_lshl_add_u64 v[56:57], v[148:149], 1, v[60:61]
	s_nop 1
	v_permlane16_swap_b32_e32 v64, v66
	v_permlane16_swap_b32_e32 v65, v67
	v_lshl_add_u64 v[244:245], v[56:57], 0, v[254:255]
	global_store_dwordx4 v[244:245], v[64:67], off

.LBB0_262:
	s_or_b64 exec, exec, s[20:21]
	v_and_b32_e32 v72, 0x5c, v148
	v_ashrrev_i32_e32 v153, 31, v152
	v_lshl_add_u64 v[62:63], v[152:153], 2, v[62:63]
	v_lshlrev_b32_e32 v172, 1, v72
	v_lshl_add_u64 v[68:69], v[68:69], 0, v[172:173]
	global_store_dwordx4 v[62:63], v[40:43], off
	global_store_dwordx4 v[62:63], v[44:47], off offset:128
	s_nop 1
	v_permlane16_swap_b32_e32 v64, v66
	v_permlane16_swap_b32_e32 v65, v67
	v_lshl_add_u64 v[244:245], v[68:69], 0, v[254:255]
	global_store_dwordx4 v[244:245], v[64:67], off
.LBB0_263:
	v_pk_mul_f32 v[40:41], v[34:35], v[50:51]
	v_pk_mul_f32 v[42:43], v[32:33], v[48:49]
	v_pk_mul_f32 v[34:35], v[34:35], v[54:55]
	v_pk_mul_f32 v[32:33], v[32:33], v[52:53]
	v_pk_fma_f32 v[40:41], v[38:39], v[54:55], v[40:41] neg_lo:[0,0,1] neg_hi:[0,0,1]
	v_pk_fma_f32 v[42:43], v[36:37], v[52:53], v[42:43] neg_lo:[0,0,1] neg_hi:[0,0,1]
	v_pk_fma_f32 v[38:39], v[38:39], v[50:51], v[34:35]
	v_pk_fma_f32 v[36:37], v[36:37], v[48:49], v[32:33]
	v_pk_mul_f32 v[32:33], v[42:43], s[80:81] op_sel_hi:[1,0]
	v_pk_mul_f32 v[34:35], v[40:41], s[80:81] op_sel_hi:[1,0]
	v_pk_mul_f32 v[44:45], v[36:37], s[80:81] op_sel_hi:[1,0]
	v_pk_mul_f32 v[46:47], v[38:39], s[80:81] op_sel_hi:[1,0]
	v_cndmask_b32_e64 v35, v41, v35, s[10:11]
	v_cndmask_b32_e64 v34, v40, v34, s[10:11]
	v_cndmask_b32_e64 v33, v43, v33, s[10:11]
	v_cndmask_b32_e64 v32, v42, v32, s[10:11]
	v_cndmask_b32_e64 v39, v39, v47, s[10:11]
	v_cndmask_b32_e64 v38, v38, v46, s[10:11]
	v_cndmask_b32_e64 v37, v37, v45, s[10:11]
	v_cndmask_b32_e64 v36, v36, v44, s[10:11]
	v_cvt_pk_bf16_f32 v40, v32, v33
	v_cvt_pk_bf16_f32 v41, v34, v35
	v_cvt_pk_bf16_f32 v42, v36, v37
	s_and_b64 vcc, exec, s[12:13]
	v_cvt_pk_bf16_f32 v43, v38, v39
	s_cbranch_vccnz .LBB0_265
	v_mov_b32_e32 v149, v173
	v_lshl_add_u64 v[44:45], v[148:149], 1, v[60:61]
	s_nop 1
	v_permlane16_swap_b32_e32 v40, v42
	v_permlane16_swap_b32_e32 v41, v43
	v_lshl_add_u64 v[244:245], v[44:45], 0, v[254:255]
	global_store_dwordx4 v[244:245], v[40:43], off offset:256

.LBB0_270:
	s_or_b64 exec, exec, s[18:19]
	v_ashrrev_i32_e32 v49, 31, v148
	v_subrev_co_u32_e32 v48, vcc, s29, v148
	v_and_b32_e32 v50, 0x5c, v148
	s_nop 0
	v_subbrev_co_u32_e32 v49, vcc, 0, v49, vcc
	v_lshl_add_u64 v[44:45], v[48:49], 2, v[44:45]
	v_lshlrev_b32_e32 v172, 1, v50
	v_lshl_add_u64 v[46:47], v[46:47], 0, v[172:173]
	global_store_dwordx4 v[44:45], v[32:35], off offset:512
	global_store_dwordx4 v[44:45], v[36:39], off offset:640
	s_nop 1
	v_permlane16_swap_b32_e32 v40, v42
	v_permlane16_swap_b32_e32 v41, v43
	v_lshl_add_u64 v[244:245], v[46:47], 0, v[254:255]
	global_store_dwordx4 v[244:245], v[40:43], off

.LBB0_274:
	s_waitcnt vmcnt(0)
	v_pk_mul_f32 v[42:43], v[26:27], v[34:35]
	v_pk_mul_f32 v[44:45], v[24:25], v[32:33]
	v_pk_mul_f32 v[26:27], v[26:27], v[38:39]
	v_pk_mul_f32 v[24:25], v[24:25], v[36:37]
	v_pk_fma_f32 v[42:43], v[30:31], v[38:39], v[42:43] neg_lo:[0,0,1] neg_hi:[0,0,1]
	v_pk_fma_f32 v[44:45], v[28:29], v[36:37], v[44:45] neg_lo:[0,0,1] neg_hi:[0,0,1]
	v_pk_fma_f32 v[30:31], v[30:31], v[34:35], v[26:27]
	v_pk_fma_f32 v[28:29], v[28:29], v[32:33], v[24:25]
	v_ashrrev_i32_e32 v47, 31, v46
	v_pk_mul_f32 v[26:27], v[42:43], s[80:81] op_sel_hi:[1,0]
	v_pk_mul_f32 v[24:25], v[44:45], s[80:81] op_sel_hi:[1,0]
	v_pk_mul_f32 v[48:49], v[30:31], s[80:81] op_sel_hi:[1,0]
	v_pk_mul_f32 v[50:51], v[28:29], s[80:81] op_sel_hi:[1,0]
	v_lshlrev_b64 v[40:41], 13, v[46:47]
	v_cndmask_b32_e64 v25, v45, v25, s[10:11]
	v_cndmask_b32_e64 v24, v44, v24, s[10:11]
	v_cndmask_b32_e64 v27, v43, v27, s[10:11]
	v_cndmask_b32_e64 v26, v42, v26, s[10:11]
	v_cndmask_b32_e64 v29, v29, v51, s[10:11]
	v_cndmask_b32_e64 v28, v28, v50, s[10:11]
	v_cndmask_b32_e64 v31, v31, v49, s[10:11]
	v_cndmask_b32_e64 v30, v30, v48, s[10:11]
	v_cvt_pk_bf16_f32 v48, v24, v25
	v_cvt_pk_bf16_f32 v49, v26, v27
	v_cvt_pk_bf16_f32 v50, v28, v29
	v_cvt_pk_bf16_f32 v51, v30, v31
	s_and_b64 vcc, exec, s[12:13]
	v_lshl_add_u64 v[44:45], s[22:23], 0, v[40:41]
	s_cbranch_vccnz .LBB0_276
	v_mov_b32_e32 v149, v173
	v_lshl_add_u64 v[40:41], v[148:149], 1, v[44:45]
	s_nop 1
	v_permlane16_swap_b32_e32 v48, v50
	v_permlane16_swap_b32_e32 v49, v51
	v_lshl_add_u64 v[244:245], v[40:41], 0, v[254:255]
	global_store_dwordx4 v[244:245], v[48:51], off

.LBB0_281:
	s_or_b64 exec, exec, s[20:21]
	v_and_b32_e32 v56, 0x5c, v148
	v_ashrrev_i32_e32 v153, 31, v152
	v_lshl_add_u64 v[46:47], v[152:153], 2, v[46:47]
	v_lshlrev_b32_e32 v172, 1, v56
	v_lshl_add_u64 v[52:53], v[52:53], 0, v[172:173]
	global_store_dwordx4 v[46:47], v[24:27], off
	global_store_dwordx4 v[46:47], v[28:31], off offset:128
	s_nop 1
	v_permlane16_swap_b32_e32 v48, v50
	v_permlane16_swap_b32_e32 v49, v51
	v_lshl_add_u64 v[244:245], v[52:53], 0, v[254:255]
	global_store_dwordx4 v[244:245], v[48:51], off
.LBB0_282:
	v_pk_mul_f32 v[24:25], v[18:19], v[34:35]
	v_pk_mul_f32 v[26:27], v[16:17], v[32:33]
	v_pk_mul_f32 v[18:19], v[18:19], v[38:39]
	v_pk_mul_f32 v[16:17], v[16:17], v[36:37]
	v_pk_fma_f32 v[24:25], v[22:23], v[38:39], v[24:25] neg_lo:[0,0,1] neg_hi:[0,0,1]
	v_pk_fma_f32 v[26:27], v[20:21], v[36:37], v[26:27] neg_lo:[0,0,1] neg_hi:[0,0,1]
	v_pk_fma_f32 v[22:23], v[22:23], v[34:35], v[18:19]
	v_pk_fma_f32 v[20:21], v[20:21], v[32:33], v[16:17]
	v_pk_mul_f32 v[16:17], v[26:27], s[80:81] op_sel_hi:[1,0]
	v_pk_mul_f32 v[18:19], v[24:25], s[80:81] op_sel_hi:[1,0]
	v_pk_mul_f32 v[28:29], v[20:21], s[80:81] op_sel_hi:[1,0]
	v_pk_mul_f32 v[30:31], v[22:23], s[80:81] op_sel_hi:[1,0]
	v_cndmask_b32_e64 v19, v25, v19, s[10:11]
	v_cndmask_b32_e64 v18, v24, v18, s[10:11]
	v_cndmask_b32_e64 v17, v27, v17, s[10:11]
	v_cndmask_b32_e64 v16, v26, v16, s[10:11]
	v_cndmask_b32_e64 v23, v23, v31, s[10:11]
	v_cndmask_b32_e64 v22, v22, v30, s[10:11]
	v_cndmask_b32_e64 v21, v21, v29, s[10:11]
	v_cndmask_b32_e64 v20, v20, v28, s[10:11]
	v_cvt_pk_bf16_f32 v24, v16, v17
	v_cvt_pk_bf16_f32 v25, v18, v19
	v_cvt_pk_bf16_f32 v26, v20, v21
	s_and_b64 vcc, exec, s[12:13]
	v_cvt_pk_bf16_f32 v27, v22, v23
	s_cbranch_vccnz .LBB0_284
	v_mov_b32_e32 v149, v173
	v_lshl_add_u64 v[28:29], v[148:149], 1, v[44:45]
	s_nop 1
	v_permlane16_swap_b32_e32 v24, v26
	v_permlane16_swap_b32_e32 v25, v27
	v_lshl_add_u64 v[244:245], v[28:29], 0, v[254:255]
	global_store_dwordx4 v[244:245], v[24:27], off offset:256

.LBB0_289:
	s_or_b64 exec, exec, s[18:19]
	v_ashrrev_i32_e32 v33, 31, v148
	v_subrev_co_u32_e32 v32, vcc, s29, v148
	v_and_b32_e32 v34, 0x5c, v148
	s_nop 0
	v_subbrev_co_u32_e32 v33, vcc, 0, v33, vcc
	v_lshl_add_u64 v[28:29], v[32:33], 2, v[28:29]
	v_lshlrev_b32_e32 v172, 1, v34
	v_lshl_add_u64 v[30:31], v[30:31], 0, v[172:173]
	global_store_dwordx4 v[28:29], v[16:19], off offset:512
	global_store_dwordx4 v[28:29], v[20:23], off offset:640
	s_nop 1
	v_permlane16_swap_b32_e32 v24, v26
	v_permlane16_swap_b32_e32 v25, v27
	v_lshl_add_u64 v[244:245], v[30:31], 0, v[254:255]
	global_store_dwordx4 v[244:245], v[24:27], off

.LBB0_301:
	v_pk_mul_f32 v[8:9], v[2:3], v[18:19]
	v_pk_mul_f32 v[10:11], v[0:1], v[16:17]
	v_pk_mul_f32 v[2:3], v[2:3], v[22:23]
	v_pk_mul_f32 v[0:1], v[0:1], v[20:21]
	v_pk_fma_f32 v[8:9], v[6:7], v[22:23], v[8:9] neg_lo:[0,0,1] neg_hi:[0,0,1]
	v_pk_fma_f32 v[10:11], v[4:5], v[20:21], v[10:11] neg_lo:[0,0,1] neg_hi:[0,0,1]
	v_pk_fma_f32 v[6:7], v[6:7], v[18:19], v[2:3]
	v_pk_fma_f32 v[4:5], v[4:5], v[16:17], v[0:1]
	v_pk_mul_f32 v[0:1], v[10:11], s[80:81] op_sel_hi:[1,0]
	v_pk_mul_f32 v[2:3], v[8:9], s[80:81] op_sel_hi:[1,0]
	v_pk_mul_f32 v[12:13], v[4:5], s[80:81] op_sel_hi:[1,0]
	v_pk_mul_f32 v[14:15], v[6:7], s[80:81] op_sel_hi:[1,0]
	v_cndmask_b32_e64 v3, v9, v3, s[10:11]
	v_cndmask_b32_e64 v2, v8, v2, s[10:11]
	v_cndmask_b32_e64 v1, v11, v1, s[10:11]
	v_cndmask_b32_e64 v0, v10, v0, s[10:11]
	v_cndmask_b32_e64 v7, v7, v15, s[10:11]
	v_cndmask_b32_e64 v6, v6, v14, s[10:11]
	v_cndmask_b32_e64 v5, v5, v13, s[10:11]
	v_cndmask_b32_e64 v4, v4, v12, s[10:11]
	v_cvt_pk_bf16_f32 v8, v0, v1
	v_cvt_pk_bf16_f32 v9, v2, v3
	v_cvt_pk_bf16_f32 v10, v4, v5
	s_and_b64 vcc, exec, s[12:13]
	v_cvt_pk_bf16_f32 v11, v6, v7
	s_cbranch_vccnz .LBB0_303
	v_mov_b32_e32 v149, v173
	v_lshl_add_u64 v[12:13], v[148:149], 1, v[28:29]
	s_nop 1
	v_permlane16_swap_b32_e32 v8, v10
	v_permlane16_swap_b32_e32 v9, v11
	v_lshl_add_u64 v[244:245], v[12:13], 0, v[254:255]
	global_store_dwordx4 v[244:245], v[8:11], off offset:256

.LBB0_323:
	s_add_u32 s14, s12, 0xfffc0080
	s_addc_u32 s15, s13, -1
	s_add_i32 s55, 0, 0x10000
	v_add_u32_e32 v144, s55, v146
	ds_read_b128 v[136:139], v144
	ds_read_b128 v[140:143], v144 offset:1024
	ds_read_b128 v[150:153], v144 offset:2048
	ds_read_b128 v[154:157], v144 offset:3072
	s_cmp_eq_u32 s54, 12
	s_cselect_b32 s35, s9, s15
	s_cselect_b32 s34, s11, s14
	s_cselect_b32 s15, s25, s53
	s_cselect_b32 s14, s27, s52
	v_lshl_add_u64 v[144:145], s[12:13], 0, v[132:133]
	s_add_i32 m0, s44, 0xc000
	ds_read_b128 v[158:161], v148
	ds_read_b128 v[162:165], v148 offset:1024
	ds_read_b128 v[166:169], v148 offset:2048
	ds_read_b128 v[182:185], v148 offset:3072
	ds_read_b128 v[186:189], v148 offset:4096
	ds_read_b128 v[190:193], v148 offset:5120
	ds_read_b128 v[194:197], v148 offset:6144
	ds_read_b128 v[198:201], v148 offset:7168
	global_load_lds_dwordx4 v[144:145], off
	v_lshl_add_u64 v[144:145], s[12:13], 0, v[134:135]
	s_add_i32 m0, s44, 0xe000
	s_nop 0
	global_load_lds_dwordx4 v[144:145], off
	s_waitcnt lgkmcnt(8)
	s_barrier
	s_waitcnt lgkmcnt(0)
	s_setprio 1
	s_waitcnt lgkmcnt(0)
	v_mfma_f32_16x16x32_bf16 v[124:127], v[136:139], v[158:161], v[124:127]
	v_mfma_f32_16x16x32_bf16 v[120:123], v[150:153], v[158:161], v[120:123]
	v_mfma_f32_16x16x32_bf16 v[108:111], v[136:139], v[166:169], v[108:111]
	v_mfma_f32_16x16x32_bf16 v[104:107], v[150:153], v[166:169], v[104:107]
	v_mfma_f32_16x16x32_bf16 v[92:95], v[136:139], v[186:189], v[92:95]
	v_mfma_f32_16x16x32_bf16 v[88:91], v[150:153], v[186:189], v[88:91]
	v_mfma_f32_16x16x32_bf16 v[76:79], v[136:139], v[194:197], v[76:79]
	v_mfma_f32_16x16x32_bf16 v[72:75], v[150:153], v[194:197], v[72:75]
	v_mfma_f32_16x16x32_bf16 v[124:127], v[140:143], v[162:165], v[124:127]
	v_mfma_f32_16x16x32_bf16 v[120:123], v[154:157], v[162:165], v[120:123]
	v_mfma_f32_16x16x32_bf16 v[108:111], v[140:143], v[182:185], v[108:111]
	v_mfma_f32_16x16x32_bf16 v[104:107], v[154:157], v[182:185], v[104:107]
	v_mfma_f32_16x16x32_bf16 v[92:95], v[140:143], v[190:193], v[92:95]
	v_mfma_f32_16x16x32_bf16 v[88:91], v[154:157], v[190:193], v[88:91]
	v_mfma_f32_16x16x32_bf16 v[76:79], v[140:143], v[198:201], v[76:79]
	v_mfma_f32_16x16x32_bf16 v[72:75], v[154:157], v[198:201], v[72:75]
	s_setprio 0
	s_barrier
	s_add_i32 s62, 0, 0x14000
	v_add_u32_e32 v144, s62, v146
	s_add_i32 s55, s55, s39
	ds_read_b128 v[202:205], v144
	ds_read_b128 v[206:209], v144 offset:1024
	ds_read_b128 v[210:213], v144 offset:2048
	ds_read_b128 v[230:233], v144 offset:3072
	v_lshl_add_u64 v[144:145], s[14:15], 0, v[172:173]
	s_mov_b32 m0, s55
	v_lshl_add_u64 v[170:171], s[14:15], 0, v[128:129]
	global_load_lds_dwordx4 v[144:145], off
	s_add_i32 m0, s55, 0x2000
	s_nop 0
	global_load_lds_dwordx4 v[170:171], off
	s_barrier
	s_waitcnt lgkmcnt(0)
	s_setprio 1
	s_waitcnt lgkmcnt(0)
	v_mfma_f32_16x16x32_bf16 v[116:119], v[202:205], v[158:161], v[116:119]
	v_mfma_f32_16x16x32_bf16 v[112:115], v[210:213], v[158:161], v[112:115]
	v_mfma_f32_16x16x32_bf16 v[100:103], v[202:205], v[166:169], v[100:103]
	v_mfma_f32_16x16x32_bf16 v[96:99], v[210:213], v[166:169], v[96:99]
	v_mfma_f32_16x16x32_bf16 v[84:87], v[202:205], v[186:189], v[84:87]
	v_mfma_f32_16x16x32_bf16 v[80:83], v[210:213], v[186:189], v[80:83]
	v_mfma_f32_16x16x32_bf16 v[68:71], v[202:205], v[194:197], v[68:71]
	v_mfma_f32_16x16x32_bf16 v[64:67], v[210:213], v[194:197], v[64:67]
	v_mfma_f32_16x16x32_bf16 v[116:119], v[206:209], v[162:165], v[116:119]
	v_mfma_f32_16x16x32_bf16 v[112:115], v[230:233], v[162:165], v[112:115]
	v_mfma_f32_16x16x32_bf16 v[100:103], v[206:209], v[182:185], v[100:103]
	v_mfma_f32_16x16x32_bf16 v[96:99], v[230:233], v[182:185], v[96:99]
	v_mfma_f32_16x16x32_bf16 v[84:87], v[206:209], v[190:193], v[84:87]
	v_mfma_f32_16x16x32_bf16 v[80:83], v[230:233], v[190:193], v[80:83]
	v_mfma_f32_16x16x32_bf16 v[68:71], v[206:209], v[198:201], v[68:71]
	v_mfma_f32_16x16x32_bf16 v[64:67], v[230:233], v[198:201], v[64:67]
	s_setprio 0
	s_mov_b32 m0, s44
	v_lshl_add_u64 v[234:235], s[34:35], 0, v[172:173]
	s_barrier
	ds_read_b128 v[158:161], v148 offset:16384
	ds_read_b128 v[162:165], v148 offset:17408
	ds_read_b128 v[166:169], v148 offset:18432
	ds_read_b128 v[182:185], v148 offset:19456
	ds_read_b128 v[186:189], v148 offset:20480
	ds_read_b128 v[190:193], v148 offset:21504
	ds_read_b128 v[194:197], v148 offset:22528
	ds_read_b128 v[198:201], v148 offset:23552
	global_load_lds_dwordx4 v[234:235], off
	v_lshl_add_u64 v[236:237], s[34:35], 0, v[128:129]
	s_mov_b32 m0, s45
	s_nop 0
	global_load_lds_dwordx4 v[236:237], off
	s_barrier
	s_waitcnt lgkmcnt(0)
	s_setprio 1
	s_waitcnt lgkmcnt(0)
	v_mfma_f32_16x16x32_bf16 v[60:63], v[136:139], v[158:161], v[60:63]
	v_mfma_f32_16x16x32_bf16 v[56:59], v[150:153], v[158:161], v[56:59]
	v_mfma_f32_16x16x32_bf16 v[44:47], v[136:139], v[166:169], v[44:47]
	v_mfma_f32_16x16x32_bf16 v[40:43], v[150:153], v[166:169], v[40:43]
	v_mfma_f32_16x16x32_bf16 v[28:31], v[136:139], v[186:189], v[28:31]
	v_mfma_f32_16x16x32_bf16 v[24:27], v[150:153], v[186:189], v[24:27]
	v_mfma_f32_16x16x32_bf16 v[12:15], v[136:139], v[194:197], v[12:15]
	v_mfma_f32_16x16x32_bf16 v[8:11], v[150:153], v[194:197], v[8:11]
	v_mfma_f32_16x16x32_bf16 v[60:63], v[140:143], v[162:165], v[60:63]
	v_mfma_f32_16x16x32_bf16 v[56:59], v[154:157], v[162:165], v[56:59]
	v_mfma_f32_16x16x32_bf16 v[44:47], v[140:143], v[182:185], v[44:47]
	v_mfma_f32_16x16x32_bf16 v[40:43], v[154:157], v[182:185], v[40:43]
	v_mfma_f32_16x16x32_bf16 v[28:31], v[140:143], v[190:193], v[28:31]
	v_mfma_f32_16x16x32_bf16 v[24:27], v[154:157], v[190:193], v[24:27]
	v_mfma_f32_16x16x32_bf16 v[12:15], v[140:143], v[198:201], v[12:15]
	v_mfma_f32_16x16x32_bf16 v[8:11], v[154:157], v[198:201], v[8:11]
	s_setprio 0
	s_barrier
	s_add_u32 s58, s14, 0x40000
	s_addc_u32 s59, s15, 0
	s_add_i32 s55, s62, s39
	v_lshl_add_u64 v[136:137], s[58:59], 0, v[172:173]
	s_mov_b32 m0, s55
	s_nop 0
	global_load_lds_dwordx4 v[136:137], off
	v_lshl_add_u64 v[136:137], s[58:59], 0, v[128:129]
	s_add_i32 m0, s55, 0x2000
	s_nop 0
	global_load_lds_dwordx4 v[136:137], off
	s_waitcnt vmcnt(6)
	s_barrier
	s_setprio 1
	v_mfma_f32_16x16x32_bf16 v[52:55], v[202:205], v[158:161], v[52:55]
	v_mfma_f32_16x16x32_bf16 v[48:51], v[210:213], v[158:161], v[48:51]
	v_mfma_f32_16x16x32_bf16 v[36:39], v[202:205], v[166:169], v[36:39]
	v_mfma_f32_16x16x32_bf16 v[32:35], v[210:213], v[166:169], v[32:35]
	v_mfma_f32_16x16x32_bf16 v[20:23], v[202:205], v[186:189], v[20:23]
	v_mfma_f32_16x16x32_bf16 v[16:19], v[210:213], v[186:189], v[16:19]
	v_mfma_f32_16x16x32_bf16 v[4:7], v[202:205], v[194:197], v[4:7]
	v_mfma_f32_16x16x32_bf16 v[0:3], v[210:213], v[194:197], v[0:3]
	v_mfma_f32_16x16x32_bf16 v[52:55], v[206:209], v[162:165], v[52:55]
	v_mfma_f32_16x16x32_bf16 v[48:51], v[230:233], v[162:165], v[48:51]
	v_mfma_f32_16x16x32_bf16 v[36:39], v[206:209], v[182:185], v[36:39]
	v_mfma_f32_16x16x32_bf16 v[32:35], v[230:233], v[182:185], v[32:35]
	v_mfma_f32_16x16x32_bf16 v[20:23], v[206:209], v[190:193], v[20:23]
	v_mfma_f32_16x16x32_bf16 v[16:19], v[230:233], v[190:193], v[16:19]
	v_mfma_f32_16x16x32_bf16 v[4:7], v[206:209], v[198:201], v[4:7]
	v_mfma_f32_16x16x32_bf16 v[0:3], v[230:233], v[198:201], v[0:3]
	s_setprio 0
	s_add_i32 s55, 0, 0x18000
	v_add_u32_e32 v149, s55, v146
	s_barrier
	ds_read_b128 v[136:139], v149
	ds_read_b128 v[140:143], v149 offset:1024
	ds_read_b128 v[150:153], v149 offset:2048
	ds_read_b128 v[154:157], v149 offset:3072
	s_add_u32 s34, s34, 0x40000
	s_addc_u32 s35, s35, 0
	s_mov_b32 m0, s46
	v_lshl_add_u64 v[202:203], s[34:35], 0, v[172:173]
	ds_read_b128 v[158:161], v148 offset:32768
	ds_read_b128 v[162:165], v148 offset:33792
	ds_read_b128 v[166:169], v148 offset:34816
	ds_read_b128 v[182:185], v148 offset:35840
	ds_read_b128 v[186:189], v148 offset:36864
	ds_read_b128 v[190:193], v148 offset:37888
	ds_read_b128 v[194:197], v148 offset:38912
	ds_read_b128 v[198:201], v148 offset:39936
	global_load_lds_dwordx4 v[202:203], off
	v_lshl_add_u64 v[202:203], s[34:35], 0, v[128:129]
	s_mov_b32 m0, s47
	s_nop 0
	global_load_lds_dwordx4 v[202:203], off
	s_waitcnt lgkmcnt(8)
	s_barrier
	s_waitcnt lgkmcnt(0)
	s_setprio 1
	s_waitcnt lgkmcnt(0)
	v_mfma_f32_16x16x32_bf16 v[124:127], v[136:139], v[158:161], v[124:127]
	v_mfma_f32_16x16x32_bf16 v[120:123], v[150:153], v[158:161], v[120:123]
	v_mfma_f32_16x16x32_bf16 v[108:111], v[136:139], v[166:169], v[108:111]
	v_mfma_f32_16x16x32_bf16 v[104:107], v[150:153], v[166:169], v[104:107]
	v_mfma_f32_16x16x32_bf16 v[92:95], v[136:139], v[186:189], v[92:95]
	v_mfma_f32_16x16x32_bf16 v[88:91], v[150:153], v[186:189], v[88:91]
	v_mfma_f32_16x16x32_bf16 v[76:79], v[136:139], v[194:197], v[76:79]
	v_mfma_f32_16x16x32_bf16 v[72:75], v[150:153], v[194:197], v[72:75]
	v_mfma_f32_16x16x32_bf16 v[124:127], v[140:143], v[162:165], v[124:127]
	v_mfma_f32_16x16x32_bf16 v[120:123], v[154:157], v[162:165], v[120:123]
	v_mfma_f32_16x16x32_bf16 v[108:111], v[140:143], v[182:185], v[108:111]
	v_mfma_f32_16x16x32_bf16 v[104:107], v[154:157], v[182:185], v[104:107]
	v_mfma_f32_16x16x32_bf16 v[92:95], v[140:143], v[190:193], v[92:95]
	v_mfma_f32_16x16x32_bf16 v[88:91], v[154:157], v[190:193], v[88:91]
	v_mfma_f32_16x16x32_bf16 v[76:79], v[140:143], v[198:201], v[76:79]
	v_mfma_f32_16x16x32_bf16 v[72:75], v[154:157], v[198:201], v[72:75]
	s_setprio 0
	s_barrier
	s_add_i32 s34, 0, 0x1c000
	s_add_i32 s35, s55, s39
	v_add_u32_e32 v149, s34, v146
	v_lshl_add_u64 v[144:145], v[144:145], 0, s[78:79]
	s_mov_b32 m0, s35
	ds_read_b128 v[202:205], v149
	ds_read_b128 v[206:209], v149 offset:1024
	ds_read_b128 v[210:213], v149 offset:2048
	ds_read_b128 v[230:233], v149 offset:3072
	global_load_lds_dwordx4 v[144:145], off
	v_lshl_add_u64 v[144:145], v[170:171], 0, s[78:79]
	s_add_i32 m0, s35, 0x2000
	s_nop 0
	global_load_lds_dwordx4 v[144:145], off
	s_barrier
	s_waitcnt lgkmcnt(0)
	s_setprio 1
	s_waitcnt lgkmcnt(0)
	v_mfma_f32_16x16x32_bf16 v[116:119], v[202:205], v[158:161], v[116:119]
	v_mfma_f32_16x16x32_bf16 v[112:115], v[210:213], v[158:161], v[112:115]
	v_mfma_f32_16x16x32_bf16 v[100:103], v[202:205], v[166:169], v[100:103]
	v_mfma_f32_16x16x32_bf16 v[96:99], v[210:213], v[166:169], v[96:99]
	v_mfma_f32_16x16x32_bf16 v[84:87], v[202:205], v[186:189], v[84:87]
	v_mfma_f32_16x16x32_bf16 v[80:83], v[210:213], v[186:189], v[80:83]
	v_mfma_f32_16x16x32_bf16 v[68:71], v[202:205], v[194:197], v[68:71]
	v_mfma_f32_16x16x32_bf16 v[64:67], v[210:213], v[194:197], v[64:67]
	v_mfma_f32_16x16x32_bf16 v[116:119], v[206:209], v[162:165], v[116:119]
	v_mfma_f32_16x16x32_bf16 v[112:115], v[230:233], v[162:165], v[112:115]
	v_mfma_f32_16x16x32_bf16 v[100:103], v[206:209], v[182:185], v[100:103]
	v_mfma_f32_16x16x32_bf16 v[96:99], v[230:233], v[182:185], v[96:99]
	v_mfma_f32_16x16x32_bf16 v[84:87], v[206:209], v[190:193], v[84:87]
	v_mfma_f32_16x16x32_bf16 v[80:83], v[230:233], v[190:193], v[80:83]
	v_mfma_f32_16x16x32_bf16 v[68:71], v[206:209], v[198:201], v[68:71]
	v_mfma_f32_16x16x32_bf16 v[64:67], v[230:233], v[198:201], v[64:67]
	s_setprio 0
	s_mov_b32 m0, s49
	v_lshl_add_u64 v[144:145], v[234:235], 0, s[78:79]
	s_barrier
	ds_read_b128 v[158:161], v148 offset:49152
	ds_read_b128 v[162:165], v148 offset:50176
	ds_read_b128 v[166:169], v148 offset:51200
	ds_read_b128 v[182:185], v148 offset:52224
	ds_read_b128 v[186:189], v148 offset:53248
	ds_read_b128 v[190:193], v148 offset:54272
	ds_read_b128 v[194:197], v148 offset:55296
	ds_read_b128 v[198:201], v148 offset:56320
	global_load_lds_dwordx4 v[144:145], off
	v_lshl_add_u64 v[144:145], v[236:237], 0, s[78:79]
	s_mov_b32 m0, s50
	s_nop 0
	global_load_lds_dwordx4 v[144:145], off
	s_barrier
	s_waitcnt lgkmcnt(0)
	s_setprio 1
	s_waitcnt lgkmcnt(0)
	v_mfma_f32_16x16x32_bf16 v[60:63], v[136:139], v[158:161], v[60:63]
	v_mfma_f32_16x16x32_bf16 v[56:59], v[150:153], v[158:161], v[56:59]
	v_mfma_f32_16x16x32_bf16 v[44:47], v[136:139], v[166:169], v[44:47]
	v_mfma_f32_16x16x32_bf16 v[40:43], v[150:153], v[166:169], v[40:43]
	v_mfma_f32_16x16x32_bf16 v[28:31], v[136:139], v[186:189], v[28:31]
	v_mfma_f32_16x16x32_bf16 v[24:27], v[150:153], v[186:189], v[24:27]
	v_mfma_f32_16x16x32_bf16 v[12:15], v[136:139], v[194:197], v[12:15]
	v_mfma_f32_16x16x32_bf16 v[8:11], v[150:153], v[194:197], v[8:11]
	v_mfma_f32_16x16x32_bf16 v[60:63], v[140:143], v[162:165], v[60:63]
	v_mfma_f32_16x16x32_bf16 v[56:59], v[154:157], v[162:165], v[56:59]
	v_mfma_f32_16x16x32_bf16 v[44:47], v[140:143], v[182:185], v[44:47]
	v_mfma_f32_16x16x32_bf16 v[40:43], v[154:157], v[182:185], v[40:43]
	v_mfma_f32_16x16x32_bf16 v[28:31], v[140:143], v[190:193], v[28:31]
	v_mfma_f32_16x16x32_bf16 v[24:27], v[154:157], v[190:193], v[24:27]
	v_mfma_f32_16x16x32_bf16 v[12:15], v[140:143], v[198:201], v[12:15]
	v_mfma_f32_16x16x32_bf16 v[8:11], v[154:157], v[198:201], v[8:11]
	s_setprio 0
	s_barrier
	s_add_u32 s14, s14, 0x40080
	s_addc_u32 s15, s15, 0
	s_add_i32 s34, s34, s39
	v_lshl_add_u64 v[136:137], s[14:15], 0, v[172:173]
	s_mov_b32 m0, s34
	s_nop 0
	global_load_lds_dwordx4 v[136:137], off
	v_lshl_add_u64 v[136:137], s[14:15], 0, v[128:129]
	s_add_i32 m0, s34, 0x2000
	s_nop 0
	global_load_lds_dwordx4 v[136:137], off
	s_waitcnt vmcnt(6)
	s_barrier
	s_setprio 1
	v_mfma_f32_16x16x32_bf16 v[52:55], v[202:205], v[158:161], v[52:55]
	v_mfma_f32_16x16x32_bf16 v[48:51], v[210:213], v[158:161], v[48:51]
	v_mfma_f32_16x16x32_bf16 v[36:39], v[202:205], v[166:169], v[36:39]
	v_mfma_f32_16x16x32_bf16 v[32:35], v[210:213], v[166:169], v[32:35]
	v_mfma_f32_16x16x32_bf16 v[20:23], v[202:205], v[186:189], v[20:23]
	v_mfma_f32_16x16x32_bf16 v[16:19], v[210:213], v[186:189], v[16:19]
	v_mfma_f32_16x16x32_bf16 v[4:7], v[202:205], v[194:197], v[4:7]
	v_mfma_f32_16x16x32_bf16 v[0:3], v[210:213], v[194:197], v[0:3]
	v_mfma_f32_16x16x32_bf16 v[52:55], v[206:209], v[162:165], v[52:55]
	v_mfma_f32_16x16x32_bf16 v[48:51], v[230:233], v[162:165], v[48:51]
	v_mfma_f32_16x16x32_bf16 v[36:39], v[206:209], v[182:185], v[36:39]
	v_mfma_f32_16x16x32_bf16 v[32:35], v[230:233], v[182:185], v[32:35]
	v_mfma_f32_16x16x32_bf16 v[20:23], v[206:209], v[190:193], v[20:23]
	v_mfma_f32_16x16x32_bf16 v[16:19], v[230:233], v[190:193], v[16:19]
	v_mfma_f32_16x16x32_bf16 v[4:7], v[206:209], v[198:201], v[4:7]
	v_mfma_f32_16x16x32_bf16 v[0:3], v[230:233], v[198:201], v[0:3]
	s_setprio 0
	s_add_i32 s54, s54, 2
	s_add_u32 s12, s12, 0x100
	s_addc_u32 s13, s13, 0
	s_add_u32 s52, s52, 0x100
	s_addc_u32 s53, s53, 0
	s_cmp_gt_u32 s54, 13
	s_barrier
	s_cbranch_scc0 .LBB0_323
	s_lshl_b32 s25, s10, 8
	s_add_i32 s25, s25, s48
	v_or_b32_e32 v136, s25, v131
	v_cmp_lt_i32_e32 vcc, s92, v136
	s_and_saveexec_b64 s[10:11], vcc
	s_xor_b64 s[10:11], exec, s[10:11]
	s_add_i32 s9, s25, 0xffff8000
	s_lshr_b32 s9, s9, 4
	v_mad_u64_u32 v[140:141], s[12:13], s9, 3, v[130:131]
	s_or_saveexec_b64 s[10:11], s[10:11]
	s_ashr_i32 s9, s25, 13
	s_mul_i32 s27, s9, 3
	s_addk_i32 s27, 0xe003
	v_mov_b64_e32 v[144:145], s[20:21]
	s_mov_b64 s[14:15], s[22:23]
	s_xor_b64 exec, exec, s[10:11]
	v_and_b32_e32 v137, 0x1fcf, v136
	v_add_u32_e32 v140, s27, v137
	v_mov_b64_e32 v[144:145], s[18:19]
	s_andn2_b64 s[14:15], s[22:23], exec
	s_or_b64 exec, exec, s[10:11]
	v_lshl_or_b32 v138, s8, 8, v147
	v_ashrrev_i32_e32 v137, 31, v136
	v_mad_i64_i32 v[140:141], s[8:9], v140, s86, v[144:145]
	v_lshlrev_b64 v[142:143], 13, v[136:137]
	s_movk_i32 s8, 0xc00
	v_ashrrev_i32_e32 v139, 31, v138
	v_and_b32_e32 v254, 4, v147
	v_lshl_add_u32 v254, v254, 1, v254
	v_add_u32_e32 v254, v138, v254
	v_mov_b32_e32 v255, 0
	v_lshl_add_u64 v[142:143], s[16:17], 0, v[142:143]
	v_cmp_gt_i32_e32 vcc, s8, v138
	v_lshl_add_u64 v[142:143], v[254:255], 1, v[142:143]
	v_lshl_add_u64 v[140:141], v[138:139], 2, v[140:141]
	v_or_b32_e32 v253, 16, v138
	s_movk_i32 s8, 0xc00
	v_cmp_gt_i32_e64 s[8:9], s8, v253
	v_or_b32_e32 v253, 0x80, v138
	s_movk_i32 s10, 0xc00
	v_cmp_gt_i32_e64 s[10:11], s10, v253
	v_or_b32_e32 v253, 0x90, v138
	s_movk_i32 s12, 0xc00
	v_cmp_gt_i32_e64 s[12:13], s12, v253
	s_and_b64 s[52:53], s[14:15], vcc
	s_and_saveexec_b64 s[34:35], s[52:53]
	s_cbranch_execz .Lgin_g0_u0
	global_store_dwordx4 v[140:141], v[124:127], off
.Lgin_g0_u0:
	s_or_b64 exec, exec, s[34:35]
	s_and_b64 s[52:53], s[14:15], s[8:9]
	s_and_saveexec_b64 s[34:35], s[52:53]
	s_cbranch_execz .Lgin_g0_u1
	global_store_dwordx4 v[140:141], v[120:123], off offset:64
.Lgin_g0_u1:
	s_or_b64 exec, exec, s[34:35]
	s_nop 0
	v_cvt_pk_bf16_f32 v124, v124, v125
	v_cvt_pk_bf16_f32 v125, v126, v127
	v_cvt_pk_bf16_f32 v126, v120, v121
	v_cvt_pk_bf16_f32 v127, v122, v123
	s_nop 1
	v_permlane16_swap_b32_e32 v124, v126
	v_permlane16_swap_b32_e32 v125, v127
	global_store_dwordx4 v[142:143], v[124:127], off
	s_and_b64 s[52:53], s[14:15], s[10:11]
	s_and_saveexec_b64 s[34:35], s[52:53]
	s_cbranch_execz .Lgin_g0_u2
	global_store_dwordx4 v[140:141], v[116:119], off offset:512
.Lgin_g0_u2:
	s_or_b64 exec, exec, s[34:35]
	s_and_b64 s[52:53], s[14:15], s[12:13]
	s_and_saveexec_b64 s[34:35], s[52:53]
	s_cbranch_execz .Lgin_g0_u3
	global_store_dwordx4 v[140:141], v[112:115], off offset:576
.Lgin_g0_u3:
	s_or_b64 exec, exec, s[34:35]
	s_nop 0
	v_cvt_pk_bf16_f32 v116, v116, v117
	v_cvt_pk_bf16_f32 v117, v118, v119
	v_cvt_pk_bf16_f32 v118, v112, v113
	v_cvt_pk_bf16_f32 v119, v114, v115
	s_nop 1
	v_permlane16_swap_b32_e32 v116, v118
	v_permlane16_swap_b32_e32 v117, v119
	global_store_dwordx4 v[142:143], v[116:119], off offset:256
	s_nop 0
	v_or_b32_e32 v112, 16, v136
	v_cmp_lt_i32_e64 s[14:15], s92, v112
	s_and_saveexec_b64 s[34:35], s[14:15]
	s_xor_b64 s[14:15], exec, s[34:35]
	s_add_i32 s34, s25, 0xffff8010
	s_lshr_b32 s34, s34, 4
	v_mad_u64_u32 v[114:115], s[34:35], s34, 3, v[130:131]
	s_or_saveexec_b64 s[34:35], s[14:15]
	v_mov_b64_e32 v[116:117], s[20:21]
	s_mov_b64 s[14:15], s[22:23]
	s_xor_b64 exec, exec, s[34:35]
	v_and_b32_e32 v113, 0x1fdf, v112
	v_add_u32_e32 v114, s27, v113
	v_mov_b64_e32 v[116:117], s[18:19]
	s_andn2_b64 s[14:15], s[22:23], exec
	s_or_b64 exec, exec, s[34:35]
	v_ashrrev_i32_e32 v113, 31, v112
	v_lshlrev_b64 v[112:113], 13, v[112:113]
	v_lshl_add_u64 v[112:113], s[16:17], 0, v[112:113]
	v_mad_i64_i32 v[114:115], s[34:35], v114, s86, v[116:117]
	v_lshl_add_u64 v[112:113], v[254:255], 1, v[112:113]
	v_lshl_add_u64 v[114:115], v[138:139], 2, v[114:115]
	s_and_b64 s[52:53], s[14:15], vcc
	s_and_saveexec_b64 s[34:35], s[52:53]
	s_cbranch_execz .Lgin_g1_u0
	global_store_dwordx4 v[114:115], v[108:111], off
.Lgin_g1_u0:
	s_or_b64 exec, exec, s[34:35]
	s_and_b64 s[52:53], s[14:15], s[8:9]
	s_and_saveexec_b64 s[34:35], s[52:53]
	s_cbranch_execz .Lgin_g1_u1
	global_store_dwordx4 v[114:115], v[104:107], off offset:64
.Lgin_g1_u1:
	s_or_b64 exec, exec, s[34:35]
	s_nop 0
	v_cvt_pk_bf16_f32 v108, v108, v109
	v_cvt_pk_bf16_f32 v109, v110, v111
	v_cvt_pk_bf16_f32 v110, v104, v105
	v_cvt_pk_bf16_f32 v111, v106, v107
	s_nop 1
	v_permlane16_swap_b32_e32 v108, v110
	v_permlane16_swap_b32_e32 v109, v111
	global_store_dwordx4 v[112:113], v[108:111], off
	s_and_b64 s[52:53], s[14:15], s[10:11]
	s_and_saveexec_b64 s[34:35], s[52:53]
	s_cbranch_execz .Lgin_g1_u2
	global_store_dwordx4 v[114:115], v[100:103], off offset:512
.Lgin_g1_u2:
	s_or_b64 exec, exec, s[34:35]
	s_and_b64 s[52:53], s[14:15], s[12:13]
	s_and_saveexec_b64 s[34:35], s[52:53]
	s_cbranch_execz .Lgin_g1_u3
	global_store_dwordx4 v[114:115], v[96:99], off offset:576
.Lgin_g1_u3:
	s_or_b64 exec, exec, s[34:35]
	s_nop 0
	v_cvt_pk_bf16_f32 v100, v100, v101
	v_cvt_pk_bf16_f32 v101, v102, v103
	v_cvt_pk_bf16_f32 v102, v96, v97
	v_cvt_pk_bf16_f32 v103, v98, v99
	s_nop 1
	v_permlane16_swap_b32_e32 v100, v102
	v_permlane16_swap_b32_e32 v101, v103
	global_store_dwordx4 v[112:113], v[100:103], off offset:256
	s_nop 0
	v_or_b32_e32 v96, 32, v136
	v_cmp_lt_i32_e64 s[14:15], s92, v96
	s_and_saveexec_b64 s[34:35], s[14:15]
	s_xor_b64 s[14:15], exec, s[34:35]
	s_add_i32 s34, s25, 0xffff8020
	s_lshr_b32 s34, s34, 4
	v_mad_u64_u32 v[98:99], s[34:35], s34, 3, v[130:131]
	s_or_saveexec_b64 s[34:35], s[14:15]
	v_mov_b64_e32 v[100:101], s[20:21]
	s_mov_b64 s[14:15], s[22:23]
	s_xor_b64 exec, exec, s[34:35]
	v_and_b32_e32 v97, 0x1fef, v96
	v_add_u32_e32 v98, s27, v97
	v_mov_b64_e32 v[100:101], s[18:19]
	s_andn2_b64 s[14:15], s[22:23], exec
	s_or_b64 exec, exec, s[34:35]
	v_ashrrev_i32_e32 v97, 31, v96
	v_lshlrev_b64 v[96:97], 13, v[96:97]
	v_lshl_add_u64 v[96:97], s[16:17], 0, v[96:97]
	v_mad_i64_i32 v[98:99], s[34:35], v98, s86, v[100:101]
	v_lshl_add_u64 v[96:97], v[254:255], 1, v[96:97]
	v_lshl_add_u64 v[98:99], v[138:139], 2, v[98:99]
	s_and_b64 s[52:53], s[14:15], vcc
	s_and_saveexec_b64 s[34:35], s[52:53]
	s_cbranch_execz .Lgin_g2_u0
	global_store_dwordx4 v[98:99], v[92:95], off
.Lgin_g2_u0:
	s_or_b64 exec, exec, s[34:35]
	s_and_b64 s[52:53], s[14:15], s[8:9]
	s_and_saveexec_b64 s[34:35], s[52:53]
	s_cbranch_execz .Lgin_g2_u1
	global_store_dwordx4 v[98:99], v[88:91], off offset:64
.Lgin_g2_u1:
	s_or_b64 exec, exec, s[34:35]
	s_nop 0
	v_cvt_pk_bf16_f32 v92, v92, v93
	v_cvt_pk_bf16_f32 v93, v94, v95
	v_cvt_pk_bf16_f32 v94, v88, v89
	v_cvt_pk_bf16_f32 v95, v90, v91
	s_nop 1
	v_permlane16_swap_b32_e32 v92, v94
	v_permlane16_swap_b32_e32 v93, v95
	global_store_dwordx4 v[96:97], v[92:95], off
	s_and_b64 s[52:53], s[14:15], s[10:11]
	s_and_saveexec_b64 s[34:35], s[52:53]
	s_cbranch_execz .Lgin_g2_u2
	global_store_dwordx4 v[98:99], v[84:87], off offset:512
.Lgin_g2_u2:
	s_or_b64 exec, exec, s[34:35]
	s_and_b64 s[52:53], s[14:15], s[12:13]
	s_and_saveexec_b64 s[34:35], s[52:53]
	s_cbranch_execz .Lgin_g2_u3
	global_store_dwordx4 v[98:99], v[80:83], off offset:576
.Lgin_g2_u3:
	s_or_b64 exec, exec, s[34:35]
	s_nop 0
	v_cvt_pk_bf16_f32 v84, v84, v85
	v_cvt_pk_bf16_f32 v85, v86, v87
	v_cvt_pk_bf16_f32 v86, v80, v81
	v_cvt_pk_bf16_f32 v87, v82, v83
	s_nop 1
	v_permlane16_swap_b32_e32 v84, v86
	v_permlane16_swap_b32_e32 v85, v87
	global_store_dwordx4 v[96:97], v[84:87], off offset:256
	s_nop 0
	v_or_b32_e32 v80, 48, v136
	v_cmp_lt_i32_e64 s[14:15], s92, v80
	s_and_saveexec_b64 s[34:35], s[14:15]
	s_xor_b64 s[14:15], exec, s[34:35]
	s_add_i32 s34, s25, 0xffff8030
	s_lshr_b32 s34, s34, 4
	v_mad_u64_u32 v[82:83], s[34:35], s34, 3, v[130:131]
	s_or_saveexec_b64 s[34:35], s[14:15]
	v_mov_b64_e32 v[84:85], s[20:21]
	s_mov_b64 s[14:15], s[22:23]
	s_xor_b64 exec, exec, s[34:35]
	v_and_b32_e32 v81, 0x1fff, v80
	s_movk_i32 s14, 0x1ffc
	v_cmp_lt_u32_e64 s[14:15], s14, v81
	s_andn2_b64 s[52:53], s[22:23], exec
	s_and_b64 s[14:15], s[14:15], exec
	v_add_u32_e32 v82, s27, v81
	v_mov_b64_e32 v[84:85], s[18:19]
	s_or_b64 s[14:15], s[52:53], s[14:15]
	s_or_b64 exec, exec, s[34:35]
	v_ashrrev_i32_e32 v81, 31, v80
	v_lshlrev_b64 v[80:81], 13, v[80:81]
	v_lshl_add_u64 v[80:81], s[16:17], 0, v[80:81]
	v_mad_i64_i32 v[82:83], s[34:35], v82, s86, v[84:85]
	v_lshl_add_u64 v[80:81], v[254:255], 1, v[80:81]
	v_lshl_add_u64 v[82:83], v[138:139], 2, v[82:83]
	s_and_b64 s[52:53], s[14:15], vcc
	s_and_saveexec_b64 s[34:35], s[52:53]
	s_cbranch_execz .Lgin_g3_u0
	global_store_dwordx4 v[82:83], v[76:79], off
.Lgin_g3_u0:
	s_or_b64 exec, exec, s[34:35]
	s_and_b64 s[52:53], s[14:15], s[8:9]
	s_and_saveexec_b64 s[34:35], s[52:53]
	s_cbranch_execz .Lgin_g3_u1
	global_store_dwordx4 v[82:83], v[72:75], off offset:64
.Lgin_g3_u1:
	s_or_b64 exec, exec, s[34:35]
	s_nop 0
	v_cvt_pk_bf16_f32 v76, v76, v77
	v_cvt_pk_bf16_f32 v77, v78, v79
	v_cvt_pk_bf16_f32 v78, v72, v73
	v_cvt_pk_bf16_f32 v79, v74, v75
	s_nop 1
	v_permlane16_swap_b32_e32 v76, v78
	v_permlane16_swap_b32_e32 v77, v79
	global_store_dwordx4 v[80:81], v[76:79], off
	s_and_b64 s[52:53], s[14:15], s[10:11]
	s_and_saveexec_b64 s[34:35], s[52:53]
	s_cbranch_execz .Lgin_g3_u2
	global_store_dwordx4 v[82:83], v[68:71], off offset:512
.Lgin_g3_u2:
	s_or_b64 exec, exec, s[34:35]
	s_and_b64 s[52:53], s[14:15], s[12:13]
	s_and_saveexec_b64 s[34:35], s[52:53]
	s_cbranch_execz .Lgin_g3_u3
	global_store_dwordx4 v[82:83], v[64:67], off offset:576
.Lgin_g3_u3:
	s_or_b64 exec, exec, s[34:35]
	s_nop 0
	v_cvt_pk_bf16_f32 v68, v68, v69
	v_cvt_pk_bf16_f32 v69, v70, v71
	v_cvt_pk_bf16_f32 v70, v64, v65
	v_cvt_pk_bf16_f32 v71, v66, v67
	s_nop 1
	v_permlane16_swap_b32_e32 v68, v70
	v_permlane16_swap_b32_e32 v69, v71
	global_store_dwordx4 v[80:81], v[68:71], off offset:256
	s_nop 0
	s_movk_i32 s14, 0x7f7f
	v_cmp_lt_i32_e64 s[14:15], s14, v136
	s_and_saveexec_b64 s[34:35], s[14:15]
	s_xor_b64 s[14:15], exec, s[34:35]
	s_add_i32 s27, s25, 0xffff8080
	s_lshr_b32 s27, s27, 4
	v_mad_u64_u32 v[66:67], s[34:35], s27, 3, v[130:131]
	s_or_saveexec_b64 s[34:35], s[14:15]
	v_add_u32_e32 v64, 0x80, v136
	v_ashrrev_i32_e32 v65, 13, v64
	v_mad_i32_i24 v70, v65, 3, v222
	v_mov_b64_e32 v[68:69], s[20:21]
	s_mov_b64 s[14:15], s[22:23]
	s_xor_b64 exec, exec, s[34:35]
	v_and_b32_e32 v65, 0x1fcf, v64
	v_add_u32_e32 v66, v70, v65
	v_mov_b64_e32 v[68:69], s[18:19]
	s_andn2_b64 s[14:15], s[22:23], exec
	s_or_b64 exec, exec, s[34:35]
	v_ashrrev_i32_e32 v65, 31, v64
	v_lshlrev_b64 v[64:65], 13, v[64:65]
	v_lshl_add_u64 v[64:65], s[16:17], 0, v[64:65]
	v_mad_i64_i32 v[66:67], s[34:35], v66, s86, v[68:69]
	v_lshl_add_u64 v[64:65], v[254:255], 1, v[64:65]
	v_lshl_add_u64 v[66:67], v[138:139], 2, v[66:67]
	s_and_b64 s[52:53], s[14:15], vcc
	s_and_saveexec_b64 s[34:35], s[52:53]
	s_cbranch_execz .Lgin_g4_u0
	global_store_dwordx4 v[66:67], v[60:63], off
.Lgin_g4_u0:
	s_or_b64 exec, exec, s[34:35]
	s_and_b64 s[52:53], s[14:15], s[8:9]
	s_and_saveexec_b64 s[34:35], s[52:53]
	s_cbranch_execz .Lgin_g4_u1
	global_store_dwordx4 v[66:67], v[56:59], off offset:64
.Lgin_g4_u1:
	s_or_b64 exec, exec, s[34:35]
	s_nop 0
	v_cvt_pk_bf16_f32 v60, v60, v61
	v_cvt_pk_bf16_f32 v61, v62, v63
	v_cvt_pk_bf16_f32 v62, v56, v57
	v_cvt_pk_bf16_f32 v63, v58, v59
	s_nop 1
	v_permlane16_swap_b32_e32 v60, v62
	v_permlane16_swap_b32_e32 v61, v63
	global_store_dwordx4 v[64:65], v[60:63], off
	s_and_b64 s[52:53], s[14:15], s[10:11]
	s_and_saveexec_b64 s[34:35], s[52:53]
	s_cbranch_execz .Lgin_g4_u2
	global_store_dwordx4 v[66:67], v[52:55], off offset:512
.Lgin_g4_u2:
	s_or_b64 exec, exec, s[34:35]
	s_and_b64 s[52:53], s[14:15], s[12:13]
	s_and_saveexec_b64 s[34:35], s[52:53]
	s_cbranch_execz .Lgin_g4_u3
	global_store_dwordx4 v[66:67], v[48:51], off offset:576
.Lgin_g4_u3:
	s_or_b64 exec, exec, s[34:35]
	s_nop 0
	v_cvt_pk_bf16_f32 v52, v52, v53
	v_cvt_pk_bf16_f32 v53, v54, v55
	v_cvt_pk_bf16_f32 v54, v48, v49
	v_cvt_pk_bf16_f32 v55, v50, v51
	s_nop 1
	v_permlane16_swap_b32_e32 v52, v54
	v_permlane16_swap_b32_e32 v53, v55
	global_store_dwordx4 v[64:65], v[52:55], off offset:256
	s_nop 0
	s_movk_i32 s14, 0x7f6f
	v_cmp_lt_i32_e64 s[14:15], s14, v136
	s_and_saveexec_b64 s[34:35], s[14:15]
	s_xor_b64 s[14:15], exec, s[34:35]
	s_add_i32 s27, s25, 0xffff8090
	s_lshr_b32 s27, s27, 4
	v_mad_u64_u32 v[50:51], s[34:35], s27, 3, v[130:131]
	s_or_saveexec_b64 s[34:35], s[14:15]
	v_add_u32_e32 v48, 0x90, v136
	v_mov_b64_e32 v[52:53], s[20:21]
	s_mov_b64 s[14:15], s[22:23]
	s_xor_b64 exec, exec, s[34:35]
	v_and_b32_e32 v49, 0x1fdf, v48
	v_add_u32_e32 v50, v70, v49
	v_mov_b64_e32 v[52:53], s[18:19]
	s_andn2_b64 s[14:15], s[22:23], exec
	s_or_b64 exec, exec, s[34:35]
	v_ashrrev_i32_e32 v49, 31, v48
	v_lshlrev_b64 v[48:49], 13, v[48:49]
	v_lshl_add_u64 v[48:49], s[16:17], 0, v[48:49]
	v_mad_i64_i32 v[50:51], s[34:35], v50, s86, v[52:53]
	v_lshl_add_u64 v[48:49], v[254:255], 1, v[48:49]
	v_lshl_add_u64 v[50:51], v[138:139], 2, v[50:51]
	s_and_b64 s[52:53], s[14:15], vcc
	s_and_saveexec_b64 s[34:35], s[52:53]
	s_cbranch_execz .Lgin_g5_u0
	global_store_dwordx4 v[50:51], v[44:47], off
.Lgin_g5_u0:
	s_or_b64 exec, exec, s[34:35]
	s_and_b64 s[52:53], s[14:15], s[8:9]
	s_and_saveexec_b64 s[34:35], s[52:53]
	s_cbranch_execz .Lgin_g5_u1
	global_store_dwordx4 v[50:51], v[40:43], off offset:64
.Lgin_g5_u1:
	s_or_b64 exec, exec, s[34:35]
	s_nop 0
	v_cvt_pk_bf16_f32 v44, v44, v45
	v_cvt_pk_bf16_f32 v45, v46, v47
	v_cvt_pk_bf16_f32 v46, v40, v41
	v_cvt_pk_bf16_f32 v47, v42, v43
	s_nop 1
	v_permlane16_swap_b32_e32 v44, v46
	v_permlane16_swap_b32_e32 v45, v47
	global_store_dwordx4 v[48:49], v[44:47], off
	s_and_b64 s[52:53], s[14:15], s[10:11]
	s_and_saveexec_b64 s[34:35], s[52:53]
	s_cbranch_execz .Lgin_g5_u2
	global_store_dwordx4 v[50:51], v[36:39], off offset:512
.Lgin_g5_u2:
	s_or_b64 exec, exec, s[34:35]
	s_and_b64 s[52:53], s[14:15], s[12:13]
	s_and_saveexec_b64 s[34:35], s[52:53]
	s_cbranch_execz .Lgin_g5_u3
	global_store_dwordx4 v[50:51], v[32:35], off offset:576
.Lgin_g5_u3:
	s_or_b64 exec, exec, s[34:35]
	s_nop 0
	v_cvt_pk_bf16_f32 v36, v36, v37
	v_cvt_pk_bf16_f32 v37, v38, v39
	v_cvt_pk_bf16_f32 v38, v32, v33
	v_cvt_pk_bf16_f32 v39, v34, v35
	s_nop 1
	v_permlane16_swap_b32_e32 v36, v38
	v_permlane16_swap_b32_e32 v37, v39
	global_store_dwordx4 v[48:49], v[36:39], off offset:256
	s_nop 0
	s_movk_i32 s14, 0x7f5f
	v_cmp_lt_i32_e64 s[14:15], s14, v136
	s_and_saveexec_b64 s[34:35], s[14:15]
	s_xor_b64 s[14:15], exec, s[34:35]
	s_add_i32 s27, s25, 0xffff80a0
	s_lshr_b32 s27, s27, 4
	v_mad_u64_u32 v[34:35], s[34:35], s27, 3, v[130:131]
	s_or_saveexec_b64 s[34:35], s[14:15]
	v_add_u32_e32 v32, 0xa0, v136
	v_mov_b64_e32 v[36:37], s[20:21]
	s_mov_b64 s[14:15], s[22:23]
	s_xor_b64 exec, exec, s[34:35]
	v_and_b32_e32 v33, 0x1fef, v32
	v_add_u32_e32 v34, v70, v33
	v_mov_b64_e32 v[36:37], s[18:19]
	s_andn2_b64 s[14:15], s[22:23], exec
	s_or_b64 exec, exec, s[34:35]
	v_ashrrev_i32_e32 v33, 31, v32
	v_lshlrev_b64 v[32:33], 13, v[32:33]
	v_lshl_add_u64 v[32:33], s[16:17], 0, v[32:33]
	v_mad_i64_i32 v[34:35], s[34:35], v34, s86, v[36:37]
	v_lshl_add_u64 v[32:33], v[254:255], 1, v[32:33]
	v_lshl_add_u64 v[34:35], v[138:139], 2, v[34:35]
	s_and_b64 s[52:53], s[14:15], vcc
	s_and_saveexec_b64 s[34:35], s[52:53]
	s_cbranch_execz .Lgin_g6_u0
	global_store_dwordx4 v[34:35], v[28:31], off
.Lgin_g6_u0:
	s_or_b64 exec, exec, s[34:35]
	s_and_b64 s[52:53], s[14:15], s[8:9]
	s_and_saveexec_b64 s[34:35], s[52:53]
	s_cbranch_execz .Lgin_g6_u1
	global_store_dwordx4 v[34:35], v[24:27], off offset:64
.Lgin_g6_u1:
	s_or_b64 exec, exec, s[34:35]
	s_nop 0
	v_cvt_pk_bf16_f32 v28, v28, v29
	v_cvt_pk_bf16_f32 v29, v30, v31
	v_cvt_pk_bf16_f32 v30, v24, v25
	v_cvt_pk_bf16_f32 v31, v26, v27
	s_nop 1
	v_permlane16_swap_b32_e32 v28, v30
	v_permlane16_swap_b32_e32 v29, v31
	global_store_dwordx4 v[32:33], v[28:31], off
	s_and_b64 s[52:53], s[14:15], s[10:11]
	s_and_saveexec_b64 s[34:35], s[52:53]
	s_cbranch_execz .Lgin_g6_u2
	global_store_dwordx4 v[34:35], v[20:23], off offset:512
.Lgin_g6_u2:
	s_or_b64 exec, exec, s[34:35]
	s_and_b64 s[52:53], s[14:15], s[12:13]
	s_and_saveexec_b64 s[34:35], s[52:53]
	s_cbranch_execz .Lgin_g6_u3
	global_store_dwordx4 v[34:35], v[16:19], off offset:576
.Lgin_g6_u3:
	s_or_b64 exec, exec, s[34:35]
	s_nop 0
	v_cvt_pk_bf16_f32 v20, v20, v21
	v_cvt_pk_bf16_f32 v21, v22, v23
	v_cvt_pk_bf16_f32 v22, v16, v17
	v_cvt_pk_bf16_f32 v23, v18, v19
	s_nop 1
	v_permlane16_swap_b32_e32 v20, v22
	v_permlane16_swap_b32_e32 v21, v23
	global_store_dwordx4 v[32:33], v[20:23], off offset:256
	s_nop 0
	s_movk_i32 s14, 0x7f4f
	v_cmp_lt_i32_e64 s[14:15], s14, v136
	s_and_saveexec_b64 s[34:35], s[14:15]
	s_xor_b64 s[14:15], exec, s[34:35]
	s_addk_i32 s25, 0x80b0
	s_lshr_b32 s25, s25, 4
	v_mad_u64_u32 v[18:19], s[34:35], s25, 3, v[130:131]
	s_or_saveexec_b64 s[34:35], s[14:15]
	v_add_u32_e32 v16, 0xb0, v136
	v_mov_b64_e32 v[20:21], s[20:21]
	s_mov_b64 s[14:15], s[22:23]
	s_xor_b64 exec, exec, s[34:35]
	v_and_b32_e32 v17, 0x1fff, v16
	s_movk_i32 s14, 0x1ffc
	v_cmp_lt_u32_e64 s[14:15], s14, v17
	s_andn2_b64 s[52:53], s[22:23], exec
	s_and_b64 s[14:15], s[14:15], exec
	v_add_u32_e32 v18, v70, v17
	v_mov_b64_e32 v[20:21], s[18:19]
	s_or_b64 s[14:15], s[52:53], s[14:15]
	s_or_b64 exec, exec, s[34:35]
	v_ashrrev_i32_e32 v17, 31, v16
	v_lshlrev_b64 v[16:17], 13, v[16:17]
	v_lshl_add_u64 v[16:17], s[16:17], 0, v[16:17]
	v_mad_i64_i32 v[18:19], s[34:35], v18, s86, v[20:21]
	v_lshl_add_u64 v[16:17], v[254:255], 1, v[16:17]
	v_lshl_add_u64 v[18:19], v[138:139], 2, v[18:19]
	s_and_b64 s[52:53], s[14:15], vcc
	s_and_saveexec_b64 s[34:35], s[52:53]
	s_cbranch_execz .Lgin_g7_u0
	global_store_dwordx4 v[18:19], v[12:15], off
.Lgin_g7_u0:
	s_or_b64 exec, exec, s[34:35]
	s_and_b64 s[52:53], s[14:15], s[8:9]
	s_and_saveexec_b64 s[34:35], s[52:53]
	s_cbranch_execz .Lgin_g7_u1
	global_store_dwordx4 v[18:19], v[8:11], off offset:64
.Lgin_g7_u1:
	s_or_b64 exec, exec, s[34:35]
	s_nop 0
	v_cvt_pk_bf16_f32 v12, v12, v13
	v_cvt_pk_bf16_f32 v13, v14, v15
	v_cvt_pk_bf16_f32 v14, v8, v9
	v_cvt_pk_bf16_f32 v15, v10, v11
	s_nop 1
	v_permlane16_swap_b32_e32 v12, v14
	v_permlane16_swap_b32_e32 v13, v15
	global_store_dwordx4 v[16:17], v[12:15], off
	s_and_b64 s[52:53], s[14:15], s[10:11]
	s_and_saveexec_b64 s[34:35], s[52:53]
	s_cbranch_execz .Lgin_g7_u2
	global_store_dwordx4 v[18:19], v[4:7], off offset:512
.Lgin_g7_u2:
	s_or_b64 exec, exec, s[34:35]
	s_and_b64 s[52:53], s[14:15], s[12:13]
	s_and_saveexec_b64 s[34:35], s[52:53]
	s_cbranch_execz .Lgin_g7_u3
	global_store_dwordx4 v[18:19], v[0:3], off offset:576
.Lgin_g7_u3:
	s_or_b64 exec, exec, s[34:35]
	s_nop 0
	v_cvt_pk_bf16_f32 v4, v4, v5
	v_cvt_pk_bf16_f32 v5, v6, v7
	v_cvt_pk_bf16_f32 v6, v0, v1
	v_cvt_pk_bf16_f32 v7, v2, v3
	s_nop 1
	v_permlane16_swap_b32_e32 v4, v6
	v_permlane16_swap_b32_e32 v5, v7
	global_store_dwordx4 v[16:17], v[4:7], off offset:256
	s_mov_b64 s[8:9], 0
	s_branch .LBB0_319

.LBB0_527:
	s_and_b64 s[10:11], s[24:25], s[28:29]
	s_andn2_b64 vcc, exec, s[10:11]
	s_waitcnt lgkmcnt(0)
	s_barrier
	s_cbranch_vccnz .LBB0_483
	ds_read2_b32 v[64:65], v233 offset1:32
	ds_read2_b32 v[66:67], v233 offset0:64 offset1:96
	v_add_u32_e32 v70, 0x400, v233
	ds_read2_b32 v[68:69], v70 offset1:32
	s_or_b64 s[26:27], s[26:27], s[8:9]
	s_waitcnt lgkmcnt(2)
	v_pk_fma_f32 v[78:79], v[48:49], v[74:75], v[64:65] op_sel_hi:[1,0,1] neg_lo:[0,0,1] neg_hi:[0,0,1]
	v_add_u32_e32 v64, 0x800, v233
	s_waitcnt lgkmcnt(1)
	v_pk_fma_f32 v[76:77], v[50:51], v[74:75], v[66:67] op_sel_hi:[1,0,1] neg_lo:[0,0,1] neg_hi:[0,0,1]
	ds_read2_b32 v[50:51], v64 offset1:32
	ds_read2_b32 v[48:49], v70 offset0:64 offset1:96
	s_waitcnt lgkmcnt(2)
	v_pk_fma_f32 v[72:73], v[52:53], v[74:75], v[68:69] op_sel_hi:[1,0,1] neg_lo:[0,0,1] neg_hi:[0,0,1]
	v_add_u32_e32 v52, 0xc00, v233
	v_pk_mul_f32 v[82:83], v[78:79], v[78:79]
	s_waitcnt lgkmcnt(1)
	v_pk_fma_f32 v[66:67], v[56:57], v[74:75], v[50:51] op_sel_hi:[1,0,1] neg_lo:[0,0,1] neg_hi:[0,0,1]
	ds_read2_b32 v[50:51], v52 offset1:32
	ds_read2_b32 v[52:53], v52 offset0:64 offset1:96
	s_waitcnt lgkmcnt(2)
	v_pk_fma_f32 v[70:71], v[54:55], v[74:75], v[48:49] op_sel_hi:[1,0,1] neg_lo:[0,0,1] neg_hi:[0,0,1]
	ds_read2_b32 v[48:49], v64 offset0:64 offset1:96
	v_add_u32_e32 v56, 0x1400, v233
	s_waitcnt lgkmcnt(2)
	v_pk_fma_f32 v[64:65], v[60:61], v[74:75], v[50:51] op_sel_hi:[1,0,1] neg_lo:[0,0,1] neg_hi:[0,0,1]
	s_waitcnt lgkmcnt(1)
	v_pk_fma_f32 v[60:61], v[62:63], v[74:75], v[52:53] op_sel_hi:[1,0,1] neg_lo:[0,0,1] neg_hi:[0,0,1]
	v_add_u32_e32 v50, 0x1000, v233
	ds_read2_b32 v[52:53], v56 offset1:32
	s_waitcnt lgkmcnt(1)
	v_pk_fma_f32 v[68:69], v[58:59], v[74:75], v[48:49] op_sel_hi:[1,0,1] neg_lo:[0,0,1] neg_hi:[0,0,1]
	ds_read2_b32 v[48:49], v50 offset1:32
	ds_read2_b32 v[50:51], v50 offset0:64 offset1:96
	v_pk_mul_f32 v[80:81], v[76:77], v[76:77]
	s_waitcnt lgkmcnt(2)
	v_pk_fma_f32 v[54:55], v[36:37], v[74:75], v[52:53] op_sel_hi:[1,0,1] neg_lo:[0,0,1] neg_hi:[0,0,1]
	v_add_u32_e32 v36, 0x1800, v233
	s_waitcnt lgkmcnt(1)
	v_pk_fma_f32 v[62:63], v[32:33], v[74:75], v[48:49] op_sel_hi:[1,0,1] neg_lo:[0,0,1] neg_hi:[0,0,1]
	s_waitcnt lgkmcnt(0)
	v_pk_fma_f32 v[58:59], v[34:35], v[74:75], v[50:51] op_sel_hi:[1,0,1] neg_lo:[0,0,1] neg_hi:[0,0,1]
	ds_read2_b32 v[34:35], v36 offset1:32
	ds_read2_b32 v[32:33], v56 offset0:64 offset1:96
	ds_read2_b32 v[36:37], v36 offset0:64 offset1:96
	v_pk_mul_f32 v[84:85], v[72:73], v[72:73]
	v_pk_mul_f32 v[86:87], v[70:71], v[70:71]
	s_waitcnt lgkmcnt(2)
	v_pk_fma_f32 v[52:53], v[40:41], v[74:75], v[34:35] op_sel_hi:[1,0,1] neg_lo:[0,0,1] neg_hi:[0,0,1]
	v_add_u32_e32 v34, 0x1c00, v233
	s_waitcnt lgkmcnt(1)
	v_pk_fma_f32 v[56:57], v[38:39], v[74:75], v[32:33] op_sel_hi:[1,0,1] neg_lo:[0,0,1] neg_hi:[0,0,1]
	ds_read2_b32 v[32:33], v34 offset1:32
	ds_read2_b32 v[34:35], v34 offset0:64 offset1:96
	v_add_u32_e32 v38, 0x2000, v233
	s_waitcnt lgkmcnt(2)
	v_pk_fma_f32 v[48:49], v[42:43], v[74:75], v[36:37] op_sel_hi:[1,0,1] neg_lo:[0,0,1] neg_hi:[0,0,1]
	ds_read2_b32 v[36:37], v38 offset1:32
	s_waitcnt lgkmcnt(2)
	v_pk_fma_f32 v[50:51], v[44:45], v[74:75], v[32:33] op_sel_hi:[1,0,1] neg_lo:[0,0,1] neg_hi:[0,0,1]
	s_waitcnt lgkmcnt(1)
	v_pk_fma_f32 v[44:45], v[46:47], v[74:75], v[34:35] op_sel_hi:[1,0,1] neg_lo:[0,0,1] neg_hi:[0,0,1]
	v_add_u32_e32 v34, 0x2400, v233
	ds_read2_b32 v[32:33], v34 offset1:32
	s_waitcnt lgkmcnt(1)
	v_pk_fma_f32 v[40:41], v[16:17], v[74:75], v[36:37] op_sel_hi:[1,0,1] neg_lo:[0,0,1] neg_hi:[0,0,1]
	ds_read2_b32 v[16:17], v38 offset0:64 offset1:96
	ds_read2_b32 v[34:35], v34 offset0:64 offset1:96
	v_pk_mul_f32 v[88:89], v[66:67], v[66:67]
	s_waitcnt lgkmcnt(2)
	v_pk_fma_f32 v[38:39], v[20:21], v[74:75], v[32:33] op_sel_hi:[1,0,1] neg_lo:[0,0,1] neg_hi:[0,0,1]
	v_pk_mul_f32 v[90:91], v[68:69], v[68:69]
	s_waitcnt lgkmcnt(1)
	v_pk_fma_f32 v[42:43], v[18:19], v[74:75], v[16:17] op_sel_hi:[1,0,1] neg_lo:[0,0,1] neg_hi:[0,0,1]
	s_waitcnt lgkmcnt(0)
	v_pk_fma_f32 v[34:35], v[22:23], v[74:75], v[34:35] op_sel_hi:[1,0,1] neg_lo:[0,0,1] neg_hi:[0,0,1]
	v_add_u32_e32 v18, 0x2800, v233
	v_add_u32_e32 v22, 0x2c00, v233
	ds_read2_b32 v[16:17], v18 offset1:32
	ds_read2_b32 v[18:19], v18 offset0:64 offset1:96
	ds_read2_b32 v[20:21], v22 offset1:32
	v_pk_mul_f32 v[92:93], v[64:65], v[64:65]
	v_pk_mul_f32 v[94:95], v[60:61], v[60:61]
	s_waitcnt lgkmcnt(2)
	v_pk_fma_f32 v[36:37], v[24:25], v[74:75], v[16:17] op_sel_hi:[1,0,1] neg_lo:[0,0,1] neg_hi:[0,0,1]
	s_waitcnt lgkmcnt(1)
	v_pk_fma_f32 v[32:33], v[26:27], v[74:75], v[18:19] op_sel_hi:[1,0,1] neg_lo:[0,0,1] neg_hi:[0,0,1]
	s_waitcnt lgkmcnt(0)
	v_pk_fma_f32 v[26:27], v[28:29], v[74:75], v[20:21] op_sel_hi:[1,0,1] neg_lo:[0,0,1] neg_hi:[0,0,1]
	v_add_u32_e32 v20, 0x3000, v233
	ds_read2_b32 v[16:17], v22 offset0:64 offset1:96
	ds_read2_b32 v[18:19], v20 offset1:32
	ds_read2_b32 v[20:21], v20 offset0:64 offset1:96
	v_pk_mul_f32 v[96:97], v[62:63], v[62:63]
	v_pk_mul_f32 v[98:99], v[58:59], v[58:59]
	s_waitcnt lgkmcnt(2)
	v_pk_fma_f32 v[28:29], v[30:31], v[74:75], v[16:17] op_sel_hi:[1,0,1] neg_lo:[0,0,1] neg_hi:[0,0,1]
	s_waitcnt lgkmcnt(1)
	v_pk_fma_f32 v[24:25], v[0:1], v[74:75], v[18:19] op_sel_hi:[1,0,1] neg_lo:[0,0,1] neg_hi:[0,0,1]
	s_waitcnt lgkmcnt(0)
	v_pk_fma_f32 v[20:21], v[2:3], v[74:75], v[20:21] op_sel_hi:[1,0,1] neg_lo:[0,0,1] neg_hi:[0,0,1]
	v_add_u32_e32 v2, 0x3400, v233
	v_add_u32_e32 v75, 0x3800, v233
	ds_read2_b32 v[0:1], v2 offset1:32
	ds_read2_b32 v[2:3], v2 offset0:64 offset1:96
	ds_read2_b32 v[16:17], v75 offset1:32
	v_pk_mul_f32 v[100:101], v[54:55], v[54:55]
	v_pk_mul_f32 v[102:103], v[56:57], v[56:57]
	s_waitcnt lgkmcnt(2)
	v_pk_fma_f32 v[22:23], v[4:5], v[74:75], v[0:1] op_sel_hi:[1,0,1] neg_lo:[0,0,1] neg_hi:[0,0,1]
	s_waitcnt lgkmcnt(1)
	v_pk_fma_f32 v[18:19], v[6:7], v[74:75], v[2:3] op_sel_hi:[1,0,1] neg_lo:[0,0,1] neg_hi:[0,0,1]
	s_waitcnt lgkmcnt(0)
	v_pk_fma_f32 v[16:17], v[8:9], v[74:75], v[16:17] op_sel_hi:[1,0,1] neg_lo:[0,0,1] neg_hi:[0,0,1]
	ds_read2_b32 v[0:1], v75 offset0:64 offset1:96
	v_add_u32_e32 v75, 0x3c00, v233
	ds_read2_b32 v[2:3], v75 offset1:32
	ds_read2_b32 v[128:129], v75 offset0:64 offset1:96
	v_pk_mul_f32 v[104:105], v[52:53], v[52:53]
	s_waitcnt lgkmcnt(2)
	v_pk_fma_f32 v[10:11], v[10:11], v[74:75], v[0:1] op_sel_hi:[1,0,1] neg_lo:[0,0,1] neg_hi:[0,0,1]
	v_pk_mul_f32 v[106:107], v[48:49], v[48:49]
	s_waitcnt lgkmcnt(1)
	v_pk_fma_f32 v[2:3], v[12:13], v[74:75], v[2:3] op_sel_hi:[1,0,1] neg_lo:[0,0,1] neg_hi:[0,0,1]
	s_waitcnt lgkmcnt(0)
	v_pk_fma_f32 v[0:1], v[14:15], v[74:75], v[128:129] op_sel_hi:[1,0,1] neg_lo:[0,0,1] neg_hi:[0,0,1]
	v_add_f32_e32 v74, v82, v83
	v_add_f32_e32 v74, v74, v80
	v_add_f32_e32 v74, v74, v81
	v_add_f32_e32 v74, v74, v84
	v_add_f32_e32 v74, v74, v85
	v_add_f32_e32 v74, v74, v86
	v_add_f32_e32 v74, v74, v87
	v_add_f32_e32 v74, v74, v88
	v_add_f32_e32 v74, v74, v89
	v_add_f32_e32 v74, v74, v90
	v_add_f32_e32 v74, v74, v91
	v_add_f32_e32 v74, v74, v92
	v_add_f32_e32 v74, v74, v93
	v_add_f32_e32 v74, v74, v94
	v_add_f32_e32 v74, v74, v95
	v_add_f32_e32 v74, v74, v96
	v_add_f32_e32 v74, v74, v97
	v_add_f32_e32 v74, v74, v98
	v_add_f32_e32 v74, v74, v99
	v_add_f32_e32 v74, v74, v100
	v_add_f32_e32 v74, v74, v101
	v_add_f32_e32 v74, v74, v102
	v_add_f32_e32 v74, v74, v103
	v_add_f32_e32 v74, v74, v104
	v_add_f32_e32 v74, v74, v105
	v_add_f32_e32 v74, v74, v106
	v_pk_mul_f32 v[108:109], v[50:51], v[50:51]
	v_add_f32_e32 v74, v74, v107
	v_add_f32_e32 v74, v74, v108
	v_pk_mul_f32 v[46:47], v[44:45], v[44:45]
	v_add_f32_e32 v74, v74, v109
	v_add_f32_e32 v46, v74, v46
	v_pk_mul_f32 v[110:111], v[40:41], v[40:41]
	v_add_f32_e32 v46, v46, v47
	v_add_f32_e32 v46, v46, v110
	v_pk_mul_f32 v[112:113], v[42:43], v[42:43]
	v_add_f32_e32 v46, v46, v111
	v_add_f32_e32 v46, v46, v112
	v_pk_mul_f32 v[114:115], v[38:39], v[38:39]
	v_add_f32_e32 v46, v46, v113
	v_add_f32_e32 v46, v46, v114
	v_pk_mul_f32 v[116:117], v[34:35], v[34:35]
	v_add_f32_e32 v46, v46, v115
	v_add_f32_e32 v46, v46, v116
	v_pk_mul_f32 v[118:119], v[36:37], v[36:37]
	v_add_f32_e32 v46, v46, v117
	v_add_f32_e32 v46, v46, v118
	v_pk_mul_f32 v[120:121], v[32:33], v[32:33]
	v_add_f32_e32 v46, v46, v119
	v_add_f32_e32 v46, v46, v120
	v_pk_mul_f32 v[122:123], v[26:27], v[26:27]
	v_add_f32_e32 v46, v46, v121
	v_add_f32_e32 v46, v46, v122
	v_pk_mul_f32 v[30:31], v[28:29], v[28:29]
	v_add_f32_e32 v46, v46, v123
	v_add_f32_e32 v30, v46, v30
	v_pk_mul_f32 v[124:125], v[24:25], v[24:25]
	v_add_f32_e32 v30, v30, v31
	v_add_f32_e32 v30, v30, v124
	v_pk_mul_f32 v[126:127], v[20:21], v[20:21]
	v_add_f32_e32 v30, v30, v125
	v_add_f32_e32 v30, v30, v126
	v_pk_mul_f32 v[4:5], v[22:23], v[22:23]
	v_add_f32_e32 v30, v30, v127
	v_add_f32_e32 v4, v30, v4
	v_pk_mul_f32 v[6:7], v[18:19], v[18:19]
	v_add_f32_e32 v4, v4, v5
	v_add_f32_e32 v4, v4, v6
	v_pk_mul_f32 v[8:9], v[16:17], v[16:17]
	v_add_f32_e32 v4, v4, v7
	v_add_f32_e32 v4, v4, v8
	v_pk_mul_f32 v[130:131], v[10:11], v[10:11]
	v_add_f32_e32 v4, v4, v9
	v_add_f32_e32 v4, v4, v130
	v_pk_mul_f32 v[12:13], v[2:3], v[2:3]
	v_add_f32_e32 v4, v4, v131
	v_add_f32_e32 v4, v4, v12
	v_pk_mul_f32 v[14:15], v[0:1], v[0:1]
	v_add_f32_e32 v4, v4, v13
	v_add_f32_e32 v4, v4, v14
	v_add_f32_e32 v4, v4, v15
	ds_bpermute_b32 v5, v191, v4
	s_and_saveexec_b64 s[10:11], s[26:27]
	s_cbranch_execz .LBB0_482
	v_add_u32_e32 v6, s82, v208
	v_ashrrev_i32_e32 v7, 31, v6
	v_lshlrev_b64 v[8:9], 13, v[6:7]
	v_lshl_add_u64 v[8:9], s[12:13], 0, v[8:9]
	v_lshl_add_u64 v[8:9], v[8:9], 0, s[72:73]
	v_mov_b32_e32 v197, v173
	v_lshl_add_u64 v[8:9], v[8:9], 0, v[196:197]
	s_mov_b64 s[26:27], 0x1800
	v_lshl_add_u64 v[8:9], v[8:9], 0, s[26:27]
	global_load_dwordx2 v[80:81], v[8:9], off
	global_load_dwordx2 v[82:83], v[8:9], off offset:16
	global_load_dwordx2 v[84:85], v[8:9], off offset:32
	global_load_dwordx2 v[86:87], v[8:9], off offset:48
	global_load_dwordx2 v[88:89], v[8:9], off offset:64
	global_load_dwordx2 v[90:91], v[8:9], off offset:80
	global_load_dwordx2 v[92:93], v[8:9], off offset:96
	global_load_dwordx2 v[94:95], v[8:9], off offset:112
	global_load_dwordx2 v[96:97], v[8:9], off offset:128
	global_load_dwordx2 v[98:99], v[8:9], off offset:144
	global_load_dwordx2 v[100:101], v[8:9], off offset:160
	global_load_dwordx2 v[102:103], v[8:9], off offset:176
	global_load_dwordx2 v[104:105], v[8:9], off offset:192
	global_load_dwordx2 v[106:107], v[8:9], off offset:208
	global_load_dwordx2 v[108:109], v[8:9], off offset:224
	global_load_dwordx2 v[110:111], v[8:9], off offset:240
	global_load_dwordx4 v[112:115], v[188:189], off
	global_load_dwordx4 v[116:119], v[188:189], off offset:32
	global_load_dwordx4 v[120:123], v[188:189], off offset:64
	global_load_dwordx4 v[124:127], v[188:189], off offset:96
	global_load_dwordx4 v[128:131], v[188:189], off offset:128
	global_load_dwordx4 v[132:135], v[188:189], off offset:160
	global_load_dwordx4 v[136:139], v[188:189], off offset:192
	global_load_dwordx4 v[140:143], v[188:189], off offset:224
	global_load_dwordx4 v[144:147], v[188:189], off offset:256
	global_load_dwordx4 v[148:151], v[188:189], off offset:288
	global_load_dwordx4 v[152:155], v[188:189], off offset:320
	global_load_dwordx4 v[156:159], v[188:189], off offset:352
	global_load_dwordx4 v[160:163], v[188:189], off offset:384
	global_load_dwordx4 v[164:167], v[188:189], off offset:416
	global_load_dwordx4 v[168:171], v[188:189], off offset:448
	s_waitcnt lgkmcnt(0)
	v_add_f32_e32 v4, v4, v5
	v_fmamk_f32 v4, v4, 0x3c000000, v216
	v_rsq_f32_e32 v4, v4
	v_lshlrev_b64 v[6:7], 11, v[6:7]
	v_lshl_add_u64 v[6:7], s[14:15], 0, v[6:7]
	v_lshl_add_u64 v[6:7], v[6:7], 0, s[72:73]
	v_mul_f32_e32 v4, v231, v4
	v_lshl_add_u64 v[6:7], v[6:7], 0, v[196:197]
	s_waitcnt vmcnt(0)
	v_lshlrev_b32_e32 v12, 16, v80
	v_and_b32_e32 v13, 0xffff0000, v80
	v_lshlrev_b32_e32 v14, 16, v81
	v_and_b32_e32 v15, 0xffff0000, v81
	v_mul_f32_e32 v30, 0xbfb8aa3b, v12
	v_mul_f32_e32 v31, 0xbfb8aa3b, v13
	v_mul_f32_e32 v46, 0xbfb8aa3b, v14
	v_mul_f32_e32 v47, 0xbfb8aa3b, v15
	v_exp_f32_e32 v30, v30
	v_exp_f32_e32 v31, v31
	v_exp_f32_e32 v46, v46
	v_exp_f32_e32 v47, v47
	v_pk_mul_f32 v[78:79], v[78:79], v[4:5] op_sel_hi:[1,0]
	v_pk_mul_f32 v[76:77], v[76:77], v[4:5] op_sel_hi:[1,0]
	v_add_f32_e32 v30, 1.0, v30
	v_add_f32_e32 v31, 1.0, v31
	v_add_f32_e32 v46, 1.0, v46
	v_add_f32_e32 v47, 1.0, v47
	v_rcp_f32_e32 v30, v30
	v_rcp_f32_e32 v31, v31
	v_rcp_f32_e32 v46, v46
	v_rcp_f32_e32 v47, v47
	v_pk_mul_f32 v[78:79], v[78:79], v[112:113]
	v_pk_mul_f32 v[76:77], v[76:77], v[114:115]
	v_pk_mul_f32 v[30:31], v[30:31], v[12:13]
	v_pk_mul_f32 v[46:47], v[46:47], v[14:15]
	v_pk_mul_f32 v[78:79], v[78:79], v[30:31]
	v_pk_mul_f32 v[76:77], v[76:77], v[46:47]
	v_cvt_pk_bf16_f32 v74, v78, v79
	v_cvt_pk_bf16_f32 v75, v76, v77
	global_store_dwordx2 v[6:7], v[74:75], off
	global_load_dwordx4 v[112:115], v[188:189], off offset:480
	v_lshlrev_b32_e32 v12, 16, v82
	v_and_b32_e32 v13, 0xffff0000, v82
	v_lshlrev_b32_e32 v14, 16, v83
	v_and_b32_e32 v15, 0xffff0000, v83
	v_mul_f32_e32 v30, 0xbfb8aa3b, v12
	v_mul_f32_e32 v31, 0xbfb8aa3b, v13
	v_mul_f32_e32 v46, 0xbfb8aa3b, v14
	v_mul_f32_e32 v47, 0xbfb8aa3b, v15
	v_exp_f32_e32 v30, v30
	v_exp_f32_e32 v31, v31
	v_exp_f32_e32 v46, v46
	v_exp_f32_e32 v47, v47
	v_pk_mul_f32 v[72:73], v[72:73], v[4:5] op_sel_hi:[1,0]
	v_pk_mul_f32 v[70:71], v[70:71], v[4:5] op_sel_hi:[1,0]
	v_add_f32_e32 v30, 1.0, v30
	v_add_f32_e32 v31, 1.0, v31
	v_add_f32_e32 v46, 1.0, v46
	v_add_f32_e32 v47, 1.0, v47
	v_rcp_f32_e32 v30, v30
	v_rcp_f32_e32 v31, v31
	v_rcp_f32_e32 v46, v46
	v_rcp_f32_e32 v47, v47
	v_pk_mul_f32 v[72:73], v[72:73], v[116:117]
	v_pk_mul_f32 v[70:71], v[70:71], v[118:119]
	v_pk_mul_f32 v[30:31], v[30:31], v[12:13]
	v_pk_mul_f32 v[46:47], v[46:47], v[14:15]
	v_pk_mul_f32 v[72:73], v[72:73], v[30:31]
	v_pk_mul_f32 v[70:71], v[70:71], v[46:47]
	v_cvt_pk_bf16_f32 v74, v72, v73
	v_cvt_pk_bf16_f32 v75, v70, v71
	global_store_dwordx2 v[6:7], v[74:75], off offset:16
	v_lshlrev_b32_e32 v12, 16, v84
	v_and_b32_e32 v13, 0xffff0000, v84
	v_lshlrev_b32_e32 v14, 16, v85
	v_and_b32_e32 v15, 0xffff0000, v85
	v_mul_f32_e32 v30, 0xbfb8aa3b, v12
	v_mul_f32_e32 v31, 0xbfb8aa3b, v13
	v_mul_f32_e32 v46, 0xbfb8aa3b, v14
	v_mul_f32_e32 v47, 0xbfb8aa3b, v15
	v_exp_f32_e32 v30, v30
	v_exp_f32_e32 v31, v31
	v_exp_f32_e32 v46, v46
	v_exp_f32_e32 v47, v47
	v_pk_mul_f32 v[66:67], v[66:67], v[4:5] op_sel_hi:[1,0]
	v_pk_mul_f32 v[68:69], v[68:69], v[4:5] op_sel_hi:[1,0]
	v_add_f32_e32 v30, 1.0, v30
	v_add_f32_e32 v31, 1.0, v31
	v_add_f32_e32 v46, 1.0, v46
	v_add_f32_e32 v47, 1.0, v47
	v_rcp_f32_e32 v30, v30
	v_rcp_f32_e32 v31, v31
	v_rcp_f32_e32 v46, v46
	v_rcp_f32_e32 v47, v47
	v_pk_mul_f32 v[66:67], v[66:67], v[120:121]
	v_pk_mul_f32 v[68:69], v[68:69], v[122:123]
	v_pk_mul_f32 v[30:31], v[30:31], v[12:13]
	v_pk_mul_f32 v[46:47], v[46:47], v[14:15]
	v_pk_mul_f32 v[66:67], v[66:67], v[30:31]
	v_pk_mul_f32 v[68:69], v[68:69], v[46:47]
	v_cvt_pk_bf16_f32 v74, v66, v67
	v_cvt_pk_bf16_f32 v75, v68, v69
	global_store_dwordx2 v[6:7], v[74:75], off offset:32
	v_lshlrev_b32_e32 v12, 16, v86
	v_and_b32_e32 v13, 0xffff0000, v86
	v_lshlrev_b32_e32 v14, 16, v87
	v_and_b32_e32 v15, 0xffff0000, v87
	v_mul_f32_e32 v30, 0xbfb8aa3b, v12
	v_mul_f32_e32 v31, 0xbfb8aa3b, v13
	v_mul_f32_e32 v46, 0xbfb8aa3b, v14
	v_mul_f32_e32 v47, 0xbfb8aa3b, v15
	v_exp_f32_e32 v30, v30
	v_exp_f32_e32 v31, v31
	v_exp_f32_e32 v46, v46
	v_exp_f32_e32 v47, v47
	v_pk_mul_f32 v[64:65], v[64:65], v[4:5] op_sel_hi:[1,0]
	v_pk_mul_f32 v[60:61], v[60:61], v[4:5] op_sel_hi:[1,0]
	v_add_f32_e32 v30, 1.0, v30
	v_add_f32_e32 v31, 1.0, v31
	v_add_f32_e32 v46, 1.0, v46
	v_add_f32_e32 v47, 1.0, v47
	v_rcp_f32_e32 v30, v30
	v_rcp_f32_e32 v31, v31
	v_rcp_f32_e32 v46, v46
	v_rcp_f32_e32 v47, v47
	v_pk_mul_f32 v[64:65], v[64:65], v[124:125]
	v_pk_mul_f32 v[60:61], v[60:61], v[126:127]
	v_pk_mul_f32 v[30:31], v[30:31], v[12:13]
	v_pk_mul_f32 v[46:47], v[46:47], v[14:15]
	v_pk_mul_f32 v[64:65], v[64:65], v[30:31]
	v_pk_mul_f32 v[60:61], v[60:61], v[46:47]
	v_cvt_pk_bf16_f32 v74, v64, v65
	v_cvt_pk_bf16_f32 v75, v60, v61
	global_store_dwordx2 v[6:7], v[74:75], off offset:48
	v_lshlrev_b32_e32 v12, 16, v88
	v_and_b32_e32 v13, 0xffff0000, v88
	v_lshlrev_b32_e32 v14, 16, v89
	v_and_b32_e32 v15, 0xffff0000, v89
	v_mul_f32_e32 v30, 0xbfb8aa3b, v12
	v_mul_f32_e32 v31, 0xbfb8aa3b, v13
	v_mul_f32_e32 v46, 0xbfb8aa3b, v14
	v_mul_f32_e32 v47, 0xbfb8aa3b, v15
	v_exp_f32_e32 v30, v30
	v_exp_f32_e32 v31, v31
	v_exp_f32_e32 v46, v46
	v_exp_f32_e32 v47, v47
	v_pk_mul_f32 v[62:63], v[62:63], v[4:5] op_sel_hi:[1,0]
	v_pk_mul_f32 v[58:59], v[58:59], v[4:5] op_sel_hi:[1,0]
	v_add_f32_e32 v30, 1.0, v30
	v_add_f32_e32 v31, 1.0, v31
	v_add_f32_e32 v46, 1.0, v46
	v_add_f32_e32 v47, 1.0, v47
	v_rcp_f32_e32 v30, v30
	v_rcp_f32_e32 v31, v31
	v_rcp_f32_e32 v46, v46
	v_rcp_f32_e32 v47, v47
	v_pk_mul_f32 v[62:63], v[62:63], v[128:129]
	v_pk_mul_f32 v[58:59], v[58:59], v[130:131]
	v_pk_mul_f32 v[30:31], v[30:31], v[12:13]
	v_pk_mul_f32 v[46:47], v[46:47], v[14:15]
	v_pk_mul_f32 v[62:63], v[62:63], v[30:31]
	v_pk_mul_f32 v[58:59], v[58:59], v[46:47]
	v_cvt_pk_bf16_f32 v74, v62, v63
	v_cvt_pk_bf16_f32 v75, v58, v59
	global_store_dwordx2 v[6:7], v[74:75], off offset:64
	v_lshlrev_b32_e32 v12, 16, v90
	v_and_b32_e32 v13, 0xffff0000, v90
	v_lshlrev_b32_e32 v14, 16, v91
	v_and_b32_e32 v15, 0xffff0000, v91
	v_mul_f32_e32 v30, 0xbfb8aa3b, v12
	v_mul_f32_e32 v31, 0xbfb8aa3b, v13
	v_mul_f32_e32 v46, 0xbfb8aa3b, v14
	v_mul_f32_e32 v47, 0xbfb8aa3b, v15
	v_exp_f32_e32 v30, v30
	v_exp_f32_e32 v31, v31
	v_exp_f32_e32 v46, v46
	v_exp_f32_e32 v47, v47
	v_pk_mul_f32 v[54:55], v[54:55], v[4:5] op_sel_hi:[1,0]
	v_pk_mul_f32 v[56:57], v[56:57], v[4:5] op_sel_hi:[1,0]
	v_add_f32_e32 v30, 1.0, v30
	v_add_f32_e32 v31, 1.0, v31
	v_add_f32_e32 v46, 1.0, v46
	v_add_f32_e32 v47, 1.0, v47
	v_rcp_f32_e32 v30, v30
	v_rcp_f32_e32 v31, v31
	v_rcp_f32_e32 v46, v46
	v_rcp_f32_e32 v47, v47
	v_pk_mul_f32 v[54:55], v[54:55], v[132:133]
	v_pk_mul_f32 v[56:57], v[56:57], v[134:135]
	v_pk_mul_f32 v[30:31], v[30:31], v[12:13]
	v_pk_mul_f32 v[46:47], v[46:47], v[14:15]
	v_pk_mul_f32 v[54:55], v[54:55], v[30:31]
	v_pk_mul_f32 v[56:57], v[56:57], v[46:47]
	v_cvt_pk_bf16_f32 v74, v54, v55
	v_cvt_pk_bf16_f32 v75, v56, v57
	global_store_dwordx2 v[6:7], v[74:75], off offset:80
	v_lshlrev_b32_e32 v12, 16, v92
	v_and_b32_e32 v13, 0xffff0000, v92
	v_lshlrev_b32_e32 v14, 16, v93
	v_and_b32_e32 v15, 0xffff0000, v93
	v_mul_f32_e32 v30, 0xbfb8aa3b, v12
	v_mul_f32_e32 v31, 0xbfb8aa3b, v13
	v_mul_f32_e32 v46, 0xbfb8aa3b, v14
	v_mul_f32_e32 v47, 0xbfb8aa3b, v15
	v_exp_f32_e32 v30, v30
	v_exp_f32_e32 v31, v31
	v_exp_f32_e32 v46, v46
	v_exp_f32_e32 v47, v47
	v_pk_mul_f32 v[52:53], v[52:53], v[4:5] op_sel_hi:[1,0]
	v_pk_mul_f32 v[48:49], v[48:49], v[4:5] op_sel_hi:[1,0]
	v_add_f32_e32 v30, 1.0, v30
	v_add_f32_e32 v31, 1.0, v31
	v_add_f32_e32 v46, 1.0, v46
	v_add_f32_e32 v47, 1.0, v47
	v_rcp_f32_e32 v30, v30
	v_rcp_f32_e32 v31, v31
	v_rcp_f32_e32 v46, v46
	v_rcp_f32_e32 v47, v47
	v_pk_mul_f32 v[52:53], v[52:53], v[136:137]
	v_pk_mul_f32 v[48:49], v[48:49], v[138:139]
	v_pk_mul_f32 v[30:31], v[30:31], v[12:13]
	v_pk_mul_f32 v[46:47], v[46:47], v[14:15]
	v_pk_mul_f32 v[52:53], v[52:53], v[30:31]
	v_pk_mul_f32 v[48:49], v[48:49], v[46:47]
	v_cvt_pk_bf16_f32 v74, v52, v53
	v_cvt_pk_bf16_f32 v75, v48, v49
	global_store_dwordx2 v[6:7], v[74:75], off offset:96
	v_lshlrev_b32_e32 v12, 16, v94
	v_and_b32_e32 v13, 0xffff0000, v94
	v_lshlrev_b32_e32 v14, 16, v95
	v_and_b32_e32 v15, 0xffff0000, v95
	v_mul_f32_e32 v30, 0xbfb8aa3b, v12
	v_mul_f32_e32 v31, 0xbfb8aa3b, v13
	v_mul_f32_e32 v46, 0xbfb8aa3b, v14
	v_mul_f32_e32 v47, 0xbfb8aa3b, v15
	v_exp_f32_e32 v30, v30
	v_exp_f32_e32 v31, v31
	v_exp_f32_e32 v46, v46
	v_exp_f32_e32 v47, v47
	v_pk_mul_f32 v[50:51], v[50:51], v[4:5] op_sel_hi:[1,0]
	v_pk_mul_f32 v[44:45], v[44:45], v[4:5] op_sel_hi:[1,0]
	v_add_f32_e32 v30, 1.0, v30
	v_add_f32_e32 v31, 1.0, v31
	v_add_f32_e32 v46, 1.0, v46
	v_add_f32_e32 v47, 1.0, v47
	v_rcp_f32_e32 v30, v30
	v_rcp_f32_e32 v31, v31
	v_rcp_f32_e32 v46, v46
	v_rcp_f32_e32 v47, v47
	v_pk_mul_f32 v[50:51], v[50:51], v[140:141]
	v_pk_mul_f32 v[44:45], v[44:45], v[142:143]
	v_pk_mul_f32 v[30:31], v[30:31], v[12:13]
	v_pk_mul_f32 v[46:47], v[46:47], v[14:15]
	v_pk_mul_f32 v[50:51], v[50:51], v[30:31]
	v_pk_mul_f32 v[44:45], v[44:45], v[46:47]
	v_cvt_pk_bf16_f32 v74, v50, v51
	v_cvt_pk_bf16_f32 v75, v44, v45
	global_store_dwordx2 v[6:7], v[74:75], off offset:112
	v_lshlrev_b32_e32 v12, 16, v96
	v_and_b32_e32 v13, 0xffff0000, v96
	v_lshlrev_b32_e32 v14, 16, v97
	v_and_b32_e32 v15, 0xffff0000, v97
	v_mul_f32_e32 v30, 0xbfb8aa3b, v12
	v_mul_f32_e32 v31, 0xbfb8aa3b, v13
	v_mul_f32_e32 v46, 0xbfb8aa3b, v14
	v_mul_f32_e32 v47, 0xbfb8aa3b, v15
	v_exp_f32_e32 v30, v30
	v_exp_f32_e32 v31, v31
	v_exp_f32_e32 v46, v46
	v_exp_f32_e32 v47, v47
	v_pk_mul_f32 v[40:41], v[40:41], v[4:5] op_sel_hi:[1,0]
	v_pk_mul_f32 v[42:43], v[42:43], v[4:5] op_sel_hi:[1,0]
	v_add_f32_e32 v30, 1.0, v30
	v_add_f32_e32 v31, 1.0, v31
	v_add_f32_e32 v46, 1.0, v46
	v_add_f32_e32 v47, 1.0, v47
	v_rcp_f32_e32 v30, v30
	v_rcp_f32_e32 v31, v31
	v_rcp_f32_e32 v46, v46
	v_rcp_f32_e32 v47, v47
	v_pk_mul_f32 v[40:41], v[40:41], v[144:145]
	v_pk_mul_f32 v[42:43], v[42:43], v[146:147]
	v_pk_mul_f32 v[30:31], v[30:31], v[12:13]
	v_pk_mul_f32 v[46:47], v[46:47], v[14:15]
	v_pk_mul_f32 v[40:41], v[40:41], v[30:31]
	v_pk_mul_f32 v[42:43], v[42:43], v[46:47]
	v_cvt_pk_bf16_f32 v74, v40, v41
	v_cvt_pk_bf16_f32 v75, v42, v43
	global_store_dwordx2 v[6:7], v[74:75], off offset:128
	v_lshlrev_b32_e32 v12, 16, v98
	v_and_b32_e32 v13, 0xffff0000, v98
	v_lshlrev_b32_e32 v14, 16, v99
	v_and_b32_e32 v15, 0xffff0000, v99
	v_mul_f32_e32 v30, 0xbfb8aa3b, v12
	v_mul_f32_e32 v31, 0xbfb8aa3b, v13
	v_mul_f32_e32 v46, 0xbfb8aa3b, v14
	v_mul_f32_e32 v47, 0xbfb8aa3b, v15
	v_exp_f32_e32 v30, v30
	v_exp_f32_e32 v31, v31
	v_exp_f32_e32 v46, v46
	v_exp_f32_e32 v47, v47
	v_pk_mul_f32 v[38:39], v[38:39], v[4:5] op_sel_hi:[1,0]
	v_pk_mul_f32 v[34:35], v[34:35], v[4:5] op_sel_hi:[1,0]
	v_add_f32_e32 v30, 1.0, v30
	v_add_f32_e32 v31, 1.0, v31
	v_add_f32_e32 v46, 1.0, v46
	v_add_f32_e32 v47, 1.0, v47
	v_rcp_f32_e32 v30, v30
	v_rcp_f32_e32 v31, v31
	v_rcp_f32_e32 v46, v46
	v_rcp_f32_e32 v47, v47
	v_pk_mul_f32 v[38:39], v[38:39], v[148:149]
	v_pk_mul_f32 v[34:35], v[34:35], v[150:151]
	v_pk_mul_f32 v[30:31], v[30:31], v[12:13]
	v_pk_mul_f32 v[46:47], v[46:47], v[14:15]
	v_pk_mul_f32 v[38:39], v[38:39], v[30:31]
	v_pk_mul_f32 v[34:35], v[34:35], v[46:47]
	v_cvt_pk_bf16_f32 v74, v38, v39
	v_cvt_pk_bf16_f32 v75, v34, v35
	global_store_dwordx2 v[6:7], v[74:75], off offset:144
	v_lshlrev_b32_e32 v12, 16, v100
	v_and_b32_e32 v13, 0xffff0000, v100
	v_lshlrev_b32_e32 v14, 16, v101
	v_and_b32_e32 v15, 0xffff0000, v101
	v_mul_f32_e32 v30, 0xbfb8aa3b, v12
	v_mul_f32_e32 v31, 0xbfb8aa3b, v13
	v_mul_f32_e32 v46, 0xbfb8aa3b, v14
	v_mul_f32_e32 v47, 0xbfb8aa3b, v15
	v_exp_f32_e32 v30, v30
	v_exp_f32_e32 v31, v31
	v_exp_f32_e32 v46, v46
	v_exp_f32_e32 v47, v47
	v_pk_mul_f32 v[36:37], v[36:37], v[4:5] op_sel_hi:[1,0]
	v_pk_mul_f32 v[32:33], v[32:33], v[4:5] op_sel_hi:[1,0]
	v_add_f32_e32 v30, 1.0, v30
	v_add_f32_e32 v31, 1.0, v31
	v_add_f32_e32 v46, 1.0, v46
	v_add_f32_e32 v47, 1.0, v47
	v_rcp_f32_e32 v30, v30
	v_rcp_f32_e32 v31, v31
	v_rcp_f32_e32 v46, v46
	v_rcp_f32_e32 v47, v47
	v_pk_mul_f32 v[36:37], v[36:37], v[152:153]
	v_pk_mul_f32 v[32:33], v[32:33], v[154:155]
	v_pk_mul_f32 v[30:31], v[30:31], v[12:13]
	v_pk_mul_f32 v[46:47], v[46:47], v[14:15]
	v_pk_mul_f32 v[36:37], v[36:37], v[30:31]
	v_pk_mul_f32 v[32:33], v[32:33], v[46:47]
	v_cvt_pk_bf16_f32 v74, v36, v37
	v_cvt_pk_bf16_f32 v75, v32, v33
	global_store_dwordx2 v[6:7], v[74:75], off offset:160
	v_lshlrev_b32_e32 v12, 16, v102
	v_and_b32_e32 v13, 0xffff0000, v102
	v_lshlrev_b32_e32 v14, 16, v103
	v_and_b32_e32 v15, 0xffff0000, v103
	v_mul_f32_e32 v30, 0xbfb8aa3b, v12
	v_mul_f32_e32 v31, 0xbfb8aa3b, v13
	v_mul_f32_e32 v46, 0xbfb8aa3b, v14
	v_mul_f32_e32 v47, 0xbfb8aa3b, v15
	v_exp_f32_e32 v30, v30
	v_exp_f32_e32 v31, v31
	v_exp_f32_e32 v46, v46
	v_exp_f32_e32 v47, v47
	v_pk_mul_f32 v[26:27], v[26:27], v[4:5] op_sel_hi:[1,0]
	v_pk_mul_f32 v[28:29], v[28:29], v[4:5] op_sel_hi:[1,0]
	v_add_f32_e32 v30, 1.0, v30
	v_add_f32_e32 v31, 1.0, v31
	v_add_f32_e32 v46, 1.0, v46
	v_add_f32_e32 v47, 1.0, v47
	v_rcp_f32_e32 v30, v30
	v_rcp_f32_e32 v31, v31
	v_rcp_f32_e32 v46, v46
	v_rcp_f32_e32 v47, v47
	v_pk_mul_f32 v[26:27], v[26:27], v[156:157]
	v_pk_mul_f32 v[28:29], v[28:29], v[158:159]
	v_pk_mul_f32 v[30:31], v[30:31], v[12:13]
	v_pk_mul_f32 v[46:47], v[46:47], v[14:15]
	v_pk_mul_f32 v[26:27], v[26:27], v[30:31]
	v_pk_mul_f32 v[28:29], v[28:29], v[46:47]
	v_cvt_pk_bf16_f32 v74, v26, v27
	v_cvt_pk_bf16_f32 v75, v28, v29
	global_store_dwordx2 v[6:7], v[74:75], off offset:176
	v_lshlrev_b32_e32 v12, 16, v104
	v_and_b32_e32 v13, 0xffff0000, v104
	v_lshlrev_b32_e32 v14, 16, v105
	v_and_b32_e32 v15, 0xffff0000, v105
	v_mul_f32_e32 v30, 0xbfb8aa3b, v12
	v_mul_f32_e32 v31, 0xbfb8aa3b, v13
	v_mul_f32_e32 v46, 0xbfb8aa3b, v14
	v_mul_f32_e32 v47, 0xbfb8aa3b, v15
	v_exp_f32_e32 v30, v30
	v_exp_f32_e32 v31, v31
	v_exp_f32_e32 v46, v46
	v_exp_f32_e32 v47, v47
	v_pk_mul_f32 v[24:25], v[24:25], v[4:5] op_sel_hi:[1,0]
	v_pk_mul_f32 v[20:21], v[20:21], v[4:5] op_sel_hi:[1,0]
	v_add_f32_e32 v30, 1.0, v30
	v_add_f32_e32 v31, 1.0, v31
	v_add_f32_e32 v46, 1.0, v46
	v_add_f32_e32 v47, 1.0, v47
	v_rcp_f32_e32 v30, v30
	v_rcp_f32_e32 v31, v31
	v_rcp_f32_e32 v46, v46
	v_rcp_f32_e32 v47, v47
	v_pk_mul_f32 v[24:25], v[24:25], v[160:161]
	v_pk_mul_f32 v[20:21], v[20:21], v[162:163]
	v_pk_mul_f32 v[30:31], v[30:31], v[12:13]
	v_pk_mul_f32 v[46:47], v[46:47], v[14:15]
	v_pk_mul_f32 v[24:25], v[24:25], v[30:31]
	v_pk_mul_f32 v[20:21], v[20:21], v[46:47]
	v_cvt_pk_bf16_f32 v74, v24, v25
	v_cvt_pk_bf16_f32 v75, v20, v21
	global_store_dwordx2 v[6:7], v[74:75], off offset:192
	v_lshlrev_b32_e32 v12, 16, v106
	v_and_b32_e32 v13, 0xffff0000, v106
	v_lshlrev_b32_e32 v14, 16, v107
	v_and_b32_e32 v15, 0xffff0000, v107
	v_mul_f32_e32 v30, 0xbfb8aa3b, v12
	v_mul_f32_e32 v31, 0xbfb8aa3b, v13
	v_mul_f32_e32 v46, 0xbfb8aa3b, v14
	v_mul_f32_e32 v47, 0xbfb8aa3b, v15
	v_exp_f32_e32 v30, v30
	v_exp_f32_e32 v31, v31
	v_exp_f32_e32 v46, v46
	v_exp_f32_e32 v47, v47
	v_pk_mul_f32 v[22:23], v[22:23], v[4:5] op_sel_hi:[1,0]
	v_pk_mul_f32 v[18:19], v[18:19], v[4:5] op_sel_hi:[1,0]
	v_add_f32_e32 v30, 1.0, v30
	v_add_f32_e32 v31, 1.0, v31
	v_add_f32_e32 v46, 1.0, v46
	v_add_f32_e32 v47, 1.0, v47
	v_rcp_f32_e32 v30, v30
	v_rcp_f32_e32 v31, v31
	v_rcp_f32_e32 v46, v46
	v_rcp_f32_e32 v47, v47
	v_pk_mul_f32 v[22:23], v[22:23], v[164:165]
	v_pk_mul_f32 v[18:19], v[18:19], v[166:167]
	v_pk_mul_f32 v[30:31], v[30:31], v[12:13]
	v_pk_mul_f32 v[46:47], v[46:47], v[14:15]
	v_pk_mul_f32 v[22:23], v[22:23], v[30:31]
	v_pk_mul_f32 v[18:19], v[18:19], v[46:47]
	v_cvt_pk_bf16_f32 v74, v22, v23
	v_cvt_pk_bf16_f32 v75, v18, v19
	global_store_dwordx2 v[6:7], v[74:75], off offset:208
	v_lshlrev_b32_e32 v12, 16, v108
	v_and_b32_e32 v13, 0xffff0000, v108
	v_lshlrev_b32_e32 v14, 16, v109
	v_and_b32_e32 v15, 0xffff0000, v109
	v_mul_f32_e32 v30, 0xbfb8aa3b, v12
	v_mul_f32_e32 v31, 0xbfb8aa3b, v13
	v_mul_f32_e32 v46, 0xbfb8aa3b, v14
	v_mul_f32_e32 v47, 0xbfb8aa3b, v15
	v_exp_f32_e32 v30, v30
	v_exp_f32_e32 v31, v31
	v_exp_f32_e32 v46, v46
	v_exp_f32_e32 v47, v47
	v_pk_mul_f32 v[16:17], v[16:17], v[4:5] op_sel_hi:[1,0]
	v_pk_mul_f32 v[10:11], v[10:11], v[4:5] op_sel_hi:[1,0]
	v_add_f32_e32 v30, 1.0, v30
	v_add_f32_e32 v31, 1.0, v31
	v_add_f32_e32 v46, 1.0, v46
	v_add_f32_e32 v47, 1.0, v47
	v_rcp_f32_e32 v30, v30
	v_rcp_f32_e32 v31, v31
	v_rcp_f32_e32 v46, v46
	v_rcp_f32_e32 v47, v47
	v_pk_mul_f32 v[16:17], v[16:17], v[168:169]
	v_pk_mul_f32 v[10:11], v[10:11], v[170:171]
	v_pk_mul_f32 v[30:31], v[30:31], v[12:13]
	v_pk_mul_f32 v[46:47], v[46:47], v[14:15]
	v_pk_mul_f32 v[16:17], v[16:17], v[30:31]
	v_pk_mul_f32 v[10:11], v[10:11], v[46:47]
	v_cvt_pk_bf16_f32 v74, v16, v17
	v_cvt_pk_bf16_f32 v75, v10, v11
	global_store_dwordx2 v[6:7], v[74:75], off offset:224
	s_waitcnt vmcnt(14)
	v_lshlrev_b32_e32 v12, 16, v110
	v_and_b32_e32 v13, 0xffff0000, v110
	v_lshlrev_b32_e32 v14, 16, v111
	v_and_b32_e32 v15, 0xffff0000, v111
	v_mul_f32_e32 v30, 0xbfb8aa3b, v12
	v_mul_f32_e32 v31, 0xbfb8aa3b, v13
	v_mul_f32_e32 v46, 0xbfb8aa3b, v14
	v_mul_f32_e32 v47, 0xbfb8aa3b, v15
	v_exp_f32_e32 v30, v30
	v_exp_f32_e32 v31, v31
	v_exp_f32_e32 v46, v46
	v_exp_f32_e32 v47, v47
	v_pk_mul_f32 v[2:3], v[2:3], v[4:5] op_sel_hi:[1,0]
	v_pk_mul_f32 v[0:1], v[0:1], v[4:5] op_sel_hi:[1,0]
	v_add_f32_e32 v30, 1.0, v30
	v_add_f32_e32 v31, 1.0, v31
	v_add_f32_e32 v46, 1.0, v46
	v_add_f32_e32 v47, 1.0, v47
	v_rcp_f32_e32 v30, v30
	v_rcp_f32_e32 v31, v31
	v_rcp_f32_e32 v46, v46
	v_rcp_f32_e32 v47, v47
	v_pk_mul_f32 v[2:3], v[2:3], v[112:113]
	v_pk_mul_f32 v[0:1], v[0:1], v[114:115]
	v_pk_mul_f32 v[30:31], v[30:31], v[12:13]
	v_pk_mul_f32 v[46:47], v[46:47], v[14:15]
	v_pk_mul_f32 v[2:3], v[2:3], v[30:31]
	v_pk_mul_f32 v[0:1], v[0:1], v[46:47]
	v_cvt_pk_bf16_f32 v74, v2, v3
	v_cvt_pk_bf16_f32 v75, v0, v1
	global_store_dwordx2 v[6:7], v[74:75], off offset:240
	s_branch .LBB0_482

.LBB0_1230:
	s_add_u32 s20, s18, 0xfffc0080
	s_addc_u32 s21, s19, -1
	s_add_i32 s48, 0, 0x10000
	v_add_u32_e32 v150, s48, v135
	ds_read_b128 v[138:141], v150
	ds_read_b128 v[142:145], v150 offset:1024
	ds_read_b128 v[146:149], v150 offset:2048
	ds_read_b128 v[150:153], v150 offset:3072
	s_cmp_eq_u32 s47, 12
	s_cselect_b32 s23, s13, s21
	s_cselect_b32 s22, s41, s20
	s_cselect_b32 s21, s11, s46
	s_cselect_b32 s20, s44, s45
	v_lshl_add_u64 v[170:171], s[18:19], 0, v[130:131]
	s_add_i32 m0, s30, 0xc000
	ds_read_b128 v[154:157], v137
	ds_read_b128 v[158:161], v137 offset:1024
	ds_read_b128 v[162:165], v137 offset:2048
	ds_read_b128 v[166:169], v137 offset:3072
	ds_read_b128 v[182:185], v137 offset:4096
	ds_read_b128 v[186:189], v137 offset:5120
	ds_read_b128 v[190:193], v137 offset:6144
	ds_read_b128 v[194:197], v137 offset:7168
	global_load_lds_dwordx4 v[170:171], off
	v_lshl_add_u64 v[170:171], s[18:19], 0, v[132:133]
	s_add_i32 m0, s30, 0xe000
	s_nop 0
	global_load_lds_dwordx4 v[170:171], off
	s_waitcnt lgkmcnt(8)
	s_barrier
	s_waitcnt lgkmcnt(0)
	s_setprio 1
	s_waitcnt lgkmcnt(0)
	v_mfma_f32_16x16x32_bf16 v[124:127], v[138:141], v[154:157], v[124:127]
	v_mfma_f32_16x16x32_bf16 v[120:123], v[146:149], v[154:157], v[120:123]
	v_mfma_f32_16x16x32_bf16 v[116:119], v[138:141], v[162:165], v[116:119]
	v_mfma_f32_16x16x32_bf16 v[108:111], v[146:149], v[162:165], v[108:111]
	v_mfma_f32_16x16x32_bf16 v[100:103], v[138:141], v[182:185], v[100:103]
	v_mfma_f32_16x16x32_bf16 v[92:95], v[146:149], v[182:185], v[92:95]
	v_mfma_f32_16x16x32_bf16 v[84:87], v[138:141], v[190:193], v[84:87]
	v_mfma_f32_16x16x32_bf16 v[76:79], v[146:149], v[190:193], v[76:79]
	v_mfma_f32_16x16x32_bf16 v[124:127], v[142:145], v[158:161], v[124:127]
	v_mfma_f32_16x16x32_bf16 v[120:123], v[150:153], v[158:161], v[120:123]
	v_mfma_f32_16x16x32_bf16 v[116:119], v[142:145], v[166:169], v[116:119]
	v_mfma_f32_16x16x32_bf16 v[108:111], v[150:153], v[166:169], v[108:111]
	v_mfma_f32_16x16x32_bf16 v[100:103], v[142:145], v[186:189], v[100:103]
	v_mfma_f32_16x16x32_bf16 v[92:95], v[150:153], v[186:189], v[92:95]
	v_mfma_f32_16x16x32_bf16 v[84:87], v[142:145], v[194:197], v[84:87]
	v_mfma_f32_16x16x32_bf16 v[76:79], v[150:153], v[194:197], v[76:79]
	s_setprio 0
	s_barrier
	s_add_i32 s50, 0, 0x14000
	v_add_u32_e32 v170, s50, v135
	s_add_i32 s48, s48, s29
	ds_read_b128 v[198:201], v170
	ds_read_b128 v[202:205], v170 offset:1024
	ds_read_b128 v[206:209], v170 offset:2048
	ds_read_b128 v[210:213], v170 offset:3072
	v_lshl_add_u64 v[170:171], s[20:21], 0, v[172:173]
	s_mov_b32 m0, s48
	v_lshl_add_u64 v[230:231], s[20:21], 0, v[128:129]
	global_load_lds_dwordx4 v[170:171], off
	s_add_i32 m0, s48, 0x2000
	s_nop 0
	global_load_lds_dwordx4 v[230:231], off
	s_barrier
	s_waitcnt lgkmcnt(0)
	s_setprio 1
	s_waitcnt lgkmcnt(0)
	v_mfma_f32_16x16x32_bf16 v[112:115], v[198:201], v[154:157], v[112:115]
	v_mfma_f32_16x16x32_bf16 v[104:107], v[206:209], v[154:157], v[104:107]
	v_mfma_f32_16x16x32_bf16 v[96:99], v[198:201], v[162:165], v[96:99]
	v_mfma_f32_16x16x32_bf16 v[88:91], v[206:209], v[162:165], v[88:91]
	v_mfma_f32_16x16x32_bf16 v[80:83], v[198:201], v[182:185], v[80:83]
	v_mfma_f32_16x16x32_bf16 v[72:75], v[206:209], v[182:185], v[72:75]
	v_mfma_f32_16x16x32_bf16 v[68:71], v[198:201], v[190:193], v[68:71]
	v_mfma_f32_16x16x32_bf16 v[64:67], v[206:209], v[190:193], v[64:67]
	v_mfma_f32_16x16x32_bf16 v[112:115], v[202:205], v[158:161], v[112:115]
	v_mfma_f32_16x16x32_bf16 v[104:107], v[210:213], v[158:161], v[104:107]
	v_mfma_f32_16x16x32_bf16 v[96:99], v[202:205], v[166:169], v[96:99]
	v_mfma_f32_16x16x32_bf16 v[88:91], v[210:213], v[166:169], v[88:91]
	v_mfma_f32_16x16x32_bf16 v[80:83], v[202:205], v[186:189], v[80:83]
	v_mfma_f32_16x16x32_bf16 v[72:75], v[210:213], v[186:189], v[72:75]
	v_mfma_f32_16x16x32_bf16 v[68:71], v[202:205], v[194:197], v[68:71]
	v_mfma_f32_16x16x32_bf16 v[64:67], v[210:213], v[194:197], v[64:67]
	s_setprio 0
	s_mov_b32 m0, s30
	v_lshl_add_u64 v[232:233], s[22:23], 0, v[172:173]
	s_barrier
	ds_read_b128 v[154:157], v137 offset:16384
	ds_read_b128 v[158:161], v137 offset:17408
	ds_read_b128 v[162:165], v137 offset:18432
	ds_read_b128 v[166:169], v137 offset:19456
	ds_read_b128 v[182:185], v137 offset:20480
	ds_read_b128 v[186:189], v137 offset:21504
	ds_read_b128 v[190:193], v137 offset:22528
	ds_read_b128 v[194:197], v137 offset:23552
	global_load_lds_dwordx4 v[232:233], off
	v_lshl_add_u64 v[234:235], s[22:23], 0, v[128:129]
	s_mov_b32 m0, s31
	s_nop 0
	global_load_lds_dwordx4 v[234:235], off
	s_barrier
	s_waitcnt lgkmcnt(0)
	s_setprio 1
	s_waitcnt lgkmcnt(0)
	v_mfma_f32_16x16x32_bf16 v[60:63], v[138:141], v[154:157], v[60:63]
	v_mfma_f32_16x16x32_bf16 v[56:59], v[146:149], v[154:157], v[56:59]
	v_mfma_f32_16x16x32_bf16 v[52:55], v[138:141], v[162:165], v[52:55]
	v_mfma_f32_16x16x32_bf16 v[44:47], v[146:149], v[162:165], v[44:47]
	v_mfma_f32_16x16x32_bf16 v[36:39], v[138:141], v[182:185], v[36:39]
	v_mfma_f32_16x16x32_bf16 v[28:31], v[146:149], v[182:185], v[28:31]
	v_mfma_f32_16x16x32_bf16 v[20:23], v[138:141], v[190:193], v[20:23]
	v_mfma_f32_16x16x32_bf16 v[12:15], v[146:149], v[190:193], v[12:15]
	v_mfma_f32_16x16x32_bf16 v[60:63], v[142:145], v[158:161], v[60:63]
	v_mfma_f32_16x16x32_bf16 v[56:59], v[150:153], v[158:161], v[56:59]
	v_mfma_f32_16x16x32_bf16 v[52:55], v[142:145], v[166:169], v[52:55]
	v_mfma_f32_16x16x32_bf16 v[44:47], v[150:153], v[166:169], v[44:47]
	v_mfma_f32_16x16x32_bf16 v[36:39], v[142:145], v[186:189], v[36:39]
	v_mfma_f32_16x16x32_bf16 v[28:31], v[150:153], v[186:189], v[28:31]
	v_mfma_f32_16x16x32_bf16 v[20:23], v[142:145], v[194:197], v[20:23]
	v_mfma_f32_16x16x32_bf16 v[12:15], v[150:153], v[194:197], v[12:15]
	s_setprio 0
	s_barrier
	s_add_u32 s48, s20, 0x40000
	s_addc_u32 s49, s21, 0
	s_add_i32 s50, s50, s29
	v_lshl_add_u64 v[138:139], s[48:49], 0, v[172:173]
	s_mov_b32 m0, s50
	s_nop 0
	global_load_lds_dwordx4 v[138:139], off
	v_lshl_add_u64 v[138:139], s[48:49], 0, v[128:129]
	s_add_i32 m0, s50, 0x2000
	s_nop 0
	global_load_lds_dwordx4 v[138:139], off
	s_waitcnt vmcnt(6)
	s_barrier
	s_setprio 1
	v_mfma_f32_16x16x32_bf16 v[48:51], v[198:201], v[154:157], v[48:51]
	v_mfma_f32_16x16x32_bf16 v[40:43], v[206:209], v[154:157], v[40:43]
	v_mfma_f32_16x16x32_bf16 v[32:35], v[198:201], v[162:165], v[32:35]
	v_mfma_f32_16x16x32_bf16 v[24:27], v[206:209], v[162:165], v[24:27]
	v_mfma_f32_16x16x32_bf16 v[16:19], v[198:201], v[182:185], v[16:19]
	v_mfma_f32_16x16x32_bf16 v[8:11], v[206:209], v[182:185], v[8:11]
	v_mfma_f32_16x16x32_bf16 v[4:7], v[198:201], v[190:193], v[4:7]
	v_mfma_f32_16x16x32_bf16 v[0:3], v[206:209], v[190:193], v[0:3]
	v_mfma_f32_16x16x32_bf16 v[48:51], v[202:205], v[158:161], v[48:51]
	v_mfma_f32_16x16x32_bf16 v[40:43], v[210:213], v[158:161], v[40:43]
	v_mfma_f32_16x16x32_bf16 v[32:35], v[202:205], v[166:169], v[32:35]
	v_mfma_f32_16x16x32_bf16 v[24:27], v[210:213], v[166:169], v[24:27]
	v_mfma_f32_16x16x32_bf16 v[16:19], v[202:205], v[186:189], v[16:19]
	v_mfma_f32_16x16x32_bf16 v[8:11], v[210:213], v[186:189], v[8:11]
	v_mfma_f32_16x16x32_bf16 v[4:7], v[202:205], v[194:197], v[4:7]
	v_mfma_f32_16x16x32_bf16 v[0:3], v[210:213], v[194:197], v[0:3]
	s_setprio 0
	s_add_i32 s48, 0, 0x18000
	v_add_u32_e32 v150, s48, v135
	s_barrier
	ds_read_b128 v[138:141], v150
	ds_read_b128 v[142:145], v150 offset:1024
	ds_read_b128 v[146:149], v150 offset:2048
	ds_read_b128 v[150:153], v150 offset:3072
	s_add_u32 s22, s22, 0x40000
	s_addc_u32 s23, s23, 0
	s_mov_b32 m0, s34
	v_lshl_add_u64 v[198:199], s[22:23], 0, v[172:173]
	ds_read_b128 v[154:157], v137 offset:32768
	ds_read_b128 v[158:161], v137 offset:33792
	ds_read_b128 v[162:165], v137 offset:34816
	ds_read_b128 v[166:169], v137 offset:35840
	ds_read_b128 v[182:185], v137 offset:36864
	ds_read_b128 v[186:189], v137 offset:37888
	ds_read_b128 v[190:193], v137 offset:38912
	ds_read_b128 v[194:197], v137 offset:39936
	global_load_lds_dwordx4 v[198:199], off
	v_lshl_add_u64 v[198:199], s[22:23], 0, v[128:129]
	s_mov_b32 m0, s35
	s_nop 0
	global_load_lds_dwordx4 v[198:199], off
	s_waitcnt lgkmcnt(8)
	s_barrier
	s_waitcnt lgkmcnt(0)
	s_setprio 1
	s_waitcnt lgkmcnt(0)
	v_mfma_f32_16x16x32_bf16 v[124:127], v[138:141], v[154:157], v[124:127]
	v_mfma_f32_16x16x32_bf16 v[120:123], v[146:149], v[154:157], v[120:123]
	v_mfma_f32_16x16x32_bf16 v[116:119], v[138:141], v[162:165], v[116:119]
	v_mfma_f32_16x16x32_bf16 v[108:111], v[146:149], v[162:165], v[108:111]
	v_mfma_f32_16x16x32_bf16 v[100:103], v[138:141], v[182:185], v[100:103]
	v_mfma_f32_16x16x32_bf16 v[92:95], v[146:149], v[182:185], v[92:95]
	v_mfma_f32_16x16x32_bf16 v[84:87], v[138:141], v[190:193], v[84:87]
	v_mfma_f32_16x16x32_bf16 v[76:79], v[146:149], v[190:193], v[76:79]
	v_mfma_f32_16x16x32_bf16 v[124:127], v[142:145], v[158:161], v[124:127]
	v_mfma_f32_16x16x32_bf16 v[120:123], v[150:153], v[158:161], v[120:123]
	v_mfma_f32_16x16x32_bf16 v[116:119], v[142:145], v[166:169], v[116:119]
	v_mfma_f32_16x16x32_bf16 v[108:111], v[150:153], v[166:169], v[108:111]
	v_mfma_f32_16x16x32_bf16 v[100:103], v[142:145], v[186:189], v[100:103]
	v_mfma_f32_16x16x32_bf16 v[92:95], v[150:153], v[186:189], v[92:95]
	v_mfma_f32_16x16x32_bf16 v[84:87], v[142:145], v[194:197], v[84:87]
	v_mfma_f32_16x16x32_bf16 v[76:79], v[150:153], v[194:197], v[76:79]
	s_setprio 0
	s_barrier
	s_add_i32 s22, 0, 0x1c000
	s_add_i32 s23, s48, s29
	v_add_u32_e32 v210, s22, v135
	v_lshl_add_u64 v[170:171], v[170:171], 0, s[78:79]
	s_mov_b32 m0, s23
	ds_read_b128 v[198:201], v210
	ds_read_b128 v[202:205], v210 offset:1024
	ds_read_b128 v[206:209], v210 offset:2048
	ds_read_b128 v[210:213], v210 offset:3072
	global_load_lds_dwordx4 v[170:171], off
	v_lshl_add_u64 v[170:171], v[230:231], 0, s[78:79]
	s_add_i32 m0, s23, 0x2000
	s_nop 0
	global_load_lds_dwordx4 v[170:171], off
	s_barrier
	s_waitcnt lgkmcnt(0)
	s_setprio 1
	s_waitcnt lgkmcnt(0)
	v_mfma_f32_16x16x32_bf16 v[112:115], v[198:201], v[154:157], v[112:115]
	v_mfma_f32_16x16x32_bf16 v[104:107], v[206:209], v[154:157], v[104:107]
	v_mfma_f32_16x16x32_bf16 v[96:99], v[198:201], v[162:165], v[96:99]
	v_mfma_f32_16x16x32_bf16 v[88:91], v[206:209], v[162:165], v[88:91]
	v_mfma_f32_16x16x32_bf16 v[80:83], v[198:201], v[182:185], v[80:83]
	v_mfma_f32_16x16x32_bf16 v[72:75], v[206:209], v[182:185], v[72:75]
	v_mfma_f32_16x16x32_bf16 v[68:71], v[198:201], v[190:193], v[68:71]
	v_mfma_f32_16x16x32_bf16 v[64:67], v[206:209], v[190:193], v[64:67]
	v_mfma_f32_16x16x32_bf16 v[112:115], v[202:205], v[158:161], v[112:115]
	v_mfma_f32_16x16x32_bf16 v[104:107], v[210:213], v[158:161], v[104:107]
	v_mfma_f32_16x16x32_bf16 v[96:99], v[202:205], v[166:169], v[96:99]
	v_mfma_f32_16x16x32_bf16 v[88:91], v[210:213], v[166:169], v[88:91]
	v_mfma_f32_16x16x32_bf16 v[80:83], v[202:205], v[186:189], v[80:83]
	v_mfma_f32_16x16x32_bf16 v[72:75], v[210:213], v[186:189], v[72:75]
	v_mfma_f32_16x16x32_bf16 v[68:71], v[202:205], v[194:197], v[68:71]
	v_mfma_f32_16x16x32_bf16 v[64:67], v[210:213], v[194:197], v[64:67]
	s_setprio 0
	s_mov_b32 m0, s36
	v_lshl_add_u64 v[170:171], v[232:233], 0, s[78:79]
	s_barrier
	ds_read_b128 v[154:157], v137 offset:49152
	ds_read_b128 v[158:161], v137 offset:50176
	ds_read_b128 v[162:165], v137 offset:51200
	ds_read_b128 v[166:169], v137 offset:52224
	ds_read_b128 v[182:185], v137 offset:53248
	ds_read_b128 v[186:189], v137 offset:54272
	ds_read_b128 v[190:193], v137 offset:55296
	ds_read_b128 v[194:197], v137 offset:56320
	global_load_lds_dwordx4 v[170:171], off
	v_lshl_add_u64 v[170:171], v[234:235], 0, s[78:79]
	s_mov_b32 m0, s37
	s_nop 0
	global_load_lds_dwordx4 v[170:171], off
	s_barrier
	s_waitcnt lgkmcnt(0)
	s_setprio 1
	s_waitcnt lgkmcnt(0)
	v_mfma_f32_16x16x32_bf16 v[60:63], v[138:141], v[154:157], v[60:63]
	v_mfma_f32_16x16x32_bf16 v[56:59], v[146:149], v[154:157], v[56:59]
	v_mfma_f32_16x16x32_bf16 v[52:55], v[138:141], v[162:165], v[52:55]
	v_mfma_f32_16x16x32_bf16 v[44:47], v[146:149], v[162:165], v[44:47]
	v_mfma_f32_16x16x32_bf16 v[36:39], v[138:141], v[182:185], v[36:39]
	v_mfma_f32_16x16x32_bf16 v[28:31], v[146:149], v[182:185], v[28:31]
	v_mfma_f32_16x16x32_bf16 v[20:23], v[138:141], v[190:193], v[20:23]
	v_mfma_f32_16x16x32_bf16 v[12:15], v[146:149], v[190:193], v[12:15]
	v_mfma_f32_16x16x32_bf16 v[60:63], v[142:145], v[158:161], v[60:63]
	v_mfma_f32_16x16x32_bf16 v[56:59], v[150:153], v[158:161], v[56:59]
	v_mfma_f32_16x16x32_bf16 v[52:55], v[142:145], v[166:169], v[52:55]
	v_mfma_f32_16x16x32_bf16 v[44:47], v[150:153], v[166:169], v[44:47]
	v_mfma_f32_16x16x32_bf16 v[36:39], v[142:145], v[186:189], v[36:39]
	v_mfma_f32_16x16x32_bf16 v[28:31], v[150:153], v[186:189], v[28:31]
	v_mfma_f32_16x16x32_bf16 v[20:23], v[142:145], v[194:197], v[20:23]
	v_mfma_f32_16x16x32_bf16 v[12:15], v[150:153], v[194:197], v[12:15]
	s_setprio 0
	s_barrier
	s_add_u32 s20, s20, 0x40080
	s_addc_u32 s21, s21, 0
	s_add_i32 s22, s22, s29
	v_lshl_add_u64 v[138:139], s[20:21], 0, v[172:173]
	s_mov_b32 m0, s22
	s_nop 0
	global_load_lds_dwordx4 v[138:139], off
	v_lshl_add_u64 v[138:139], s[20:21], 0, v[128:129]
	s_add_i32 m0, s22, 0x2000
	s_nop 0
	global_load_lds_dwordx4 v[138:139], off
	s_waitcnt vmcnt(6)
	s_barrier
	s_setprio 1
	v_mfma_f32_16x16x32_bf16 v[48:51], v[198:201], v[154:157], v[48:51]
	v_mfma_f32_16x16x32_bf16 v[40:43], v[206:209], v[154:157], v[40:43]
	v_mfma_f32_16x16x32_bf16 v[32:35], v[198:201], v[162:165], v[32:35]
	v_mfma_f32_16x16x32_bf16 v[24:27], v[206:209], v[162:165], v[24:27]
	v_mfma_f32_16x16x32_bf16 v[16:19], v[198:201], v[182:185], v[16:19]
	v_mfma_f32_16x16x32_bf16 v[8:11], v[206:209], v[182:185], v[8:11]
	v_mfma_f32_16x16x32_bf16 v[4:7], v[198:201], v[190:193], v[4:7]
	v_mfma_f32_16x16x32_bf16 v[0:3], v[206:209], v[190:193], v[0:3]
	v_mfma_f32_16x16x32_bf16 v[48:51], v[202:205], v[158:161], v[48:51]
	v_mfma_f32_16x16x32_bf16 v[40:43], v[210:213], v[158:161], v[40:43]
	v_mfma_f32_16x16x32_bf16 v[32:35], v[202:205], v[166:169], v[32:35]
	v_mfma_f32_16x16x32_bf16 v[24:27], v[210:213], v[166:169], v[24:27]
	v_mfma_f32_16x16x32_bf16 v[16:19], v[202:205], v[186:189], v[16:19]
	v_mfma_f32_16x16x32_bf16 v[8:11], v[210:213], v[186:189], v[8:11]
	v_mfma_f32_16x16x32_bf16 v[4:7], v[202:205], v[194:197], v[4:7]
	v_mfma_f32_16x16x32_bf16 v[0:3], v[210:213], v[194:197], v[0:3]
	s_setprio 0
	s_add_i32 s47, s47, 2
	s_add_u32 s18, s18, 0x100
	s_addc_u32 s19, s19, 0
	s_add_u32 s45, s45, 0x100
	s_addc_u32 s46, s46, 0
	s_cmp_gt_u32 s47, 13
	s_barrier
	s_cbranch_scc0 .LBB0_1230
	v_lshl_add_u32 v138, s40, 8, v134
	v_lshl_or_b32 v140, s39, 8, v136
	v_and_b32_e32 v139, 4, v136
	v_lshl_add_u32 v139, v139, 1, v139
	v_add_u32_e32 v140, v140, v139
	v_ashrrev_i32_e32 v139, 31, v138
	v_ashrrev_i32_e32 v141, 31, v140
	v_lshlrev_b64 v[142:143], 11, v[138:139]
	v_lshl_add_u64 v[142:143], s[8:9], 0, v[142:143]
	v_lshlrev_b64 v[140:141], 1, v[140:141]
	v_lshl_add_u64 v[142:143], v[142:143], 0, v[140:141]
	v_cvt_pk_bf16_f32 v124, v124, v125
	v_cvt_pk_bf16_f32 v125, v126, v127
	v_cvt_pk_bf16_f32 v126, v120, v121
	v_cvt_pk_bf16_f32 v127, v122, v123
	v_cvt_pk_bf16_f32 v112, v112, v113
	v_cvt_pk_bf16_f32 v113, v114, v115
	v_cvt_pk_bf16_f32 v114, v104, v105
	v_cvt_pk_bf16_f32 v115, v106, v107
	s_nop 1
	v_permlane16_swap_b32_e32 v124, v126
	v_permlane16_swap_b32_e32 v125, v127
	v_permlane16_swap_b32_e32 v112, v114
	v_permlane16_swap_b32_e32 v113, v115
	global_store_dwordx4 v[142:143], v[124:127], off
	global_store_dwordx4 v[142:143], v[112:115], off offset:256
	v_cvt_pk_bf16_f32 v116, v116, v117
	v_cvt_pk_bf16_f32 v117, v118, v119
	v_cvt_pk_bf16_f32 v118, v108, v109
	v_cvt_pk_bf16_f32 v119, v110, v111
	v_cvt_pk_bf16_f32 v96, v96, v97
	v_cvt_pk_bf16_f32 v97, v98, v99
	v_cvt_pk_bf16_f32 v98, v88, v89
	v_cvt_pk_bf16_f32 v99, v90, v91
	s_mov_b64 s[18:19], 0x8000
	v_lshl_add_u64 v[140:141], v[142:143], 0, s[18:19]
	v_permlane16_swap_b32_e32 v116, v118
	v_permlane16_swap_b32_e32 v117, v119
	v_permlane16_swap_b32_e32 v96, v98
	v_permlane16_swap_b32_e32 v97, v99
	global_store_dwordx4 v[140:141], v[116:119], off
	global_store_dwordx4 v[140:141], v[96:99], off offset:256
	v_cvt_pk_bf16_f32 v100, v100, v101
	v_cvt_pk_bf16_f32 v101, v102, v103
	v_cvt_pk_bf16_f32 v102, v92, v93
	v_cvt_pk_bf16_f32 v103, v94, v95
	v_cvt_pk_bf16_f32 v80, v80, v81
	v_cvt_pk_bf16_f32 v81, v82, v83
	v_cvt_pk_bf16_f32 v82, v72, v73
	v_cvt_pk_bf16_f32 v83, v74, v75
	s_mov_b64 s[18:19], 0x10000
	v_lshl_add_u64 v[138:139], v[142:143], 0, s[18:19]
	v_permlane16_swap_b32_e32 v100, v102
	v_permlane16_swap_b32_e32 v101, v103
	v_permlane16_swap_b32_e32 v80, v82
	v_permlane16_swap_b32_e32 v81, v83
	global_store_dwordx4 v[138:139], v[100:103], off
	global_store_dwordx4 v[138:139], v[80:83], off offset:256
	v_cvt_pk_bf16_f32 v84, v84, v85
	v_cvt_pk_bf16_f32 v85, v86, v87
	v_cvt_pk_bf16_f32 v86, v76, v77
	v_cvt_pk_bf16_f32 v87, v78, v79
	v_cvt_pk_bf16_f32 v68, v68, v69
	v_cvt_pk_bf16_f32 v69, v70, v71
	v_cvt_pk_bf16_f32 v70, v64, v65
	v_cvt_pk_bf16_f32 v71, v66, v67
	s_mov_b64 s[18:19], 0x18000
	v_lshl_add_u64 v[140:141], v[142:143], 0, s[18:19]
	v_permlane16_swap_b32_e32 v84, v86
	v_permlane16_swap_b32_e32 v85, v87
	v_permlane16_swap_b32_e32 v68, v70
	v_permlane16_swap_b32_e32 v69, v71
	global_store_dwordx4 v[140:141], v[84:87], off
	global_store_dwordx4 v[140:141], v[68:71], off offset:256
	v_cvt_pk_bf16_f32 v60, v60, v61
	v_cvt_pk_bf16_f32 v61, v62, v63
	v_cvt_pk_bf16_f32 v62, v56, v57
	v_cvt_pk_bf16_f32 v63, v58, v59
	v_cvt_pk_bf16_f32 v48, v48, v49
	v_cvt_pk_bf16_f32 v49, v50, v51
	v_cvt_pk_bf16_f32 v50, v40, v41
	v_cvt_pk_bf16_f32 v51, v42, v43
	s_mov_b64 s[18:19], 0x40000
	v_lshl_add_u64 v[138:139], v[142:143], 0, s[18:19]
	v_permlane16_swap_b32_e32 v60, v62
	v_permlane16_swap_b32_e32 v61, v63
	v_permlane16_swap_b32_e32 v48, v50
	v_permlane16_swap_b32_e32 v49, v51
	global_store_dwordx4 v[138:139], v[60:63], off
	global_store_dwordx4 v[138:139], v[48:51], off offset:256
	v_cvt_pk_bf16_f32 v52, v52, v53
	v_cvt_pk_bf16_f32 v53, v54, v55
	v_cvt_pk_bf16_f32 v54, v44, v45
	v_cvt_pk_bf16_f32 v55, v46, v47
	v_cvt_pk_bf16_f32 v32, v32, v33
	v_cvt_pk_bf16_f32 v33, v34, v35
	v_cvt_pk_bf16_f32 v34, v24, v25
	v_cvt_pk_bf16_f32 v35, v26, v27
	s_mov_b64 s[18:19], 0x48000
	v_lshl_add_u64 v[140:141], v[142:143], 0, s[18:19]
	v_permlane16_swap_b32_e32 v52, v54
	v_permlane16_swap_b32_e32 v53, v55
	v_permlane16_swap_b32_e32 v32, v34
	v_permlane16_swap_b32_e32 v33, v35
	global_store_dwordx4 v[140:141], v[52:55], off
	global_store_dwordx4 v[140:141], v[32:35], off offset:256
	v_cvt_pk_bf16_f32 v36, v36, v37
	v_cvt_pk_bf16_f32 v37, v38, v39
	v_cvt_pk_bf16_f32 v38, v28, v29
	v_cvt_pk_bf16_f32 v39, v30, v31
	v_cvt_pk_bf16_f32 v16, v16, v17
	v_cvt_pk_bf16_f32 v17, v18, v19
	v_cvt_pk_bf16_f32 v18, v8, v9
	v_cvt_pk_bf16_f32 v19, v10, v11
	s_mov_b64 s[18:19], 0x50000
	v_lshl_add_u64 v[138:139], v[142:143], 0, s[18:19]
	v_permlane16_swap_b32_e32 v36, v38
	v_permlane16_swap_b32_e32 v37, v39
	v_permlane16_swap_b32_e32 v16, v18
	v_permlane16_swap_b32_e32 v17, v19
	global_store_dwordx4 v[138:139], v[36:39], off
	global_store_dwordx4 v[138:139], v[16:19], off offset:256
	v_cvt_pk_bf16_f32 v20, v20, v21
	v_cvt_pk_bf16_f32 v21, v22, v23
	v_cvt_pk_bf16_f32 v22, v12, v13
	v_cvt_pk_bf16_f32 v23, v14, v15
	v_cvt_pk_bf16_f32 v4, v4, v5
	v_cvt_pk_bf16_f32 v5, v6, v7
	v_cvt_pk_bf16_f32 v6, v0, v1
	v_cvt_pk_bf16_f32 v7, v2, v3
	s_mov_b64 s[18:19], 0x58000
	v_lshl_add_u64 v[140:141], v[142:143], 0, s[18:19]
	v_permlane16_swap_b32_e32 v20, v22
	v_permlane16_swap_b32_e32 v21, v23
	v_permlane16_swap_b32_e32 v4, v6
	v_permlane16_swap_b32_e32 v5, v7
	global_store_dwordx4 v[140:141], v[20:23], off
	global_store_dwordx4 v[140:141], v[4:7], off offset:256
	s_and_b64 vcc, exec, s[6:7]
	s_mov_b32 s39, s10
	s_mov_b32 s40, s12
	s_mov_b64 s[20:21], s[16:17]
	s_mov_b64 s[18:19], s[14:15]
	s_cbranch_vccz .LBB0_1223
	s_waitcnt vmcnt(0)
	s_cmpk_gt_u32 s24, 0xff
	s_cbranch_scc1 .LBB0_1234
	s_barrier
